# BO3 + extra s_setprio 0/1 toggle window after every 8 MFMAs of each 16-run in the GEMM K-loops
# baseline (speedup 1.0000x reference)
; #define PG8_SB(B) __builtin_amdgcn_rcpf(1.f + expneg(B))
; #define PG8_SB(B) __builtin_amdgcn_rcpf(1.f + expneg(B))
; #define PG8_STAGE(bufoff, gbase, voff) do { _Pragma("unroll") for (int _i = 0; _i < 2; ++_i) \
;         __builtin_amdgcn_global_load_lds((const unsigned*)((const char*)(gbase) + (size_t)_i * qstep + (voff)[0]), (PG8_LAS unsigned*)(lds + (bufoff) + ldsw + _i * 8192), 16, 0, 0); } while (0)
; #define PG8_LDA(dst, b, h) do { _Pragma("unroll") for (int m = 0; m < 4; ++m) _Pragma("unroll") for (int k = 0; k < 2; ++k) dst[m][k] = *(const PG8_LAS bf16x8*)(lds + PG8_SA(b, h) + aoff + m * 2048 + k * 1024); } while (0)
; #define PG8_MMA(ai, bj, At, Bt) do { __builtin_amdgcn_s_setprio(1); _Pragma("unroll") for (int m = 0; m < 4; ++m) _Pragma("unroll") for (int n = 0; n < 2; ++n) _Pragma("unroll") for (int k = 0; k < 2; ++k) \
;         acc[ai][bj][m][n] = __builtin_amdgcn_mfma_f32_16x16x32_bf16(Bt[n][k], At[m][k], acc[ai][bj][m][n], 0, 0, 0); __builtin_amdgcn_s_setprio(0); } while (0)
; #define PG8_WAIT_V89() do { if constexpr (SLIVER) PG8_WAIT_V(9); else PG8_WAIT_V(8); } while (0)
; #define PG8_LDS_S(b) do { if constexpr (SLIVER) { Sf[0] = *(const PG8_LAS bf16x8*)(lds + STAGE_BYTES + (b) * 2048 + soff0); Sf[1] = *(const PG8_LAS bf16x8*)(lds + STAGE_BYTES + (b) * 2048 + (soff0 ^ 64)); } } while (0)
; #define PG8_WAIT_L(n) asm volatile("s_waitcnt lgkmcnt(" #n ")" ::: "memory")
; #define PG8_BAR __builtin_amdgcn_s_barrier()
; #define PG8_SCHED __builtin_amdgcn_sched_barrier(0)
; template <class Epi, class Sched, bool ALIGN_EPI = false, bool SP2 = false, bool SLIVER = false>
; __device__ __forceinline__ void gemm_phase(PG8_LAS unsigned char* lds, const Gemm g, const Sched& S, const Epi& E) {
;     ...
;             PG8_WAIT_V89(); PG8_WAIT_L(0); PG8_BAR; PG8_MMA(0, 0, At, B0); PG8_MMA(0, 1, At, B1); PG8_BAR; PG8_SCHED;
;             PG8_LDA(At, 0, 1); PG8_LDS_S(0); PG8_STAGE(PG8_SB(0, 0), b2, voffB); PG8_STAGE(PG8_SB(0, 1), b2 + hstep, voffB); PG8_STAGE(PG8_SA(0, 0), a2, voffA);
;             PG8_WAIT_V89(); PG8_WAIT_L(0); PG8_BAR; PG8_MMA(1, 0, At, B0); PG8_MMA(1, 1, At, B1); PG8_MMA_S(); PG8_BAR; PG8_SCHED;
.Lgin_skipw0:
	s_waitcnt lgkmcnt(0)
	s_setprio 1
	s_barrier
	v_mfma_f32_16x16x32_bf16 v[126:129], v[136:139], v[174:177], v[126:129]
	v_mfma_f32_16x16x32_bf16 v[126:129], v[140:143], v[180:183], v[126:129]
	v_mfma_f32_16x16x32_bf16 v[122:125], v[154:157], v[180:183], v[122:125]
	v_mfma_f32_16x16x32_bf16 v[122:125], v[150:153], v[174:177], v[122:125]
	v_mfma_f32_16x16x32_bf16 v[106:109], v[150:153], v[184:187], v[106:109]
	v_mfma_f32_16x16x32_bf16 v[106:109], v[154:157], v[188:191], v[106:109]
	v_mfma_f32_16x16x32_bf16 v[114:117], v[140:143], v[188:191], v[114:117]
	v_mfma_f32_16x16x32_bf16 v[114:117], v[136:139], v[184:187], v[114:117]
	s_setprio 0
	s_setprio 1
	v_mfma_f32_16x16x32_bf16 v[98:101], v[136:139], v[192:195], v[98:101]
	v_mfma_f32_16x16x32_bf16 v[98:101], v[140:143], v[196:199], v[98:101]
	v_mfma_f32_16x16x32_bf16 v[90:93], v[154:157], v[196:199], v[90:93]
	v_mfma_f32_16x16x32_bf16 v[90:93], v[150:153], v[192:195], v[90:93]
	v_mfma_f32_16x16x32_bf16 v[74:77], v[150:153], v[200:203], v[74:77]
	v_mfma_f32_16x16x32_bf16 v[74:77], v[154:157], v[210:213], v[74:77]
	v_mfma_f32_16x16x32_bf16 v[82:85], v[140:143], v[210:213], v[82:85]
	v_mfma_f32_16x16x32_bf16 v[82:85], v[136:139], v[200:203], v[82:85]
	s_setprio 0
	s_setprio 1
	v_mfma_f32_16x16x32_bf16 v[66:69], v[166:169], v[200:203], v[66:69]
	v_mfma_f32_16x16x32_bf16 v[66:69], v[170:173], v[210:213], v[66:69]
	v_mfma_f32_16x16x32_bf16 v[110:113], v[170:173], v[180:183], v[110:113]
	v_mfma_f32_16x16x32_bf16 v[110:113], v[166:169], v[174:177], v[110:113]
	v_mfma_f32_16x16x32_bf16 v[118:121], v[158:161], v[174:177], v[118:121]
	v_mfma_f32_16x16x32_bf16 v[118:121], v[162:165], v[180:183], v[118:121]
	v_mfma_f32_16x16x32_bf16 v[102:105], v[162:165], v[188:191], v[102:105]
	v_mfma_f32_16x16x32_bf16 v[102:105], v[158:161], v[184:187], v[102:105]
	s_setprio 0
	s_setprio 1
	v_mfma_f32_16x16x32_bf16 v[94:97], v[166:169], v[184:187], v[94:97]
	v_mfma_f32_16x16x32_bf16 v[94:97], v[170:173], v[188:191], v[94:97]
	v_mfma_f32_16x16x32_bf16 v[78:81], v[170:173], v[196:199], v[78:81]
	v_mfma_f32_16x16x32_bf16 v[78:81], v[166:169], v[192:195], v[78:81]
	v_mfma_f32_16x16x32_bf16 v[86:89], v[158:161], v[192:195], v[86:89]
	v_mfma_f32_16x16x32_bf16 v[86:89], v[162:165], v[196:199], v[86:89]
	v_mfma_f32_16x16x32_bf16 v[70:73], v[162:165], v[210:213], v[70:73]
	v_mfma_f32_16x16x32_bf16 v[70:73], v[158:161], v[200:203], v[70:73]
	s_barrier
	s_setprio 0
	s_add_i32 s77, s77, s53
	s_mov_b32 m0, s77
	ds_read_b128 v[174:177], v149 offset:16384
	ds_read_b128 v[180:183], v149 offset:17408
	ds_read_b128 v[184:187], v149 offset:18432
	ds_read_b128 v[188:191], v149 offset:19456
	ds_read_b128 v[192:195], v149 offset:20480
	ds_read_b128 v[196:199], v149 offset:21504
	ds_read_b128 v[200:203], v149 offset:22528
	ds_read_b128 v[210:213], v149 offset:23552
	global_load_lds_dwordx4 v132, s[78:79]
	s_add_i32 m0, s77, 0x2000
	s_add_i32 s77, s80, s53
	s_add_u32 s58, s78, 0x40000
	s_addc_u32 s59, s79, 0
	global_load_lds_dwordx4 v132, s[58:59]
	s_mov_b32 m0, s77
	s_nop 0
	s_add_u32 s60, s78, 0x80000
	s_addc_u32 s61, s79, 0
	global_load_lds_dwordx4 v132, s[60:61]
	s_add_i32 m0, s77, 0x2000
	s_nop 0
	s_add_u32 s36, s78, 0xc0000
	s_addc_u32 s37, s79, 0
	global_load_lds_dwordx4 v132, s[36:37]
	s_mov_b64 s[46:47], s[62:63]
	s_mov_b32 m0, s91
	s_nop 0
	global_load_lds_dwordx4 v130, s[46:47]
	s_mov_b32 m0, s50
	s_nop 0
	s_add_u32 s58, s46, 0x40000
	s_addc_u32 s59, s47, 0
	global_load_lds_dwordx4 v130, s[58:59]
	s_cmp_eq_u32 s76, s101
	s_cbranch_scc1 .Lgin_skipw1
	s_waitcnt vmcnt(8)
.Lgin_skipw1:
	s_waitcnt lgkmcnt(0)
	s_setprio 1
	s_barrier
	v_mfma_f32_16x16x32_bf16 v[62:65], v[136:139], v[174:177], v[62:65]
	v_mfma_f32_16x16x32_bf16 v[62:65], v[140:143], v[180:183], v[62:65]
	v_mfma_f32_16x16x32_bf16 v[58:61], v[154:157], v[180:183], v[58:61]
	v_mfma_f32_16x16x32_bf16 v[58:61], v[150:153], v[174:177], v[58:61]
	v_mfma_f32_16x16x32_bf16 v[42:45], v[150:153], v[184:187], v[42:45]
	v_mfma_f32_16x16x32_bf16 v[42:45], v[154:157], v[188:191], v[42:45]
	v_mfma_f32_16x16x32_bf16 v[50:53], v[140:143], v[188:191], v[50:53]
	v_mfma_f32_16x16x32_bf16 v[50:53], v[136:139], v[184:187], v[50:53]
	s_setprio 0
	s_setprio 1
	v_mfma_f32_16x16x32_bf16 v[34:37], v[136:139], v[192:195], v[34:37]
	v_mfma_f32_16x16x32_bf16 v[34:37], v[140:143], v[196:199], v[34:37]
	v_mfma_f32_16x16x32_bf16 v[26:29], v[154:157], v[196:199], v[26:29]
	v_mfma_f32_16x16x32_bf16 v[26:29], v[150:153], v[192:195], v[26:29]
	v_mfma_f32_16x16x32_bf16 v[10:13], v[150:153], v[200:203], v[10:13]
	v_mfma_f32_16x16x32_bf16 v[10:13], v[154:157], v[210:213], v[10:13]
	v_mfma_f32_16x16x32_bf16 v[18:21], v[140:143], v[210:213], v[18:21]
	v_mfma_f32_16x16x32_bf16 v[18:21], v[136:139], v[200:203], v[18:21]
	s_setprio 0
	s_setprio 1
	v_mfma_f32_16x16x32_bf16 v[2:5], v[166:169], v[200:203], v[2:5]
	v_mfma_f32_16x16x32_bf16 v[2:5], v[170:173], v[210:213], v[2:5]
	v_mfma_f32_16x16x32_bf16 v[46:49], v[170:173], v[180:183], v[46:49]
	v_mfma_f32_16x16x32_bf16 v[46:49], v[166:169], v[174:177], v[46:49]
	v_mfma_f32_16x16x32_bf16 v[54:57], v[158:161], v[174:177], v[54:57]
	v_mfma_f32_16x16x32_bf16 v[54:57], v[162:165], v[180:183], v[54:57]
	v_mfma_f32_16x16x32_bf16 v[38:41], v[162:165], v[188:191], v[38:41]
	v_mfma_f32_16x16x32_bf16 v[38:41], v[158:161], v[184:187], v[38:41]
	s_setprio 0
	s_setprio 1
	v_mfma_f32_16x16x32_bf16 v[30:33], v[166:169], v[184:187], v[30:33]
	v_mfma_f32_16x16x32_bf16 v[30:33], v[170:173], v[188:191], v[30:33]
	v_mfma_f32_16x16x32_bf16 v[14:17], v[170:173], v[196:199], v[14:17]
	v_mfma_f32_16x16x32_bf16 v[14:17], v[166:169], v[192:195], v[14:17]
	v_mfma_f32_16x16x32_bf16 v[22:25], v[158:161], v[192:195], v[22:25]
	v_mfma_f32_16x16x32_bf16 v[22:25], v[162:165], v[196:199], v[22:25]
	v_mfma_f32_16x16x32_bf16 v[6:9], v[162:165], v[210:213], v[6:9]
	v_mfma_f32_16x16x32_bf16 v[6:9], v[158:161], v[200:203], v[6:9]
	s_barrier
; #define PG8_STAGE(bufoff, gbase, voff) do { _Pragma("unroll") for (int _i = 0; _i < 2; ++_i) \
;         __builtin_amdgcn_global_load_lds((const unsigned*)((const char*)(gbase) + (size_t)_i * qstep + (voff)[0]), (PG8_LAS unsigned*)(lds + (bufoff) + ldsw + _i * 8192), 16, 0, 0); } while (0)
; #define PG8_LDA(dst, b, h) do { _Pragma("unroll") for (int m = 0; m < 4; ++m) _Pragma("unroll") for (int k = 0; k < 2; ++k) dst[m][k] = *(const PG8_LAS bf16x8*)(lds + PG8_SA(b, h) + aoff + m * 2048 + k * 1024); } while (0)
; #define PG8_LDB(dst, b, h) do { _Pragma("unroll") for (int n = 0; n < 2; ++n) _Pragma("unroll") for (int k = 0; k < 2; ++k) dst[n][k] = *(const PG8_LAS bf16x8*)(lds + PG8_SB(b, h) + boff + n * 2048 + k * 1024); } while (0)
; #define PG8_MMA(ai, bj, At, Bt) do { __builtin_amdgcn_s_setprio(1); _Pragma("unroll") for (int m = 0; m < 4; ++m) _Pragma("unroll") for (int n = 0; n < 2; ++n) _Pragma("unroll") for (int k = 0; k < 2; ++k) \
;         acc[ai][bj][m][n] = __builtin_amdgcn_mfma_f32_16x16x32_bf16(Bt[n][k], At[m][k], acc[ai][bj][m][n], 0, 0, 0); __builtin_amdgcn_s_setprio(0); } while (0)
; #define PG8_WAIT_V89() do { if constexpr (SLIVER) PG8_WAIT_V(9); else PG8_WAIT_V(8); } while (0)
; #define PG8_STAGE_S(b, gbase) do { if constexpr (SLIVER) __builtin_amdgcn_global_load_lds((const unsigned*)((const char*)(gbase) + voffS), (PG8_LAS unsigned*)(lds + STAGE_BYTES + (b) * 2048 + wid * 256), 4, 0, 0); } while (0)
; #define PG8_WAIT_L(n) asm volatile("s_waitcnt lgkmcnt(" #n ")" ::: "memory")
; #define PG8_BAR __builtin_amdgcn_s_barrier()
; #define PG8_SCHED __builtin_amdgcn_sched_barrier(0)
; template <class Epi, class Sched, bool ALIGN_EPI = false, bool SP2 = false, bool SLIVER = false>
; __device__ __forceinline__ void gemm_phase(PG8_LAS unsigned char* lds, const Gemm g, const Sched& S, const Epi& E) {
;     ...
;             PG8_LDB(B0, 1, 0); PG8_LDB(B1, 1, 1); PG8_SCHED; PG8_LDA(At, 1, 0); PG8_STAGE(PG8_SA(0, 1), a2 + hstep, voffA); PG8_STAGE_S(0, s2);
;             PG8_WAIT_V89(); PG8_WAIT_L(0); PG8_BAR; PG8_MMA(0, 0, At, B0); PG8_MMA(0, 1, At, B1); PG8_BAR; PG8_SCHED;
	s_setprio 0
	s_add_i32 s62, 0, 0x18000
	v_add_u32_e32 v144, s62, v145
	s_add_i32 s63, 0, 0x1c000
	ds_read_b128 v[136:139], v144
	ds_read_b128 v[140:143], v144 offset:1024
	ds_read_b128 v[150:153], v144 offset:2048
	ds_read_b128 v[154:157], v144 offset:3072
	v_add_u32_e32 v144, s63, v145
	ds_read_b128 v[158:161], v144
	ds_read_b128 v[162:165], v144 offset:1024
	ds_read_b128 v[166:169], v144 offset:2048
	ds_read_b128 v[170:173], v144 offset:3072
	s_mov_b32 m0, s51
	ds_read_b128 v[174:177], v149 offset:32768
	ds_read_b128 v[180:183], v149 offset:33792
	ds_read_b128 v[184:187], v149 offset:34816
	ds_read_b128 v[188:191], v149 offset:35840
	ds_read_b128 v[192:195], v149 offset:36864
	ds_read_b128 v[196:199], v149 offset:37888
	ds_read_b128 v[200:203], v149 offset:38912
	ds_read_b128 v[210:213], v149 offset:39936
	s_add_u32 s60, s46, 0x80000
	s_addc_u32 s61, s47, 0
	global_load_lds_dwordx4 v130, s[60:61]
	s_mov_b32 m0, s54
	s_nop 0
	s_add_u32 s36, s46, 0xc0000
	s_addc_u32 s37, s47, 0
	global_load_lds_dwordx4 v130, s[36:37]
	s_waitcnt vmcnt(8)
	s_waitcnt lgkmcnt(0)
	s_setprio 1
	s_barrier
	v_mfma_f32_16x16x32_bf16 v[126:129], v[136:139], v[174:177], v[126:129]
	v_mfma_f32_16x16x32_bf16 v[126:129], v[140:143], v[180:183], v[126:129]
	v_mfma_f32_16x16x32_bf16 v[122:125], v[154:157], v[180:183], v[122:125]
	v_mfma_f32_16x16x32_bf16 v[122:125], v[150:153], v[174:177], v[122:125]
	v_mfma_f32_16x16x32_bf16 v[106:109], v[150:153], v[184:187], v[106:109]
	v_mfma_f32_16x16x32_bf16 v[106:109], v[154:157], v[188:191], v[106:109]
	v_mfma_f32_16x16x32_bf16 v[114:117], v[140:143], v[188:191], v[114:117]
	v_mfma_f32_16x16x32_bf16 v[114:117], v[136:139], v[184:187], v[114:117]
	s_setprio 0
	s_setprio 1
	v_mfma_f32_16x16x32_bf16 v[98:101], v[136:139], v[192:195], v[98:101]
	v_mfma_f32_16x16x32_bf16 v[98:101], v[140:143], v[196:199], v[98:101]
	v_mfma_f32_16x16x32_bf16 v[90:93], v[154:157], v[196:199], v[90:93]
	v_mfma_f32_16x16x32_bf16 v[90:93], v[150:153], v[192:195], v[90:93]
	v_mfma_f32_16x16x32_bf16 v[74:77], v[150:153], v[200:203], v[74:77]
	v_mfma_f32_16x16x32_bf16 v[74:77], v[154:157], v[210:213], v[74:77]
	v_mfma_f32_16x16x32_bf16 v[82:85], v[140:143], v[210:213], v[82:85]
	v_mfma_f32_16x16x32_bf16 v[82:85], v[136:139], v[200:203], v[82:85]
	s_setprio 0
	s_setprio 1
	v_mfma_f32_16x16x32_bf16 v[66:69], v[166:169], v[200:203], v[66:69]
	v_mfma_f32_16x16x32_bf16 v[66:69], v[170:173], v[210:213], v[66:69]
	v_mfma_f32_16x16x32_bf16 v[110:113], v[170:173], v[180:183], v[110:113]
	v_mfma_f32_16x16x32_bf16 v[110:113], v[166:169], v[174:177], v[110:113]
	v_mfma_f32_16x16x32_bf16 v[118:121], v[158:161], v[174:177], v[118:121]
	v_mfma_f32_16x16x32_bf16 v[118:121], v[162:165], v[180:183], v[118:121]
	v_mfma_f32_16x16x32_bf16 v[102:105], v[162:165], v[188:191], v[102:105]
	v_mfma_f32_16x16x32_bf16 v[102:105], v[158:161], v[184:187], v[102:105]
	s_setprio 0
	s_setprio 1
	v_mfma_f32_16x16x32_bf16 v[94:97], v[166:169], v[184:187], v[94:97]
	v_mfma_f32_16x16x32_bf16 v[94:97], v[170:173], v[188:191], v[94:97]
	v_mfma_f32_16x16x32_bf16 v[78:81], v[170:173], v[196:199], v[78:81]
	v_mfma_f32_16x16x32_bf16 v[78:81], v[166:169], v[192:195], v[78:81]
	v_mfma_f32_16x16x32_bf16 v[86:89], v[158:161], v[192:195], v[86:89]
	v_mfma_f32_16x16x32_bf16 v[86:89], v[162:165], v[196:199], v[86:89]
	v_mfma_f32_16x16x32_bf16 v[70:73], v[162:165], v[210:213], v[70:73]
	v_mfma_f32_16x16x32_bf16 v[70:73], v[158:161], v[200:203], v[70:73]
	s_barrier
; #define PG8_SB(B) __builtin_amdgcn_rcpf(1.f + expneg(B))
; #define PG8_SB(B) __builtin_amdgcn_rcpf(1.f + expneg(B))
; #define PG8_STAGE(bufoff, gbase, voff) do { _Pragma("unroll") for (int _i = 0; _i < 2; ++_i) \
;         __builtin_amdgcn_global_load_lds((const unsigned*)((const char*)(gbase) + (size_t)_i * qstep + (voff)[0]), (PG8_LAS unsigned*)(lds + (bufoff) + ldsw + _i * 8192), 16, 0, 0); } while (0)
; #define PG8_LDA(dst, b, h) do { _Pragma("unroll") for (int m = 0; m < 4; ++m) _Pragma("unroll") for (int k = 0; k < 2; ++k) dst[m][k] = *(const PG8_LAS bf16x8*)(lds + PG8_SA(b, h) + aoff + m * 2048 + k * 1024); } while (0)
; #define PG8_MMA(ai, bj, At, Bt) do { __builtin_amdgcn_s_setprio(1); _Pragma("unroll") for (int m = 0; m < 4; ++m) _Pragma("unroll") for (int n = 0; n < 2; ++n) _Pragma("unroll") for (int k = 0; k < 2; ++k) \
;         acc[ai][bj][m][n] = __builtin_amdgcn_mfma_f32_16x16x32_bf16(Bt[n][k], At[m][k], acc[ai][bj][m][n], 0, 0, 0); __builtin_amdgcn_s_setprio(0); } while (0)
; #define PG8_WAIT_V89() do { if constexpr (SLIVER) PG8_WAIT_V(9); else PG8_WAIT_V(8); } while (0)
; #define PG8_LDS_S(b) do { if constexpr (SLIVER) { Sf[0] = *(const PG8_LAS bf16x8*)(lds + STAGE_BYTES + (b) * 2048 + soff0); Sf[1] = *(const PG8_LAS bf16x8*)(lds + STAGE_BYTES + (b) * 2048 + (soff0 ^ 64)); } } while (0)
; #define PG8_WAIT_L(n) asm volatile("s_waitcnt lgkmcnt(" #n ")" ::: "memory")
; #define PG8_BAR __builtin_amdgcn_s_barrier()
; #define PG8_SCHED __builtin_amdgcn_sched_barrier(0)
; template <class Epi, class Sched, bool ALIGN_EPI = false, bool SP2 = false, bool SLIVER = false>
; __device__ __forceinline__ void gemm_phase(PG8_LAS unsigned char* lds, const Gemm g, const Sched& S, const Epi& E) {
;     ...
;             PG8_LDA(At, 1, 1); PG8_LDS_S(1); PG8_STAGE(PG8_SB(1, 0), b3, voffB); PG8_STAGE(PG8_SB(1, 1), b3 + hstep, voffB); PG8_STAGE(PG8_SA(1, 0), a3, voffA);
;             PG8_WAIT_V89(); PG8_WAIT_L(0); PG8_BAR; PG8_MMA(1, 0, At, B0); PG8_MMA(1, 1, At, B1); PG8_MMA_S(); PG8_BAR; PG8_SCHED;
	s_setprio 0
	s_add_i32 s62, s62, s53
	s_mov_b32 m0, s62
	ds_read_b128 v[174:177], v149 offset:49152
	ds_read_b128 v[180:183], v149 offset:50176
	ds_read_b128 v[184:187], v149 offset:51200
	ds_read_b128 v[188:191], v149 offset:52224
	ds_read_b128 v[192:195], v149 offset:53248
	ds_read_b128 v[196:199], v149 offset:54272
	ds_read_b128 v[200:203], v149 offset:55296
	ds_read_b128 v[210:213], v149 offset:56320
	s_add_u32 s58, s78, 0x80
	s_addc_u32 s59, s79, 0
	global_load_lds_dwordx4 v132, s[58:59]
	s_add_i32 m0, s62, 0x2000
	s_add_i32 s62, s63, s53
	s_add_u32 s60, s78, 0x40080
	s_addc_u32 s61, s79, 0
	global_load_lds_dwordx4 v132, s[60:61]
	s_mov_b32 m0, s62
	s_add_u32 s36, s78, 0x80080
	s_addc_u32 s37, s79, 0
	global_load_lds_dwordx4 v132, s[36:37]
	s_add_i32 m0, s62, 0x2000
	s_nop 0
	s_add_u32 s58, s78, 0xc0080
	s_addc_u32 s59, s79, 0
	global_load_lds_dwordx4 v132, s[58:59]
	s_mov_b32 m0, s10
	s_nop 0
	s_add_u32 s60, s46, 0x80
	s_addc_u32 s61, s47, 0
	global_load_lds_dwordx4 v130, s[60:61]
	s_mov_b32 m0, s55
	s_nop 0
	s_add_u32 s36, s46, 0x40080
	s_addc_u32 s37, s47, 0
	global_load_lds_dwordx4 v130, s[36:37]
	s_waitcnt vmcnt(8)
	s_waitcnt lgkmcnt(0)
	s_setprio 1
	s_barrier
	v_mfma_f32_16x16x32_bf16 v[62:65], v[136:139], v[174:177], v[62:65]
	v_mfma_f32_16x16x32_bf16 v[62:65], v[140:143], v[180:183], v[62:65]
	v_mfma_f32_16x16x32_bf16 v[58:61], v[154:157], v[180:183], v[58:61]
	v_mfma_f32_16x16x32_bf16 v[58:61], v[150:153], v[174:177], v[58:61]
	v_mfma_f32_16x16x32_bf16 v[42:45], v[150:153], v[184:187], v[42:45]
	v_mfma_f32_16x16x32_bf16 v[42:45], v[154:157], v[188:191], v[42:45]
	v_mfma_f32_16x16x32_bf16 v[50:53], v[140:143], v[188:191], v[50:53]
	v_mfma_f32_16x16x32_bf16 v[50:53], v[136:139], v[184:187], v[50:53]
	s_setprio 0
	s_setprio 1
	v_mfma_f32_16x16x32_bf16 v[34:37], v[136:139], v[192:195], v[34:37]
	v_mfma_f32_16x16x32_bf16 v[34:37], v[140:143], v[196:199], v[34:37]
	v_mfma_f32_16x16x32_bf16 v[26:29], v[154:157], v[196:199], v[26:29]
	v_mfma_f32_16x16x32_bf16 v[26:29], v[150:153], v[192:195], v[26:29]
	v_mfma_f32_16x16x32_bf16 v[10:13], v[150:153], v[200:203], v[10:13]
	v_mfma_f32_16x16x32_bf16 v[10:13], v[154:157], v[210:213], v[10:13]
	v_mfma_f32_16x16x32_bf16 v[18:21], v[140:143], v[210:213], v[18:21]
	v_mfma_f32_16x16x32_bf16 v[18:21], v[136:139], v[200:203], v[18:21]
	s_setprio 0
	s_setprio 1
	v_mfma_f32_16x16x32_bf16 v[2:5], v[166:169], v[200:203], v[2:5]
	v_mfma_f32_16x16x32_bf16 v[2:5], v[170:173], v[210:213], v[2:5]
	v_mfma_f32_16x16x32_bf16 v[46:49], v[170:173], v[180:183], v[46:49]
	v_mfma_f32_16x16x32_bf16 v[46:49], v[166:169], v[174:177], v[46:49]
	v_mfma_f32_16x16x32_bf16 v[54:57], v[158:161], v[174:177], v[54:57]
	v_mfma_f32_16x16x32_bf16 v[54:57], v[162:165], v[180:183], v[54:57]
	v_mfma_f32_16x16x32_bf16 v[38:41], v[162:165], v[188:191], v[38:41]
	v_mfma_f32_16x16x32_bf16 v[38:41], v[158:161], v[184:187], v[38:41]
	s_setprio 0
	s_setprio 1
	v_mfma_f32_16x16x32_bf16 v[30:33], v[166:169], v[184:187], v[30:33]
	v_mfma_f32_16x16x32_bf16 v[30:33], v[170:173], v[188:191], v[30:33]
	v_mfma_f32_16x16x32_bf16 v[14:17], v[170:173], v[196:199], v[14:17]
	v_mfma_f32_16x16x32_bf16 v[14:17], v[166:169], v[192:195], v[14:17]
	v_mfma_f32_16x16x32_bf16 v[22:25], v[158:161], v[192:195], v[22:25]
	v_mfma_f32_16x16x32_bf16 v[22:25], v[162:165], v[196:199], v[22:25]
	v_mfma_f32_16x16x32_bf16 v[6:9], v[162:165], v[210:213], v[6:9]
	v_mfma_f32_16x16x32_bf16 v[6:9], v[158:161], v[200:203], v[6:9]
	s_barrier
	s_setprio 0
	s_add_i32 s76, s76, 2
	s_add_u32 s40, s40, 0x100
	s_addc_u32 s41, s41, 0
	s_add_u32 s68, s68, 0x100
	s_addc_u32 s69, s69, 0
	s_cmp_gt_u32 s76, 29
	s_cbranch_scc0 .LBB0_153
	s_and_b64 vcc, exec, s[48:49]
	s_cbranch_vccz .LBB0_156
	s_barrier

; #define PG8_STAGE(bufoff, gbase, voff) do { _Pragma("unroll") for (int _i = 0; _i < 2; ++_i) \
;         __builtin_amdgcn_global_load_lds((const unsigned*)((const char*)(gbase) + (size_t)_i * qstep + (voff)[0]), (PG8_LAS unsigned*)(lds + (bufoff) + ldsw + _i * 8192), 16, 0, 0); } while (0)
; #define PG8_LDA(dst, b, h) do { _Pragma("unroll") for (int m = 0; m < 4; ++m) _Pragma("unroll") for (int k = 0; k < 2; ++k) dst[m][k] = *(const PG8_LAS bf16x8*)(lds + PG8_SA(b, h) + aoff + m * 2048 + k * 1024); } while (0)
; #define PG8_LDB(dst, b, h) do { _Pragma("unroll") for (int n = 0; n < 2; ++n) _Pragma("unroll") for (int k = 0; k < 2; ++k) dst[n][k] = *(const PG8_LAS bf16x8*)(lds + PG8_SB(b, h) + boff + n * 2048 + k * 1024); } while (0)
; #define PG8_MMA(ai, bj, At, Bt) do { __builtin_amdgcn_s_setprio(1); _Pragma("unroll") for (int m = 0; m < 4; ++m) _Pragma("unroll") for (int n = 0; n < 2; ++n) _Pragma("unroll") for (int k = 0; k < 2; ++k) \
;         acc[ai][bj][m][n] = __builtin_amdgcn_mfma_f32_16x16x32_bf16(Bt[n][k], At[m][k], acc[ai][bj][m][n], 0, 0, 0); __builtin_amdgcn_s_setprio(0); } while (0)
; #define PG8_WAIT_V89() do { if constexpr (SLIVER) PG8_WAIT_V(9); else PG8_WAIT_V(8); } while (0)
; #define PG8_WAIT_L(n) asm volatile("s_waitcnt lgkmcnt(" #n ")" ::: "memory")
; #define PG8_BAR __builtin_amdgcn_s_barrier()
; #define PG8_SCHED __builtin_amdgcn_sched_barrier(0)
; template <class Epi, class Sched, bool ALIGN_EPI = false, bool SP2 = false, bool SLIVER = false>
; __device__ __forceinline__ void gemm_phase(PG8_LAS unsigned char* lds, const Gemm g, const Sched& S, const Epi& E) {
;     ...
;             const bool last = (t == nt - 2);
;             const char* a1 = cA + (size_t)(t + 1) * kstep;
;             const char* a2 = last ? nA : cA + (size_t)(t + 2) * kstep; const char* b2 = last ? nB : cB + (size_t)(t + 2) * kstep;
;             const char* a3 = a2 + kstep; const char* b3 = b2 + kstep;
;             const char* s1 = cS + (size_t)(t + 1) * kstep; const char* s2 = last ? nS : cS + (size_t)(t + 2) * kstep;
;             if (last && has_next) S.a_ready(nxt);
;             if constexpr (SP2) {
;             PG8_LDB(B0, 0, 0); PG8_LDB(B1, 0, 1); PG8_SCHED; PG8_LDA(At, 0, 0); PG8_STAGE(PG8_SA(1, 1), a1 + hstep, voffA); PG8_STAGE_S(1, s1);
;             PG8_WAIT_V89(); PG8_WAIT_L(0); PG8_BAR; PG8_MMA(0, 0, At, B0); PG8_MMA(0, 1, At, B1); PG8_BAR; PG8_SCHED;
.LBB0_498:
	s_cmp_eq_u32 s66, s80
	s_cselect_b64 s[86:87], -1, 0
	s_add_u32 s40, s16, s80
	s_addc_u32 s41, s17, s81
	s_add_u32 s68, s40, 0x100
	s_addc_u32 s69, s41, 0
	s_and_b64 s[40:41], s[86:87], exec
	s_cselect_b32 s41, s55, s69
	s_cselect_b32 s40, s54, s68
	s_add_u32 s76, s12, s80
	s_addc_u32 s77, s13, s81
	s_add_i32 s78, 0, 0x10000
	s_and_b64 s[68:69], s[86:87], exec
	v_add_u32_e32 v138, s78, v239
	s_cselect_b32 s69, s83, s77
	s_cselect_b32 s68, s82, s76
	s_add_i32 s76, 0, 0x14000
	ds_read_b128 v[146:149], v138
	ds_read_b128 v[150:153], v138 offset:1024
	ds_read_b128 v[154:157], v138 offset:2048
	ds_read_b128 v[158:161], v138 offset:3072
	v_add_u32_e32 v138, s76, v239
	ds_read_b128 v[166:169], v138
	ds_read_b128 v[170:173], v138 offset:1024
	ds_read_b128 v[174:177], v138 offset:2048
	ds_read_b128 v[162:165], v138 offset:3072
	v_lshl_add_u64 v[208:209], v[188:189], 0, s[80:81]
	v_lshl_add_u64 v[224:225], v[208:209], 0, s[34:35]
	s_add_i32 m0, s96, 0xc000
	s_mov_b64 s[88:89], 0x120080
	ds_read_b128 v[138:141], v242
	ds_read_b128 v[142:145], v242 offset:1024
	ds_read_b128 v[180:183], v242 offset:2048
	ds_read_b128 v[184:187], v242 offset:3072
	ds_read_b128 v[192:195], v242 offset:4096
	ds_read_b128 v[196:199], v242 offset:5120
	ds_read_b128 v[200:203], v242 offset:6144
	ds_read_b128 v[220:223], v242 offset:7168
	global_load_lds_dwordx4 v[224:225], off
	v_lshl_add_u64 v[208:209], v[208:209], 0, s[88:89]
	s_add_i32 m0, s96, 0xe000
	s_nop 0
	global_load_lds_dwordx4 v[208:209], off
	v_lshl_add_u64 v[208:209], v[190:191], 0, s[80:81]
	s_add_i32 m0, s94, 0x20800
	s_nop 0
	global_load_lds_dword v[208:209], off
	s_waitcnt vmcnt(9)
	s_waitcnt lgkmcnt(0)
	s_setprio 1
	s_barrier
	v_mfma_f32_16x16x32_bf16 v[134:137], v[146:149], v[138:141], v[134:137]
	v_mfma_f32_16x16x32_bf16 v[134:137], v[150:153], v[142:145], v[134:137]
	v_mfma_f32_16x16x32_bf16 v[130:133], v[158:161], v[142:145], v[130:133]
	v_mfma_f32_16x16x32_bf16 v[130:133], v[154:157], v[138:141], v[130:133]
	v_mfma_f32_16x16x32_bf16 v[122:125], v[154:157], v[180:183], v[122:125]
	v_mfma_f32_16x16x32_bf16 v[122:125], v[158:161], v[184:187], v[122:125]
	v_mfma_f32_16x16x32_bf16 v[126:129], v[150:153], v[184:187], v[126:129]
	v_mfma_f32_16x16x32_bf16 v[126:129], v[146:149], v[180:183], v[126:129]
	s_setprio 0
	s_setprio 1
	v_mfma_f32_16x16x32_bf16 v[118:121], v[146:149], v[192:195], v[118:121]
	v_mfma_f32_16x16x32_bf16 v[118:121], v[150:153], v[196:199], v[118:121]
	v_mfma_f32_16x16x32_bf16 v[114:117], v[158:161], v[196:199], v[114:117]
	v_mfma_f32_16x16x32_bf16 v[114:117], v[154:157], v[192:195], v[114:117]
	v_mfma_f32_16x16x32_bf16 v[106:109], v[154:157], v[200:203], v[106:109]
	v_mfma_f32_16x16x32_bf16 v[106:109], v[158:161], v[220:223], v[106:109]
	v_mfma_f32_16x16x32_bf16 v[110:113], v[150:153], v[220:223], v[110:113]
	v_mfma_f32_16x16x32_bf16 v[110:113], v[146:149], v[200:203], v[110:113]
	s_setprio 0
	s_setprio 1
	v_mfma_f32_16x16x32_bf16 v[66:69], v[174:177], v[200:203], v[66:69]
	v_mfma_f32_16x16x32_bf16 v[66:69], v[162:165], v[220:223], v[66:69]
	v_mfma_f32_16x16x32_bf16 v[98:101], v[162:165], v[142:145], v[98:101]
	v_mfma_f32_16x16x32_bf16 v[98:101], v[174:177], v[138:141], v[98:101]
	v_mfma_f32_16x16x32_bf16 v[102:105], v[166:169], v[138:141], v[102:105]
	v_mfma_f32_16x16x32_bf16 v[102:105], v[170:173], v[142:145], v[102:105]
	v_mfma_f32_16x16x32_bf16 v[90:93], v[170:173], v[184:187], v[90:93]
	v_mfma_f32_16x16x32_bf16 v[90:93], v[166:169], v[180:183], v[90:93]
	s_setprio 0
	s_setprio 1
	v_mfma_f32_16x16x32_bf16 v[86:89], v[174:177], v[180:183], v[86:89]
	v_mfma_f32_16x16x32_bf16 v[86:89], v[162:165], v[184:187], v[86:89]
	v_mfma_f32_16x16x32_bf16 v[74:77], v[162:165], v[196:199], v[74:77]
	v_mfma_f32_16x16x32_bf16 v[74:77], v[174:177], v[192:195], v[74:77]
	v_mfma_f32_16x16x32_bf16 v[78:81], v[166:169], v[192:195], v[78:81]
	v_mfma_f32_16x16x32_bf16 v[78:81], v[170:173], v[196:199], v[78:81]
	v_mfma_f32_16x16x32_bf16 v[70:73], v[170:173], v[220:223], v[70:73]
	v_mfma_f32_16x16x32_bf16 v[70:73], v[166:169], v[200:203], v[70:73]
	s_barrier
; #define PG8_SB(B) __builtin_amdgcn_rcpf(1.f + expneg(B))
; #define PG8_SB(B) __builtin_amdgcn_rcpf(1.f + expneg(B))
; #define PG8_STAGE(bufoff, gbase, voff) do { _Pragma("unroll") for (int _i = 0; _i < 2; ++_i) \
;         __builtin_amdgcn_global_load_lds((const unsigned*)((const char*)(gbase) + (size_t)_i * qstep + (voff)[0]), (PG8_LAS unsigned*)(lds + (bufoff) + ldsw + _i * 8192), 16, 0, 0); } while (0)
; #define PG8_LDA(dst, b, h) do { _Pragma("unroll") for (int m = 0; m < 4; ++m) _Pragma("unroll") for (int k = 0; k < 2; ++k) dst[m][k] = *(const PG8_LAS bf16x8*)(lds + PG8_SA(b, h) + aoff + m * 2048 + k * 1024); } while (0)
; #define PG8_MMA(ai, bj, At, Bt) do { __builtin_amdgcn_s_setprio(1); _Pragma("unroll") for (int m = 0; m < 4; ++m) _Pragma("unroll") for (int n = 0; n < 2; ++n) _Pragma("unroll") for (int k = 0; k < 2; ++k) \
;         acc[ai][bj][m][n] = __builtin_amdgcn_mfma_f32_16x16x32_bf16(Bt[n][k], At[m][k], acc[ai][bj][m][n], 0, 0, 0); __builtin_amdgcn_s_setprio(0); } while (0)
; #define PG8_WAIT_V89() do { if constexpr (SLIVER) PG8_WAIT_V(9); else PG8_WAIT_V(8); } while (0)
; #define PG8_LDS_S(b) do { if constexpr (SLIVER) { Sf[0] = *(const PG8_LAS bf16x8*)(lds + STAGE_BYTES + (b) * 2048 + soff0); Sf[1] = *(const PG8_LAS bf16x8*)(lds + STAGE_BYTES + (b) * 2048 + (soff0 ^ 64)); } } while (0)
; #define PG8_WAIT_L(n) asm volatile("s_waitcnt lgkmcnt(" #n ")" ::: "memory")
; #define PG8_BAR __builtin_amdgcn_s_barrier()
; #define PG8_SCHED __builtin_amdgcn_sched_barrier(0)
; template <class Epi, class Sched, bool ALIGN_EPI = false, bool SP2 = false, bool SLIVER = false>
; __device__ __forceinline__ void gemm_phase(PG8_LAS unsigned char* lds, const Gemm g, const Sched& S, const Epi& E) {
;     ...
;             PG8_LDA(At, 0, 1); PG8_LDS_S(0); PG8_STAGE(PG8_SB(0, 0), b2, voffB); PG8_STAGE(PG8_SB(0, 1), b2 + hstep, voffB); PG8_STAGE(PG8_SA(0, 0), a2, voffA);
;             PG8_WAIT_V89(); PG8_WAIT_L(0); PG8_BAR; PG8_MMA(1, 0, At, B0); PG8_MMA(1, 1, At, B1); PG8_MMA_S(); PG8_BAR; PG8_SCHED;
	s_setprio 0
	s_add_i32 s77, 0, 0x20000
	v_lshl_add_u64 v[192:193], s[68:69], 0, v[212:213]
	s_add_i32 s68, s78, s95
	v_add_u32_e32 v178, s77, v240
	v_add_u32_e32 v184, s77, v241
	s_mov_b32 m0, s68
	s_mov_b64 s[88:89], 0x60000
	ds_read_b128 v[138:141], v242 offset:16384
	ds_read_b128 v[142:145], v242 offset:17408
	ds_read_b128 v[196:199], v242 offset:18432
	ds_read_b128 v[200:203], v242 offset:19456
	ds_read_b128 v[220:223], v242 offset:20480
	ds_read_b128 v[224:227], v242 offset:21504
	ds_read_b128 v[228:231], v242 offset:22528
	ds_read_b128 v[232:235], v242 offset:23552
	ds_read_b128 v[180:183], v178
	ds_read_b128 v[184:187], v184
	global_load_lds_dwordx4 v[192:193], off
	v_lshl_add_u64 v[194:195], v[192:193], 0, s[88:89]
	s_add_i32 m0, s68, 0x2000
	s_add_i32 s68, s76, s95
	global_load_lds_dwordx4 v[194:195], off
	v_lshl_add_u64 v[194:195], v[192:193], 0, s[24:25]
	s_mov_b32 m0, s68
	s_nop 0
	global_load_lds_dwordx4 v[194:195], off
	v_lshl_add_u64 v[194:195], v[192:193], 0, s[14:15]
	s_add_i32 m0, s68, 0x2000
	s_nop 0
	global_load_lds_dwordx4 v[194:195], off
	v_lshl_add_u64 v[194:195], s[40:41], 0, v[210:211]
	s_mov_b32 m0, s96
	v_lshl_add_u64 v[208:209], v[194:195], 0, s[88:89]
	global_load_lds_dwordx4 v[194:195], off
	s_mov_b32 m0, s19
	s_nop 0
	global_load_lds_dwordx4 v[208:209], off
	s_waitcnt vmcnt(9)
	s_waitcnt lgkmcnt(0)
	s_setprio 1
	s_barrier
	v_mfma_f32_16x16x32_bf16 v[62:65], v[146:149], v[138:141], v[62:65]
	v_mfma_f32_16x16x32_bf16 v[62:65], v[150:153], v[142:145], v[62:65]
	v_mfma_f32_16x16x32_bf16 v[58:61], v[158:161], v[142:145], v[58:61]
	v_mfma_f32_16x16x32_bf16 v[58:61], v[154:157], v[138:141], v[58:61]
	v_mfma_f32_16x16x32_bf16 v[50:53], v[154:157], v[196:199], v[50:53]
	v_mfma_f32_16x16x32_bf16 v[50:53], v[158:161], v[200:203], v[50:53]
	v_mfma_f32_16x16x32_bf16 v[54:57], v[150:153], v[200:203], v[54:57]
	v_mfma_f32_16x16x32_bf16 v[54:57], v[146:149], v[196:199], v[54:57]
	s_setprio 0
	s_setprio 1
	v_mfma_f32_16x16x32_bf16 v[46:49], v[146:149], v[220:223], v[46:49]
	v_mfma_f32_16x16x32_bf16 v[46:49], v[150:153], v[224:227], v[46:49]
	v_mfma_f32_16x16x32_bf16 v[42:45], v[158:161], v[224:227], v[42:45]
	v_mfma_f32_16x16x32_bf16 v[42:45], v[154:157], v[220:223], v[42:45]
	v_mfma_f32_16x16x32_bf16 v[34:37], v[154:157], v[228:231], v[34:37]
	v_mfma_f32_16x16x32_bf16 v[34:37], v[158:161], v[232:235], v[34:37]
	v_mfma_f32_16x16x32_bf16 v[38:41], v[150:153], v[232:235], v[38:41]
	v_mfma_f32_16x16x32_bf16 v[38:41], v[146:149], v[228:231], v[38:41]
	s_setprio 0
	s_setprio 1
	v_mfma_f32_16x16x32_bf16 v[2:5], v[174:177], v[228:231], v[2:5]
	v_mfma_f32_16x16x32_bf16 v[2:5], v[162:165], v[232:235], v[2:5]
	v_mfma_f32_16x16x32_bf16 v[26:29], v[162:165], v[142:145], v[26:29]
	v_mfma_f32_16x16x32_bf16 v[26:29], v[174:177], v[138:141], v[26:29]
	v_mfma_f32_16x16x32_bf16 v[30:33], v[166:169], v[138:141], v[30:33]
	v_mfma_f32_16x16x32_bf16 v[30:33], v[170:173], v[142:145], v[30:33]
	v_mfma_f32_16x16x32_bf16 v[22:25], v[170:173], v[200:203], v[22:25]
	v_mfma_f32_16x16x32_bf16 v[22:25], v[166:169], v[196:199], v[22:25]
	s_setprio 0
	s_setprio 1
	v_mfma_f32_16x16x32_bf16 v[18:21], v[174:177], v[196:199], v[18:21]
	v_mfma_f32_16x16x32_bf16 v[18:21], v[162:165], v[200:203], v[18:21]
	v_mfma_f32_16x16x32_bf16 v[10:13], v[162:165], v[224:227], v[10:13]
	v_mfma_f32_16x16x32_bf16 v[10:13], v[174:177], v[220:223], v[10:13]
	v_mfma_f32_16x16x32_bf16 v[14:17], v[166:169], v[220:223], v[14:17]
	v_mfma_f32_16x16x32_bf16 v[14:17], v[170:173], v[224:227], v[14:17]
	v_mfma_f32_16x16x32_bf16 v[6:9], v[170:173], v[232:235], v[6:9]
	v_mfma_f32_16x16x32_bf16 v[6:9], v[166:169], v[228:231], v[6:9]
	s_setprio 0
	s_setprio 1
	s_and_b64 vcc, exec, s[52:53]
	s_cbranch_vccz .Lslv_b0
	v_mfma_f32_16x16x32_bf16 v[138:141], v[166:169], v[180:183], v[82:85]
	v_mfma_f32_16x16x32_bf16 v[142:145], v[174:177], v[180:183], v[94:97]
	v_mfma_f32_16x16x32_bf16 v[138:141], v[170:173], v[184:187], v[138:141]
	v_mfma_f32_16x16x32_bf16 v[142:145], v[162:165], v[184:187], v[142:145]
	s_branch .LBB0_502

; #define PG8_STAGE(bufoff, gbase, voff) do { _Pragma("unroll") for (int _i = 0; _i < 2; ++_i) \
;         __builtin_amdgcn_global_load_lds((const unsigned*)((const char*)(gbase) + (size_t)_i * qstep + (voff)[0]), (PG8_LAS unsigned*)(lds + (bufoff) + ldsw + _i * 8192), 16, 0, 0); } while (0)
; #define PG8_LDA(dst, b, h) do { _Pragma("unroll") for (int m = 0; m < 4; ++m) _Pragma("unroll") for (int k = 0; k < 2; ++k) dst[m][k] = *(const PG8_LAS bf16x8*)(lds + PG8_SA(b, h) + aoff + m * 2048 + k * 1024); } while (0)
; #define PG8_LDB(dst, b, h) do { _Pragma("unroll") for (int n = 0; n < 2; ++n) _Pragma("unroll") for (int k = 0; k < 2; ++k) dst[n][k] = *(const PG8_LAS bf16x8*)(lds + PG8_SB(b, h) + boff + n * 2048 + k * 1024); } while (0)
; #define PG8_MMA(ai, bj, At, Bt) do { __builtin_amdgcn_s_setprio(1); _Pragma("unroll") for (int m = 0; m < 4; ++m) _Pragma("unroll") for (int n = 0; n < 2; ++n) _Pragma("unroll") for (int k = 0; k < 2; ++k) \
;         acc[ai][bj][m][n] = __builtin_amdgcn_mfma_f32_16x16x32_bf16(Bt[n][k], At[m][k], acc[ai][bj][m][n], 0, 0, 0); __builtin_amdgcn_s_setprio(0); } while (0)
; #define PG8_WAIT_V89() do { if constexpr (SLIVER) PG8_WAIT_V(9); else PG8_WAIT_V(8); } while (0)
; #define PG8_STAGE_S(b, gbase) do { if constexpr (SLIVER) __builtin_amdgcn_global_load_lds((const unsigned*)((const char*)(gbase) + voffS), (PG8_LAS unsigned*)(lds + STAGE_BYTES + (b) * 2048 + wid * 256), 4, 0, 0); } while (0)
; #define PG8_WAIT_L(n) asm volatile("s_waitcnt lgkmcnt(" #n ")" ::: "memory")
; #define PG8_BAR __builtin_amdgcn_s_barrier()
; #define PG8_SCHED __builtin_amdgcn_sched_barrier(0)
; template <class Epi, class Sched, bool ALIGN_EPI = false, bool SP2 = false, bool SLIVER = false>
; __device__ __forceinline__ void gemm_phase(PG8_LAS unsigned char* lds, const Gemm g, const Sched& S, const Epi& E) {
;     ...
;             PG8_WAIT_V89(); PG8_WAIT_L(0); PG8_BAR; PG8_MMA(1, 0, At, B0); PG8_MMA(1, 1, At, B1); PG8_MMA_S(); PG8_BAR; PG8_SCHED;
;             PG8_LDB(B0, 1, 0); PG8_LDB(B1, 1, 1); PG8_SCHED; PG8_LDA(At, 1, 0); PG8_STAGE(PG8_SA(0, 1), a2 + hstep, voffA); PG8_STAGE_S(0, s2);
;             PG8_WAIT_V89(); PG8_WAIT_L(0); PG8_BAR; PG8_MMA(0, 0, At, B0); PG8_MMA(0, 1, At, B1); PG8_BAR; PG8_SCHED;
.LBB0_502:
	s_barrier
	s_setprio 0
	s_add_u32 s68, s62, s80
	s_addc_u32 s69, s63, s81
	s_add_u32 s76, s68, 0x100
	s_addc_u32 s77, s69, 0
	s_and_b64 s[68:69], s[86:87], exec
	s_cselect_b32 s69, s85, s77
	s_cselect_b32 s68, s84, s76
	s_add_i32 s76, 0, 0x18000
	v_add_u32_e32 v82, s76, v239
	s_add_i32 s77, 0, 0x1c000
	ds_read_b128 v[146:149], v82
	ds_read_b128 v[150:153], v82 offset:1024
	ds_read_b128 v[154:157], v82 offset:2048
	ds_read_b128 v[158:161], v82 offset:3072
	v_add_u32_e32 v82, s77, v239
	ds_read_b128 v[166:169], v82
	ds_read_b128 v[170:173], v82 offset:1024
	ds_read_b128 v[174:177], v82 offset:2048
	ds_read_b128 v[162:165], v82 offset:3072
	s_mov_b32 m0, s91
	v_lshl_add_u64 v[208:209], v[194:195], 0, s[24:25]
	ds_read_b128 v[82:85], v242 offset:32768
	ds_read_b128 v[94:97], v242 offset:33792
	ds_read_b128 v[180:183], v242 offset:34816
	ds_read_b128 v[184:187], v242 offset:35840
	ds_read_b128 v[196:199], v242 offset:36864
	ds_read_b128 v[200:203], v242 offset:37888
	ds_read_b128 v[220:223], v242 offset:38912
	ds_read_b128 v[224:227], v242 offset:39936
	global_load_lds_dwordx4 v[208:209], off
	v_lshl_add_u64 v[208:209], v[194:195], 0, s[14:15]
	s_mov_b32 m0, s92
	s_nop 0
	global_load_lds_dwordx4 v[208:209], off
	v_lshl_add_u64 v[208:209], s[68:69], 0, v[214:215]
	s_mov_b32 m0, s93
	s_nop 0
	global_load_lds_dword v[208:209], off
	s_waitcnt vmcnt(9)
	s_waitcnt lgkmcnt(0)
	s_setprio 1
	s_barrier
	v_mfma_f32_16x16x32_bf16 v[134:137], v[146:149], v[82:85], v[134:137]
	v_mfma_f32_16x16x32_bf16 v[134:137], v[150:153], v[94:97], v[134:137]
	v_mfma_f32_16x16x32_bf16 v[130:133], v[158:161], v[94:97], v[130:133]
	v_mfma_f32_16x16x32_bf16 v[130:133], v[154:157], v[82:85], v[130:133]
	v_mfma_f32_16x16x32_bf16 v[122:125], v[154:157], v[180:183], v[122:125]
	v_mfma_f32_16x16x32_bf16 v[122:125], v[158:161], v[184:187], v[122:125]
	v_mfma_f32_16x16x32_bf16 v[126:129], v[150:153], v[184:187], v[126:129]
	v_mfma_f32_16x16x32_bf16 v[126:129], v[146:149], v[180:183], v[126:129]
	s_setprio 0
	s_setprio 1
	v_mfma_f32_16x16x32_bf16 v[118:121], v[146:149], v[196:199], v[118:121]
	v_mfma_f32_16x16x32_bf16 v[118:121], v[150:153], v[200:203], v[118:121]
	v_mfma_f32_16x16x32_bf16 v[114:117], v[158:161], v[200:203], v[114:117]
	v_mfma_f32_16x16x32_bf16 v[114:117], v[154:157], v[196:199], v[114:117]
	v_mfma_f32_16x16x32_bf16 v[106:109], v[154:157], v[220:223], v[106:109]
	v_mfma_f32_16x16x32_bf16 v[106:109], v[158:161], v[224:227], v[106:109]
	v_mfma_f32_16x16x32_bf16 v[110:113], v[150:153], v[224:227], v[110:113]
	v_mfma_f32_16x16x32_bf16 v[110:113], v[146:149], v[220:223], v[110:113]
	s_setprio 0
	s_setprio 1
	v_mfma_f32_16x16x32_bf16 v[102:105], v[166:169], v[82:85], v[102:105]
	v_mfma_f32_16x16x32_bf16 v[102:105], v[170:173], v[94:97], v[102:105]
	v_mfma_f32_16x16x32_bf16 v[82:85], v[174:177], v[82:85], v[98:101]
	v_mfma_f32_16x16x32_bf16 v[98:101], v[162:165], v[94:97], v[82:85]
	v_mfma_f32_16x16x32_bf16 v[82:85], v[166:169], v[180:183], v[90:93]
	v_mfma_f32_16x16x32_bf16 v[90:93], v[170:173], v[184:187], v[82:85]
	v_mfma_f32_16x16x32_bf16 v[82:85], v[174:177], v[180:183], v[86:89]
	v_mfma_f32_16x16x32_bf16 v[86:89], v[162:165], v[184:187], v[82:85]
	s_setprio 0
	s_setprio 1
	v_mfma_f32_16x16x32_bf16 v[78:81], v[166:169], v[196:199], v[78:81]
	v_mfma_f32_16x16x32_bf16 v[78:81], v[170:173], v[200:203], v[78:81]
	v_mfma_f32_16x16x32_bf16 v[74:77], v[174:177], v[196:199], v[74:77]
	v_mfma_f32_16x16x32_bf16 v[74:77], v[162:165], v[200:203], v[74:77]
	v_mfma_f32_16x16x32_bf16 v[70:73], v[166:169], v[220:223], v[70:73]
	v_mfma_f32_16x16x32_bf16 v[70:73], v[170:173], v[224:227], v[70:73]
	v_mfma_f32_16x16x32_bf16 v[66:69], v[174:177], v[220:223], v[66:69]
	v_mfma_f32_16x16x32_bf16 v[66:69], v[162:165], v[224:227], v[66:69]
	s_barrier
; #define PG8_SB(B) __builtin_amdgcn_rcpf(1.f + expneg(B))
; #define PG8_SB(B) __builtin_amdgcn_rcpf(1.f + expneg(B))
; #define PG8_STAGE(bufoff, gbase, voff) do { _Pragma("unroll") for (int _i = 0; _i < 2; ++_i) \
;         __builtin_amdgcn_global_load_lds((const unsigned*)((const char*)(gbase) + (size_t)_i * qstep + (voff)[0]), (PG8_LAS unsigned*)(lds + (bufoff) + ldsw + _i * 8192), 16, 0, 0); } while (0)
; #define PG8_LDA(dst, b, h) do { _Pragma("unroll") for (int m = 0; m < 4; ++m) _Pragma("unroll") for (int k = 0; k < 2; ++k) dst[m][k] = *(const PG8_LAS bf16x8*)(lds + PG8_SA(b, h) + aoff + m * 2048 + k * 1024); } while (0)
; #define PG8_MMA(ai, bj, At, Bt) do { __builtin_amdgcn_s_setprio(1); _Pragma("unroll") for (int m = 0; m < 4; ++m) _Pragma("unroll") for (int n = 0; n < 2; ++n) _Pragma("unroll") for (int k = 0; k < 2; ++k) \
;         acc[ai][bj][m][n] = __builtin_amdgcn_mfma_f32_16x16x32_bf16(Bt[n][k], At[m][k], acc[ai][bj][m][n], 0, 0, 0); __builtin_amdgcn_s_setprio(0); } while (0)
; #define PG8_WAIT_V89() do { if constexpr (SLIVER) PG8_WAIT_V(9); else PG8_WAIT_V(8); } while (0)
; #define PG8_LDS_S(b) do { if constexpr (SLIVER) { Sf[0] = *(const PG8_LAS bf16x8*)(lds + STAGE_BYTES + (b) * 2048 + soff0); Sf[1] = *(const PG8_LAS bf16x8*)(lds + STAGE_BYTES + (b) * 2048 + (soff0 ^ 64)); } } while (0)
; #define PG8_WAIT_L(n) asm volatile("s_waitcnt lgkmcnt(" #n ")" ::: "memory")
; #define PG8_BAR __builtin_amdgcn_s_barrier()
; #define PG8_SCHED __builtin_amdgcn_sched_barrier(0)
; template <class Epi, class Sched, bool ALIGN_EPI = false, bool SP2 = false, bool SLIVER = false>
; __device__ __forceinline__ void gemm_phase(PG8_LAS unsigned char* lds, const Gemm g, const Sched& S, const Epi& E) {
;     ...
;             PG8_LDA(At, 1, 1); PG8_LDS_S(1); PG8_STAGE(PG8_SB(1, 0), b3, voffB); PG8_STAGE(PG8_SB(1, 1), b3 + hstep, voffB); PG8_STAGE(PG8_SA(1, 0), a3, voffA);
;             PG8_WAIT_V89(); PG8_WAIT_L(0); PG8_BAR; PG8_MMA(1, 0, At, B0); PG8_MMA(1, 1, At, B1); PG8_MMA_S(); PG8_BAR; PG8_SCHED;
	s_setprio 0
	s_add_i32 s68, 0, 0x20800
	v_add_u32_e32 v178, s68, v240
	v_add_u32_e32 v184, s68, v241
	s_add_i32 s68, s76, s95
	v_lshl_add_u64 v[208:209], v[192:193], 0, s[26:27]
	s_mov_b32 m0, s68
	ds_read_b128 v[82:85], v242 offset:49152
	ds_read_b128 v[94:97], v242 offset:50176
	ds_read_b128 v[196:199], v242 offset:51200
	ds_read_b128 v[200:203], v242 offset:52224
	ds_read_b128 v[220:223], v242 offset:53248
	ds_read_b128 v[224:227], v242 offset:54272
	ds_read_b128 v[228:231], v242 offset:55296
	ds_read_b128 v[232:235], v242 offset:56320
	ds_read_b128 v[180:183], v178
	ds_read_b128 v[184:187], v184
	global_load_lds_dwordx4 v[208:209], off
	v_lshl_add_u64 v[208:209], v[192:193], 0, s[72:73]
	s_add_i32 m0, s68, 0x2000
	s_add_i32 s68, s77, s95
	global_load_lds_dwordx4 v[208:209], off
	v_lshl_add_u64 v[208:209], v[192:193], 0, s[34:35]
	s_mov_b32 m0, s68
	s_mov_b64 s[76:77], 0x120080
	global_load_lds_dwordx4 v[208:209], off
	v_lshl_add_u64 v[192:193], v[192:193], 0, s[76:77]
	s_add_i32 m0, s68, 0x2000
	s_nop 0
	global_load_lds_dwordx4 v[192:193], off
	v_lshl_add_u64 v[192:193], v[194:195], 0, s[26:27]
	s_mov_b32 m0, s97
	s_nop 0
	global_load_lds_dwordx4 v[192:193], off
	v_lshl_add_u64 v[192:193], v[194:195], 0, s[72:73]
	s_mov_b32 m0, s18
	s_nop 0
	global_load_lds_dwordx4 v[192:193], off
	s_waitcnt vmcnt(9)
	s_waitcnt lgkmcnt(0)
	s_setprio 1
	s_barrier
	v_mfma_f32_16x16x32_bf16 v[62:65], v[146:149], v[82:85], v[62:65]
	v_mfma_f32_16x16x32_bf16 v[62:65], v[150:153], v[94:97], v[62:65]
	v_mfma_f32_16x16x32_bf16 v[58:61], v[158:161], v[94:97], v[58:61]
	v_mfma_f32_16x16x32_bf16 v[58:61], v[154:157], v[82:85], v[58:61]
	v_mfma_f32_16x16x32_bf16 v[50:53], v[154:157], v[196:199], v[50:53]
	v_mfma_f32_16x16x32_bf16 v[50:53], v[158:161], v[200:203], v[50:53]
	v_mfma_f32_16x16x32_bf16 v[54:57], v[150:153], v[200:203], v[54:57]
	v_mfma_f32_16x16x32_bf16 v[54:57], v[146:149], v[196:199], v[54:57]
	s_setprio 0
	s_setprio 1
	v_mfma_f32_16x16x32_bf16 v[46:49], v[146:149], v[220:223], v[46:49]
	v_mfma_f32_16x16x32_bf16 v[46:49], v[150:153], v[224:227], v[46:49]
	v_mfma_f32_16x16x32_bf16 v[42:45], v[158:161], v[224:227], v[42:45]
	v_mfma_f32_16x16x32_bf16 v[42:45], v[154:157], v[220:223], v[42:45]
	v_mfma_f32_16x16x32_bf16 v[34:37], v[154:157], v[228:231], v[34:37]
	v_mfma_f32_16x16x32_bf16 v[34:37], v[158:161], v[232:235], v[34:37]
	v_mfma_f32_16x16x32_bf16 v[38:41], v[150:153], v[232:235], v[38:41]
	v_mfma_f32_16x16x32_bf16 v[38:41], v[146:149], v[228:231], v[38:41]
	s_setprio 0
	s_setprio 1
	v_mfma_f32_16x16x32_bf16 v[2:5], v[174:177], v[228:231], v[2:5]
	v_mfma_f32_16x16x32_bf16 v[2:5], v[162:165], v[232:235], v[2:5]
	v_mfma_f32_16x16x32_bf16 v[26:29], v[162:165], v[94:97], v[26:29]
	v_mfma_f32_16x16x32_bf16 v[26:29], v[174:177], v[82:85], v[26:29]
	v_mfma_f32_16x16x32_bf16 v[30:33], v[166:169], v[82:85], v[30:33]
	v_mfma_f32_16x16x32_bf16 v[30:33], v[170:173], v[94:97], v[30:33]
	v_mfma_f32_16x16x32_bf16 v[22:25], v[170:173], v[200:203], v[22:25]
	v_mfma_f32_16x16x32_bf16 v[22:25], v[166:169], v[196:199], v[22:25]
	s_setprio 0
	s_setprio 1
	v_mfma_f32_16x16x32_bf16 v[18:21], v[174:177], v[196:199], v[18:21]
	v_mfma_f32_16x16x32_bf16 v[18:21], v[162:165], v[200:203], v[18:21]
	v_mfma_f32_16x16x32_bf16 v[10:13], v[162:165], v[224:227], v[10:13]
	v_mfma_f32_16x16x32_bf16 v[10:13], v[174:177], v[220:223], v[10:13]
	v_mfma_f32_16x16x32_bf16 v[14:17], v[166:169], v[220:223], v[14:17]
	v_mfma_f32_16x16x32_bf16 v[14:17], v[170:173], v[224:227], v[14:17]
	v_mfma_f32_16x16x32_bf16 v[6:9], v[170:173], v[232:235], v[6:9]
	v_mfma_f32_16x16x32_bf16 v[6:9], v[166:169], v[228:231], v[6:9]
	s_setprio 0
	s_setprio 1
	s_and_b64 vcc, exec, s[52:53]
	s_cbranch_vccz .Lslv_c0
	v_mfma_f32_16x16x32_bf16 v[82:85], v[166:169], v[180:183], v[138:141]
	v_mfma_f32_16x16x32_bf16 v[94:97], v[174:177], v[180:183], v[142:145]
	v_mfma_f32_16x16x32_bf16 v[82:85], v[170:173], v[184:187], v[82:85]
	v_mfma_f32_16x16x32_bf16 v[94:97], v[162:165], v[184:187], v[94:97]
	s_branch .LBB0_497

; #define PG8_STAGE(bufoff, gbase, voff) do { _Pragma("unroll") for (int _i = 0; _i < 2; ++_i) \
;         __builtin_amdgcn_global_load_lds((const unsigned*)((const char*)(gbase) + (size_t)_i * qstep + (voff)[0]), (PG8_LAS unsigned*)(lds + (bufoff) + ldsw + _i * 8192), 16, 0, 0); } while (0)
; #define PG8_LDA(dst, b, h) do { _Pragma("unroll") for (int m = 0; m < 4; ++m) _Pragma("unroll") for (int k = 0; k < 2; ++k) dst[m][k] = *(const PG8_LAS bf16x8*)(lds + PG8_SA(b, h) + aoff + m * 2048 + k * 1024); } while (0)
; #define PG8_LDB(dst, b, h) do { _Pragma("unroll") for (int n = 0; n < 2; ++n) _Pragma("unroll") for (int k = 0; k < 2; ++k) dst[n][k] = *(const PG8_LAS bf16x8*)(lds + PG8_SB(b, h) + boff + n * 2048 + k * 1024); } while (0)
; #define PG8_MMA(ai, bj, At, Bt) do { __builtin_amdgcn_s_setprio(1); _Pragma("unroll") for (int m = 0; m < 4; ++m) _Pragma("unroll") for (int n = 0; n < 2; ++n) _Pragma("unroll") for (int k = 0; k < 2; ++k) \
;         acc[ai][bj][m][n] = __builtin_amdgcn_mfma_f32_16x16x32_bf16(Bt[n][k], At[m][k], acc[ai][bj][m][n], 0, 0, 0); __builtin_amdgcn_s_setprio(0); } while (0)
; #define PG8_WAIT_V89() do { if constexpr (SLIVER) PG8_WAIT_V(9); else PG8_WAIT_V(8); } while (0)
; #define PG8_WAIT_L(n) asm volatile("s_waitcnt lgkmcnt(" #n ")" ::: "memory")
; #define PG8_BAR __builtin_amdgcn_s_barrier()
; #define PG8_SCHED __builtin_amdgcn_sched_barrier(0)
; template <class Epi, class Sched, bool ALIGN_EPI = false, bool SP2 = false, bool SLIVER = false>
; __device__ __forceinline__ void gemm_phase(PG8_LAS unsigned char* lds, const Gemm g, const Sched& S, const Epi& E) {
;     ...
;             const bool last = (t == nt - 2);
;             const char* a1 = cA + (size_t)(t + 1) * kstep;
;             const char* a2 = last ? nA : cA + (size_t)(t + 2) * kstep; const char* b2 = last ? nB : cB + (size_t)(t + 2) * kstep;
;             const char* a3 = a2 + kstep; const char* b3 = b2 + kstep;
;             const char* s1 = cS + (size_t)(t + 1) * kstep; const char* s2 = last ? nS : cS + (size_t)(t + 2) * kstep;
;             if (last && has_next) S.a_ready(nxt);
;             if constexpr (SP2) {
;             PG8_LDB(B0, 0, 0); PG8_LDB(B1, 0, 1); PG8_SCHED; PG8_LDA(At, 0, 0); PG8_STAGE(PG8_SA(1, 1), a1 + hstep, voffA); PG8_STAGE_S(1, s1);
;             PG8_WAIT_V89(); PG8_WAIT_L(0); PG8_BAR; PG8_MMA(0, 0, At, B0); PG8_MMA(0, 1, At, B1); PG8_BAR; PG8_SCHED;
.LBB0_598:
	s_add_u32 s40, s92, s62
	s_addc_u32 s41, s93, s63
	s_add_u32 s77, s40, 0x100
	s_addc_u32 s78, s41, 0
	s_add_u32 s83, s68, s62
	s_addc_u32 s79, s69, s63
	s_add_i32 s96, 0, 0x10000
	s_cmpk_eq_i32 s62, 0xf00
	s_cselect_b64 s[80:81], -1, 0
	s_and_b64 s[40:41], s[80:81], exec
	s_cselect_b32 s41, s12, s78
	s_cselect_b32 s40, s13, s77
	v_add_u32_e32 v138, s96, v212
	s_cselect_b32 s79, s17, s79
	s_cselect_b32 s78, s55, s83
	s_add_i32 s77, 0, 0x14000
	ds_read_b128 v[146:149], v138
	ds_read_b128 v[150:153], v138 offset:1024
	ds_read_b128 v[154:157], v138 offset:2048
	ds_read_b128 v[158:161], v138 offset:3072
	v_add_u32_e32 v138, s77, v212
	ds_read_b128 v[166:169], v138
	ds_read_b128 v[170:173], v138 offset:1024
	ds_read_b128 v[174:177], v138 offset:2048
	ds_read_b128 v[162:165], v138 offset:3072
	v_lshl_add_u64 v[202:203], v[200:201], 0, s[62:63]
	v_lshl_add_u64 v[208:209], v[202:203], 0, s[30:31]
	s_add_i32 m0, s85, 0xc000
	ds_read_b128 v[138:141], v215
	ds_read_b128 v[142:145], v215 offset:1024
	ds_read_b128 v[180:183], v215 offset:2048
	ds_read_b128 v[184:187], v215 offset:3072
	ds_read_b128 v[216:219], v215 offset:4096
	ds_read_b128 v[220:223], v215 offset:5120
	ds_read_b128 v[224:227], v215 offset:6144
	ds_read_b128 v[228:231], v215 offset:7168
	global_load_lds_dwordx4 v[208:209], off
	v_lshl_add_u64 v[202:203], v[202:203], 0, s[34:35]
	s_add_i32 m0, s85, 0xe000
	s_nop 0
	global_load_lds_dwordx4 v[202:203], off
	v_lshl_add_u64 v[202:203], v[198:199], 0, s[62:63]
	s_add_i32 m0, s45, 0x20800
	s_nop 0
	global_load_lds_dword v[202:203], off
	s_waitcnt vmcnt(9)
	s_waitcnt lgkmcnt(0)
	s_setprio 1
	s_barrier
	v_mfma_f32_16x16x32_bf16 v[134:137], v[146:149], v[138:141], v[134:137]
	v_mfma_f32_16x16x32_bf16 v[134:137], v[150:153], v[142:145], v[134:137]
	v_mfma_f32_16x16x32_bf16 v[130:133], v[158:161], v[142:145], v[130:133]
	v_mfma_f32_16x16x32_bf16 v[130:133], v[154:157], v[138:141], v[130:133]
	v_mfma_f32_16x16x32_bf16 v[114:117], v[154:157], v[180:183], v[114:117]
	v_mfma_f32_16x16x32_bf16 v[114:117], v[158:161], v[184:187], v[114:117]
	v_mfma_f32_16x16x32_bf16 v[118:121], v[150:153], v[184:187], v[118:121]
	v_mfma_f32_16x16x32_bf16 v[118:121], v[146:149], v[180:183], v[118:121]
	s_setprio 0
	s_setprio 1
	v_mfma_f32_16x16x32_bf16 v[102:105], v[146:149], v[216:219], v[102:105]
	v_mfma_f32_16x16x32_bf16 v[102:105], v[150:153], v[220:223], v[102:105]
	v_mfma_f32_16x16x32_bf16 v[98:101], v[158:161], v[220:223], v[98:101]
	v_mfma_f32_16x16x32_bf16 v[98:101], v[154:157], v[216:219], v[98:101]
	v_mfma_f32_16x16x32_bf16 v[82:85], v[154:157], v[224:227], v[82:85]
	v_mfma_f32_16x16x32_bf16 v[82:85], v[158:161], v[228:231], v[82:85]
	v_mfma_f32_16x16x32_bf16 v[86:89], v[150:153], v[228:231], v[86:89]
	v_mfma_f32_16x16x32_bf16 v[86:89], v[146:149], v[224:227], v[86:89]
	s_setprio 0
	s_setprio 1
	v_mfma_f32_16x16x32_bf16 v[74:77], v[174:177], v[224:227], v[74:77]
	v_mfma_f32_16x16x32_bf16 v[74:77], v[162:165], v[228:231], v[74:77]
	v_mfma_f32_16x16x32_bf16 v[122:125], v[162:165], v[142:145], v[122:125]
	v_mfma_f32_16x16x32_bf16 v[122:125], v[174:177], v[138:141], v[122:125]
	v_mfma_f32_16x16x32_bf16 v[126:129], v[166:169], v[138:141], v[126:129]
	v_mfma_f32_16x16x32_bf16 v[126:129], v[170:173], v[142:145], v[126:129]
	v_mfma_f32_16x16x32_bf16 v[110:113], v[170:173], v[184:187], v[110:113]
	v_mfma_f32_16x16x32_bf16 v[110:113], v[166:169], v[180:183], v[110:113]
	s_setprio 0
	s_setprio 1
	v_mfma_f32_16x16x32_bf16 v[106:109], v[174:177], v[180:183], v[106:109]
	v_mfma_f32_16x16x32_bf16 v[106:109], v[162:165], v[184:187], v[106:109]
	v_mfma_f32_16x16x32_bf16 v[90:93], v[162:165], v[220:223], v[90:93]
	v_mfma_f32_16x16x32_bf16 v[90:93], v[174:177], v[216:219], v[90:93]
	v_mfma_f32_16x16x32_bf16 v[94:97], v[166:169], v[216:219], v[94:97]
	v_mfma_f32_16x16x32_bf16 v[94:97], v[170:173], v[220:223], v[94:97]
	v_mfma_f32_16x16x32_bf16 v[78:81], v[170:173], v[228:231], v[78:81]
	v_mfma_f32_16x16x32_bf16 v[78:81], v[166:169], v[224:227], v[78:81]
	s_barrier
; #define PG8_SB(B) __builtin_amdgcn_rcpf(1.f + expneg(B))
; #define PG8_SB(B) __builtin_amdgcn_rcpf(1.f + expneg(B))
; #define PG8_STAGE(bufoff, gbase, voff) do { _Pragma("unroll") for (int _i = 0; _i < 2; ++_i) \
;         __builtin_amdgcn_global_load_lds((const unsigned*)((const char*)(gbase) + (size_t)_i * qstep + (voff)[0]), (PG8_LAS unsigned*)(lds + (bufoff) + ldsw + _i * 8192), 16, 0, 0); } while (0)
; #define PG8_LDA(dst, b, h) do { _Pragma("unroll") for (int m = 0; m < 4; ++m) _Pragma("unroll") for (int k = 0; k < 2; ++k) dst[m][k] = *(const PG8_LAS bf16x8*)(lds + PG8_SA(b, h) + aoff + m * 2048 + k * 1024); } while (0)
; #define PG8_MMA(ai, bj, At, Bt) do { __builtin_amdgcn_s_setprio(1); _Pragma("unroll") for (int m = 0; m < 4; ++m) _Pragma("unroll") for (int n = 0; n < 2; ++n) _Pragma("unroll") for (int k = 0; k < 2; ++k) \
;         acc[ai][bj][m][n] = __builtin_amdgcn_mfma_f32_16x16x32_bf16(Bt[n][k], At[m][k], acc[ai][bj][m][n], 0, 0, 0); __builtin_amdgcn_s_setprio(0); } while (0)
; #define PG8_WAIT_V89() do { if constexpr (SLIVER) PG8_WAIT_V(9); else PG8_WAIT_V(8); } while (0)
; #define PG8_LDS_S(b) do { if constexpr (SLIVER) { Sf[0] = *(const PG8_LAS bf16x8*)(lds + STAGE_BYTES + (b) * 2048 + soff0); Sf[1] = *(const PG8_LAS bf16x8*)(lds + STAGE_BYTES + (b) * 2048 + (soff0 ^ 64)); } } while (0)
; #define PG8_WAIT_L(n) asm volatile("s_waitcnt lgkmcnt(" #n ")" ::: "memory")
; #define PG8_BAR __builtin_amdgcn_s_barrier()
; #define PG8_SCHED __builtin_amdgcn_sched_barrier(0)
; template <class Epi, class Sched, bool ALIGN_EPI = false, bool SP2 = false, bool SLIVER = false>
; __device__ __forceinline__ void gemm_phase(PG8_LAS unsigned char* lds, const Gemm g, const Sched& S, const Epi& E) {
;     ...
;             PG8_LDA(At, 0, 1); PG8_LDS_S(0); PG8_STAGE(PG8_SB(0, 0), b2, voffB); PG8_STAGE(PG8_SB(0, 1), b2 + hstep, voffB); PG8_STAGE(PG8_SA(0, 0), a2, voffA);
;             PG8_WAIT_V89(); PG8_WAIT_L(0); PG8_BAR; PG8_MMA(1, 0, At, B0); PG8_MMA(1, 1, At, B1); PG8_MMA_S(); PG8_BAR; PG8_SCHED;
	s_setprio 0
	s_add_i32 s83, 0, 0x20000
	v_lshl_add_u64 v[202:203], s[78:79], 0, v[190:191]
	s_add_i32 s78, s96, s18
	v_add_u32_e32 v178, s83, v213
	v_add_u32_e32 v184, s83, v214
	s_mov_b32 m0, s78
	ds_read_b128 v[138:141], v215 offset:16384
	ds_read_b128 v[142:145], v215 offset:17408
	ds_read_b128 v[216:219], v215 offset:18432
	ds_read_b128 v[220:223], v215 offset:19456
	ds_read_b128 v[224:227], v215 offset:20480
	ds_read_b128 v[228:231], v215 offset:21504
	ds_read_b128 v[232:235], v215 offset:22528
	ds_read_b128 v[240:243], v215 offset:23552
	ds_read_b128 v[180:183], v178
	ds_read_b128 v[184:187], v184
	global_load_lds_dwordx4 v[202:203], off
	v_lshl_add_u64 v[208:209], v[202:203], 0, s[20:21]
	s_add_i32 m0, s78, 0x2000
	s_add_i32 s77, s77, s18
	global_load_lds_dwordx4 v[208:209], off
	v_lshl_add_u64 v[208:209], v[202:203], 0, s[22:23]
	s_mov_b32 m0, s77
	v_lshl_add_u64 v[210:211], s[40:41], 0, v[188:189]
	global_load_lds_dwordx4 v[208:209], off
	v_lshl_add_u64 v[208:209], v[202:203], 0, s[24:25]
	s_add_i32 m0, s77, 0x2000
	s_nop 0
	global_load_lds_dwordx4 v[208:209], off
	s_mov_b32 m0, s85
	v_lshl_add_u64 v[208:209], v[210:211], 0, s[20:21]
	global_load_lds_dwordx4 v[210:211], off
	s_mov_b32 m0, s19
	s_nop 0
	global_load_lds_dwordx4 v[208:209], off
	s_waitcnt vmcnt(9)
	s_waitcnt lgkmcnt(0)
	s_setprio 1
	s_barrier
	v_mfma_f32_16x16x32_bf16 v[70:73], v[146:149], v[138:141], v[70:73]
	v_mfma_f32_16x16x32_bf16 v[70:73], v[150:153], v[142:145], v[70:73]
	v_mfma_f32_16x16x32_bf16 v[66:69], v[158:161], v[142:145], v[66:69]
	v_mfma_f32_16x16x32_bf16 v[66:69], v[154:157], v[138:141], v[66:69]
	v_mfma_f32_16x16x32_bf16 v[50:53], v[154:157], v[216:219], v[50:53]
	v_mfma_f32_16x16x32_bf16 v[50:53], v[158:161], v[220:223], v[50:53]
	v_mfma_f32_16x16x32_bf16 v[54:57], v[150:153], v[220:223], v[54:57]
	v_mfma_f32_16x16x32_bf16 v[54:57], v[146:149], v[216:219], v[54:57]
	s_setprio 0
	s_setprio 1
	v_mfma_f32_16x16x32_bf16 v[38:41], v[146:149], v[224:227], v[38:41]
	v_mfma_f32_16x16x32_bf16 v[38:41], v[150:153], v[228:231], v[38:41]
	v_mfma_f32_16x16x32_bf16 v[34:37], v[158:161], v[228:231], v[34:37]
	v_mfma_f32_16x16x32_bf16 v[34:37], v[154:157], v[224:227], v[34:37]
	v_mfma_f32_16x16x32_bf16 v[18:21], v[154:157], v[232:235], v[18:21]
	v_mfma_f32_16x16x32_bf16 v[18:21], v[158:161], v[240:243], v[18:21]
	v_mfma_f32_16x16x32_bf16 v[22:25], v[150:153], v[240:243], v[22:25]
	v_mfma_f32_16x16x32_bf16 v[22:25], v[146:149], v[232:235], v[22:25]
	s_setprio 0
	s_setprio 1
	v_mfma_f32_16x16x32_bf16 v[10:13], v[174:177], v[232:235], v[10:13]
	v_mfma_f32_16x16x32_bf16 v[10:13], v[162:165], v[240:243], v[10:13]
	v_mfma_f32_16x16x32_bf16 v[58:61], v[162:165], v[142:145], v[58:61]
	v_mfma_f32_16x16x32_bf16 v[58:61], v[174:177], v[138:141], v[58:61]
	v_mfma_f32_16x16x32_bf16 v[62:65], v[166:169], v[138:141], v[62:65]
	v_mfma_f32_16x16x32_bf16 v[62:65], v[170:173], v[142:145], v[62:65]
	v_mfma_f32_16x16x32_bf16 v[46:49], v[170:173], v[220:223], v[46:49]
	v_mfma_f32_16x16x32_bf16 v[46:49], v[166:169], v[216:219], v[46:49]
	s_setprio 0
	s_setprio 1
	v_mfma_f32_16x16x32_bf16 v[42:45], v[174:177], v[216:219], v[42:45]
	v_mfma_f32_16x16x32_bf16 v[42:45], v[162:165], v[220:223], v[42:45]
	v_mfma_f32_16x16x32_bf16 v[26:29], v[162:165], v[228:231], v[26:29]
	v_mfma_f32_16x16x32_bf16 v[26:29], v[174:177], v[224:227], v[26:29]
	v_mfma_f32_16x16x32_bf16 v[30:33], v[166:169], v[224:227], v[30:33]
	v_mfma_f32_16x16x32_bf16 v[30:33], v[170:173], v[228:231], v[30:33]
	v_mfma_f32_16x16x32_bf16 v[14:17], v[170:173], v[240:243], v[14:17]
	v_mfma_f32_16x16x32_bf16 v[14:17], v[166:169], v[232:235], v[14:17]
	s_setprio 0
	s_setprio 1
	s_and_b64 vcc, exec, s[52:53]
	s_cbranch_vccz .Lslv_b1
	v_mfma_f32_16x16x32_bf16 v[138:141], v[166:169], v[180:183], v[6:9]
	v_mfma_f32_16x16x32_bf16 v[142:145], v[174:177], v[180:183], v[2:5]
	v_mfma_f32_16x16x32_bf16 v[138:141], v[170:173], v[184:187], v[138:141]
	v_mfma_f32_16x16x32_bf16 v[142:145], v[162:165], v[184:187], v[142:145]
	s_branch .LBB0_602

; #define PG8_STAGE(bufoff, gbase, voff) do { _Pragma("unroll") for (int _i = 0; _i < 2; ++_i) \
;         __builtin_amdgcn_global_load_lds((const unsigned*)((const char*)(gbase) + (size_t)_i * qstep + (voff)[0]), (PG8_LAS unsigned*)(lds + (bufoff) + ldsw + _i * 8192), 16, 0, 0); } while (0)
; #define PG8_LDA(dst, b, h) do { _Pragma("unroll") for (int m = 0; m < 4; ++m) _Pragma("unroll") for (int k = 0; k < 2; ++k) dst[m][k] = *(const PG8_LAS bf16x8*)(lds + PG8_SA(b, h) + aoff + m * 2048 + k * 1024); } while (0)
; #define PG8_LDB(dst, b, h) do { _Pragma("unroll") for (int n = 0; n < 2; ++n) _Pragma("unroll") for (int k = 0; k < 2; ++k) dst[n][k] = *(const PG8_LAS bf16x8*)(lds + PG8_SB(b, h) + boff + n * 2048 + k * 1024); } while (0)
; #define PG8_MMA(ai, bj, At, Bt) do { __builtin_amdgcn_s_setprio(1); _Pragma("unroll") for (int m = 0; m < 4; ++m) _Pragma("unroll") for (int n = 0; n < 2; ++n) _Pragma("unroll") for (int k = 0; k < 2; ++k) \
;         acc[ai][bj][m][n] = __builtin_amdgcn_mfma_f32_16x16x32_bf16(Bt[n][k], At[m][k], acc[ai][bj][m][n], 0, 0, 0); __builtin_amdgcn_s_setprio(0); } while (0)
; #define PG8_WAIT_V89() do { if constexpr (SLIVER) PG8_WAIT_V(9); else PG8_WAIT_V(8); } while (0)
; #define PG8_STAGE_S(b, gbase) do { if constexpr (SLIVER) __builtin_amdgcn_global_load_lds((const unsigned*)((const char*)(gbase) + voffS), (PG8_LAS unsigned*)(lds + STAGE_BYTES + (b) * 2048 + wid * 256), 4, 0, 0); } while (0)
; #define PG8_WAIT_L(n) asm volatile("s_waitcnt lgkmcnt(" #n ")" ::: "memory")
; #define PG8_BAR __builtin_amdgcn_s_barrier()
; #define PG8_SCHED __builtin_amdgcn_sched_barrier(0)
; template <class Epi, class Sched, bool ALIGN_EPI = false, bool SP2 = false, bool SLIVER = false>
; __device__ __forceinline__ void gemm_phase(PG8_LAS unsigned char* lds, const Gemm g, const Sched& S, const Epi& E) {
;     ...
;             PG8_WAIT_V89(); PG8_WAIT_L(0); PG8_BAR; PG8_MMA(1, 0, At, B0); PG8_MMA(1, 1, At, B1); PG8_MMA_S(); PG8_BAR; PG8_SCHED;
;             PG8_LDB(B0, 1, 0); PG8_LDB(B1, 1, 1); PG8_SCHED; PG8_LDA(At, 1, 0); PG8_STAGE(PG8_SA(0, 1), a2 + hstep, voffA); PG8_STAGE_S(0, s2);
;             PG8_WAIT_V89(); PG8_WAIT_L(0); PG8_BAR; PG8_MMA(0, 0, At, B0); PG8_MMA(0, 1, At, B1); PG8_BAR; PG8_SCHED;
.LBB0_602:
	s_barrier
	s_setprio 0
	s_add_u32 s77, s94, s62
	s_addc_u32 s78, s95, s63
	s_add_u32 s77, s77, 0x100
	s_addc_u32 s83, s78, 0
	s_and_b64 s[78:79], s[80:81], exec
	s_cselect_b32 s79, s66, s83
	s_cselect_b32 s78, s67, s77
	s_add_i32 s77, 0, 0x18000
	v_add_u32_e32 v2, s77, v212
	s_add_i32 s80, 0, 0x1c000
	ds_read_b128 v[146:149], v2
	ds_read_b128 v[150:153], v2 offset:1024
	ds_read_b128 v[154:157], v2 offset:2048
	ds_read_b128 v[158:161], v2 offset:3072
	v_add_u32_e32 v2, s80, v212
	ds_read_b128 v[166:169], v2
	ds_read_b128 v[170:173], v2 offset:1024
	ds_read_b128 v[174:177], v2 offset:2048
	ds_read_b128 v[162:165], v2 offset:3072
	s_mov_b32 m0, s49
	v_lshl_add_u64 v[208:209], v[210:211], 0, s[22:23]
	ds_read_b128 v[2:5], v215 offset:32768
	ds_read_b128 v[6:9], v215 offset:33792
	ds_read_b128 v[180:183], v215 offset:34816
	ds_read_b128 v[184:187], v215 offset:35840
	ds_read_b128 v[216:219], v215 offset:36864
	ds_read_b128 v[220:223], v215 offset:37888
	ds_read_b128 v[224:227], v215 offset:38912
	ds_read_b128 v[228:231], v215 offset:39936
	global_load_lds_dwordx4 v[208:209], off
	v_lshl_add_u64 v[208:209], v[210:211], 0, s[24:25]
	s_mov_b32 m0, s50
	s_nop 0
	global_load_lds_dwordx4 v[208:209], off
	v_lshl_add_u64 v[208:209], s[78:79], 0, v[192:193]
	s_mov_b32 m0, s51
	s_nop 0
	global_load_lds_dword v[208:209], off
	s_waitcnt vmcnt(9)
	s_waitcnt lgkmcnt(0)
	s_setprio 1
	s_barrier
	v_mfma_f32_16x16x32_bf16 v[134:137], v[146:149], v[2:5], v[134:137]
	v_mfma_f32_16x16x32_bf16 v[134:137], v[150:153], v[6:9], v[134:137]
	v_mfma_f32_16x16x32_bf16 v[130:133], v[158:161], v[6:9], v[130:133]
	v_mfma_f32_16x16x32_bf16 v[130:133], v[154:157], v[2:5], v[130:133]
	v_mfma_f32_16x16x32_bf16 v[114:117], v[154:157], v[180:183], v[114:117]
	v_mfma_f32_16x16x32_bf16 v[114:117], v[158:161], v[184:187], v[114:117]
	v_mfma_f32_16x16x32_bf16 v[118:121], v[150:153], v[184:187], v[118:121]
	v_mfma_f32_16x16x32_bf16 v[118:121], v[146:149], v[180:183], v[118:121]
	s_setprio 0
	s_setprio 1
	v_mfma_f32_16x16x32_bf16 v[102:105], v[146:149], v[216:219], v[102:105]
	v_mfma_f32_16x16x32_bf16 v[102:105], v[150:153], v[220:223], v[102:105]
	v_mfma_f32_16x16x32_bf16 v[98:101], v[158:161], v[220:223], v[98:101]
	v_mfma_f32_16x16x32_bf16 v[98:101], v[154:157], v[216:219], v[98:101]
	v_mfma_f32_16x16x32_bf16 v[82:85], v[154:157], v[224:227], v[82:85]
	v_mfma_f32_16x16x32_bf16 v[82:85], v[158:161], v[228:231], v[82:85]
	v_mfma_f32_16x16x32_bf16 v[86:89], v[150:153], v[228:231], v[86:89]
	v_mfma_f32_16x16x32_bf16 v[86:89], v[146:149], v[224:227], v[86:89]
	s_setprio 0
	s_setprio 1
	v_mfma_f32_16x16x32_bf16 v[126:129], v[166:169], v[2:5], v[126:129]
	v_mfma_f32_16x16x32_bf16 v[126:129], v[170:173], v[6:9], v[126:129]
	v_mfma_f32_16x16x32_bf16 v[2:5], v[174:177], v[2:5], v[122:125]
	v_mfma_f32_16x16x32_bf16 v[122:125], v[162:165], v[6:9], v[2:5]
	v_mfma_f32_16x16x32_bf16 v[2:5], v[166:169], v[180:183], v[110:113]
	v_mfma_f32_16x16x32_bf16 v[110:113], v[170:173], v[184:187], v[2:5]
	v_mfma_f32_16x16x32_bf16 v[2:5], v[174:177], v[180:183], v[106:109]
	v_mfma_f32_16x16x32_bf16 v[106:109], v[162:165], v[184:187], v[2:5]
	s_setprio 0
	s_setprio 1
	v_mfma_f32_16x16x32_bf16 v[2:5], v[166:169], v[216:219], v[94:97]
	v_mfma_f32_16x16x32_bf16 v[94:97], v[170:173], v[220:223], v[2:5]
	v_mfma_f32_16x16x32_bf16 v[2:5], v[174:177], v[216:219], v[90:93]
	v_mfma_f32_16x16x32_bf16 v[90:93], v[162:165], v[220:223], v[2:5]
	v_mfma_f32_16x16x32_bf16 v[2:5], v[166:169], v[224:227], v[78:81]
	v_mfma_f32_16x16x32_bf16 v[78:81], v[170:173], v[228:231], v[2:5]
	v_mfma_f32_16x16x32_bf16 v[2:5], v[174:177], v[224:227], v[74:77]
	v_mfma_f32_16x16x32_bf16 v[74:77], v[162:165], v[228:231], v[2:5]
	s_barrier
; #define PG8_SB(B) __builtin_amdgcn_rcpf(1.f + expneg(B))
; #define PG8_SB(B) __builtin_amdgcn_rcpf(1.f + expneg(B))
; #define PG8_STAGE(bufoff, gbase, voff) do { _Pragma("unroll") for (int _i = 0; _i < 2; ++_i) \
;         __builtin_amdgcn_global_load_lds((const unsigned*)((const char*)(gbase) + (size_t)_i * qstep + (voff)[0]), (PG8_LAS unsigned*)(lds + (bufoff) + ldsw + _i * 8192), 16, 0, 0); } while (0)
; #define PG8_LDA(dst, b, h) do { _Pragma("unroll") for (int m = 0; m < 4; ++m) _Pragma("unroll") for (int k = 0; k < 2; ++k) dst[m][k] = *(const PG8_LAS bf16x8*)(lds + PG8_SA(b, h) + aoff + m * 2048 + k * 1024); } while (0)
; #define PG8_MMA(ai, bj, At, Bt) do { __builtin_amdgcn_s_setprio(1); _Pragma("unroll") for (int m = 0; m < 4; ++m) _Pragma("unroll") for (int n = 0; n < 2; ++n) _Pragma("unroll") for (int k = 0; k < 2; ++k) \
;         acc[ai][bj][m][n] = __builtin_amdgcn_mfma_f32_16x16x32_bf16(Bt[n][k], At[m][k], acc[ai][bj][m][n], 0, 0, 0); __builtin_amdgcn_s_setprio(0); } while (0)
; #define PG8_WAIT_V89() do { if constexpr (SLIVER) PG8_WAIT_V(9); else PG8_WAIT_V(8); } while (0)
; #define PG8_LDS_S(b) do { if constexpr (SLIVER) { Sf[0] = *(const PG8_LAS bf16x8*)(lds + STAGE_BYTES + (b) * 2048 + soff0); Sf[1] = *(const PG8_LAS bf16x8*)(lds + STAGE_BYTES + (b) * 2048 + (soff0 ^ 64)); } } while (0)
; #define PG8_WAIT_L(n) asm volatile("s_waitcnt lgkmcnt(" #n ")" ::: "memory")
; #define PG8_BAR __builtin_amdgcn_s_barrier()
; #define PG8_SCHED __builtin_amdgcn_sched_barrier(0)
; template <class Epi, class Sched, bool ALIGN_EPI = false, bool SP2 = false, bool SLIVER = false>
; __device__ __forceinline__ void gemm_phase(PG8_LAS unsigned char* lds, const Gemm g, const Sched& S, const Epi& E) {
;     ...
;             PG8_LDA(At, 1, 1); PG8_LDS_S(1); PG8_STAGE(PG8_SB(1, 0), b3, voffB); PG8_STAGE(PG8_SB(1, 1), b3 + hstep, voffB); PG8_STAGE(PG8_SA(1, 0), a3, voffA);
;             PG8_WAIT_V89(); PG8_WAIT_L(0); PG8_BAR; PG8_MMA(1, 0, At, B0); PG8_MMA(1, 1, At, B1); PG8_MMA_S(); PG8_BAR; PG8_SCHED;
	s_setprio 0
	s_add_i32 s78, 0, 0x20800
	s_add_i32 s77, s77, s18
	v_add_u32_e32 v178, s78, v213
	v_add_u32_e32 v184, s78, v214
	v_lshl_add_u64 v[208:209], v[202:203], 0, s[26:27]
	s_mov_b32 m0, s77
	ds_read_b128 v[2:5], v215 offset:49152
	ds_read_b128 v[6:9], v215 offset:50176
	ds_read_b128 v[216:219], v215 offset:51200
	ds_read_b128 v[220:223], v215 offset:52224
	ds_read_b128 v[224:227], v215 offset:53248
	ds_read_b128 v[228:231], v215 offset:54272
	ds_read_b128 v[232:235], v215 offset:55296
	ds_read_b128 v[240:243], v215 offset:56320
	ds_read_b128 v[180:183], v178
	ds_read_b128 v[184:187], v184
	global_load_lds_dwordx4 v[208:209], off
	v_lshl_add_u64 v[208:209], v[202:203], 0, s[28:29]
	s_add_i32 m0, s77, 0x2000
	s_add_i32 s77, s80, s18
	global_load_lds_dwordx4 v[208:209], off
	v_lshl_add_u64 v[208:209], v[202:203], 0, s[30:31]
	s_mov_b32 m0, s77
	v_lshl_add_u64 v[202:203], v[202:203], 0, s[34:35]
	global_load_lds_dwordx4 v[208:209], off
	s_add_i32 m0, s77, 0x2000
	s_nop 0
	global_load_lds_dwordx4 v[202:203], off
	v_lshl_add_u64 v[202:203], v[210:211], 0, s[26:27]
	s_mov_b32 m0, s10
	s_nop 0
	global_load_lds_dwordx4 v[202:203], off
	v_lshl_add_u64 v[202:203], v[210:211], 0, s[28:29]
	s_mov_b32 m0, s2
	s_nop 0
	global_load_lds_dwordx4 v[202:203], off
	s_waitcnt vmcnt(9)
	s_waitcnt lgkmcnt(0)
	s_setprio 1
	s_barrier
	v_mfma_f32_16x16x32_bf16 v[70:73], v[146:149], v[2:5], v[70:73]
	v_mfma_f32_16x16x32_bf16 v[70:73], v[150:153], v[6:9], v[70:73]
	v_mfma_f32_16x16x32_bf16 v[66:69], v[158:161], v[6:9], v[66:69]
	v_mfma_f32_16x16x32_bf16 v[66:69], v[154:157], v[2:5], v[66:69]
	v_mfma_f32_16x16x32_bf16 v[50:53], v[154:157], v[216:219], v[50:53]
	v_mfma_f32_16x16x32_bf16 v[50:53], v[158:161], v[220:223], v[50:53]
	v_mfma_f32_16x16x32_bf16 v[54:57], v[150:153], v[220:223], v[54:57]
	v_mfma_f32_16x16x32_bf16 v[54:57], v[146:149], v[216:219], v[54:57]
	s_setprio 0
	s_setprio 1
	v_mfma_f32_16x16x32_bf16 v[38:41], v[146:149], v[224:227], v[38:41]
	v_mfma_f32_16x16x32_bf16 v[38:41], v[150:153], v[228:231], v[38:41]
	v_mfma_f32_16x16x32_bf16 v[34:37], v[158:161], v[228:231], v[34:37]
	v_mfma_f32_16x16x32_bf16 v[34:37], v[154:157], v[224:227], v[34:37]
	v_mfma_f32_16x16x32_bf16 v[18:21], v[154:157], v[232:235], v[18:21]
	v_mfma_f32_16x16x32_bf16 v[18:21], v[158:161], v[240:243], v[18:21]
	v_mfma_f32_16x16x32_bf16 v[22:25], v[150:153], v[240:243], v[22:25]
	v_mfma_f32_16x16x32_bf16 v[22:25], v[146:149], v[232:235], v[22:25]
	s_setprio 0
	s_setprio 1
	v_mfma_f32_16x16x32_bf16 v[62:65], v[166:169], v[2:5], v[62:65]
	v_mfma_f32_16x16x32_bf16 v[62:65], v[170:173], v[6:9], v[62:65]
	v_mfma_f32_16x16x32_bf16 v[2:5], v[174:177], v[2:5], v[58:61]
	v_mfma_f32_16x16x32_bf16 v[58:61], v[162:165], v[6:9], v[2:5]
	v_mfma_f32_16x16x32_bf16 v[2:5], v[166:169], v[216:219], v[46:49]
	v_mfma_f32_16x16x32_bf16 v[46:49], v[170:173], v[220:223], v[2:5]
	v_mfma_f32_16x16x32_bf16 v[2:5], v[174:177], v[216:219], v[42:45]
	v_mfma_f32_16x16x32_bf16 v[42:45], v[162:165], v[220:223], v[2:5]
	s_setprio 0
	s_setprio 1
	v_mfma_f32_16x16x32_bf16 v[2:5], v[166:169], v[224:227], v[30:33]
	v_mfma_f32_16x16x32_bf16 v[30:33], v[170:173], v[228:231], v[2:5]
	v_mfma_f32_16x16x32_bf16 v[2:5], v[174:177], v[224:227], v[26:29]
	v_mfma_f32_16x16x32_bf16 v[26:29], v[162:165], v[228:231], v[2:5]
	v_mfma_f32_16x16x32_bf16 v[2:5], v[166:169], v[232:235], v[14:17]
	v_mfma_f32_16x16x32_bf16 v[14:17], v[170:173], v[240:243], v[2:5]
	v_mfma_f32_16x16x32_bf16 v[2:5], v[174:177], v[232:235], v[10:13]
	v_mfma_f32_16x16x32_bf16 v[10:13], v[162:165], v[240:243], v[2:5]
	s_setprio 0
	s_setprio 1
	s_and_b64 vcc, exec, s[52:53]
	s_cbranch_vccz .Lslv_c1
	v_mfma_f32_16x16x32_bf16 v[2:5], v[166:169], v[180:183], v[138:141]
	v_mfma_f32_16x16x32_bf16 v[6:9], v[170:173], v[184:187], v[2:5]
	v_mfma_f32_16x16x32_bf16 v[2:5], v[174:177], v[180:183], v[142:145]
	v_mfma_f32_16x16x32_bf16 v[2:5], v[162:165], v[184:187], v[2:5]
	s_branch .LBB0_597

; #define PG8_SB(B) __builtin_amdgcn_rcpf(1.f + expneg(B))
; #define PG8_SB(B) __builtin_amdgcn_rcpf(1.f + expneg(B))
; #define PG8_STAGE(bufoff, gbase, voff) do { _Pragma("unroll") for (int _i = 0; _i < 2; ++_i) \
;         __builtin_amdgcn_global_load_lds((const unsigned*)((const char*)(gbase) + (size_t)_i * qstep + (voff)[0]), (PG8_LAS unsigned*)(lds + (bufoff) + ldsw + _i * 8192), 16, 0, 0); } while (0)
; #define PG8_LDA(dst, b, h) do { _Pragma("unroll") for (int m = 0; m < 4; ++m) _Pragma("unroll") for (int k = 0; k < 2; ++k) dst[m][k] = *(const PG8_LAS bf16x8*)(lds + PG8_SA(b, h) + aoff + m * 2048 + k * 1024); } while (0)
; #define PG8_MMA(ai, bj, At, Bt) do { __builtin_amdgcn_s_setprio(1); _Pragma("unroll") for (int m = 0; m < 4; ++m) _Pragma("unroll") for (int n = 0; n < 2; ++n) _Pragma("unroll") for (int k = 0; k < 2; ++k) \
;         acc[ai][bj][m][n] = __builtin_amdgcn_mfma_f32_16x16x32_bf16(Bt[n][k], At[m][k], acc[ai][bj][m][n], 0, 0, 0); __builtin_amdgcn_s_setprio(0); } while (0)
; #define PG8_WAIT_V89() do { if constexpr (SLIVER) PG8_WAIT_V(9); else PG8_WAIT_V(8); } while (0)
; #define PG8_LDS_S(b) do { if constexpr (SLIVER) { Sf[0] = *(const PG8_LAS bf16x8*)(lds + STAGE_BYTES + (b) * 2048 + soff0); Sf[1] = *(const PG8_LAS bf16x8*)(lds + STAGE_BYTES + (b) * 2048 + (soff0 ^ 64)); } } while (0)
; #define PG8_WAIT_L(n) asm volatile("s_waitcnt lgkmcnt(" #n ")" ::: "memory")
; #define PG8_BAR __builtin_amdgcn_s_barrier()
; #define PG8_SCHED __builtin_amdgcn_sched_barrier(0)
; template <class Epi, class Sched, bool ALIGN_EPI = false, bool SP2 = false, bool SLIVER = false>
; __device__ __forceinline__ void gemm_phase(PG8_LAS unsigned char* lds, const Gemm g, const Sched& S, const Epi& E) {
;     ...
;             PG8_WAIT_V89(); PG8_WAIT_L(0); PG8_BAR; PG8_MMA(0, 0, At, B0); PG8_MMA(0, 1, At, B1); PG8_BAR; PG8_SCHED;
;             PG8_LDA(At, 0, 1); PG8_LDS_S(0); PG8_STAGE(PG8_SB(0, 0), b2, voffB); PG8_STAGE(PG8_SB(0, 1), b2 + hstep, voffB); PG8_STAGE(PG8_SA(0, 0), a2, voffA);
;             PG8_WAIT_V89(); PG8_WAIT_L(0); PG8_BAR; PG8_MMA(1, 0, At, B0); PG8_MMA(1, 1, At, B1); PG8_MMA_S(); PG8_BAR; PG8_SCHED;
.Lgup_skipw0:
	s_waitcnt lgkmcnt(0)
	s_setprio 1
	s_barrier
	v_mfma_f32_16x16x32_bf16 v[126:129], v[130:133], v[172:175], v[126:129]
	v_mfma_f32_16x16x32_bf16 v[126:129], v[138:141], v[180:183], v[126:129]
	v_mfma_f32_16x16x32_bf16 v[118:121], v[152:155], v[180:183], v[118:121]
	v_mfma_f32_16x16x32_bf16 v[118:121], v[148:151], v[172:175], v[118:121]
	v_mfma_f32_16x16x32_bf16 v[102:105], v[148:151], v[184:187], v[102:105]
	v_mfma_f32_16x16x32_bf16 v[102:105], v[152:155], v[188:191], v[102:105]
	v_mfma_f32_16x16x32_bf16 v[110:113], v[138:141], v[188:191], v[110:113]
	v_mfma_f32_16x16x32_bf16 v[110:113], v[130:133], v[184:187], v[110:113]
	s_setprio 0
	s_setprio 1
	v_mfma_f32_16x16x32_bf16 v[94:97], v[130:133], v[192:195], v[94:97]
	v_mfma_f32_16x16x32_bf16 v[94:97], v[138:141], v[196:199], v[94:97]
	v_mfma_f32_16x16x32_bf16 v[86:89], v[152:155], v[196:199], v[86:89]
	v_mfma_f32_16x16x32_bf16 v[86:89], v[148:151], v[192:195], v[86:89]
	v_mfma_f32_16x16x32_bf16 v[70:73], v[148:151], v[200:203], v[70:73]
	v_mfma_f32_16x16x32_bf16 v[70:73], v[152:155], v[210:213], v[70:73]
	v_mfma_f32_16x16x32_bf16 v[78:81], v[138:141], v[210:213], v[78:81]
	v_mfma_f32_16x16x32_bf16 v[78:81], v[130:133], v[200:203], v[78:81]
	s_setprio 0
	s_setprio 1
	v_mfma_f32_16x16x32_bf16 v[66:69], v[164:167], v[200:203], v[66:69]
	v_mfma_f32_16x16x32_bf16 v[66:69], v[168:171], v[210:213], v[66:69]
	v_mfma_f32_16x16x32_bf16 v[114:117], v[168:171], v[180:183], v[114:117]
	v_mfma_f32_16x16x32_bf16 v[114:117], v[164:167], v[172:175], v[114:117]
	v_mfma_f32_16x16x32_bf16 v[122:125], v[156:159], v[172:175], v[122:125]
	v_mfma_f32_16x16x32_bf16 v[122:125], v[160:163], v[180:183], v[122:125]
	v_mfma_f32_16x16x32_bf16 v[106:109], v[160:163], v[188:191], v[106:109]
	v_mfma_f32_16x16x32_bf16 v[106:109], v[156:159], v[184:187], v[106:109]
	s_setprio 0
	s_setprio 1
	v_mfma_f32_16x16x32_bf16 v[98:101], v[164:167], v[184:187], v[98:101]
	v_mfma_f32_16x16x32_bf16 v[98:101], v[168:171], v[188:191], v[98:101]
	v_mfma_f32_16x16x32_bf16 v[82:85], v[168:171], v[196:199], v[82:85]
	v_mfma_f32_16x16x32_bf16 v[82:85], v[164:167], v[192:195], v[82:85]
	v_mfma_f32_16x16x32_bf16 v[90:93], v[156:159], v[192:195], v[90:93]
	v_mfma_f32_16x16x32_bf16 v[90:93], v[160:163], v[196:199], v[90:93]
	v_mfma_f32_16x16x32_bf16 v[74:77], v[160:163], v[210:213], v[74:77]
	v_mfma_f32_16x16x32_bf16 v[74:77], v[156:159], v[200:203], v[74:77]
	s_barrier
	s_setprio 0
	s_mov_b64 s[46:47], s[76:77]
	s_add_i32 s76, s78, s88
	s_mov_b32 m0, s76
	ds_read_b128 v[172:175], v147 offset:16384
	ds_read_b128 v[180:183], v147 offset:17408
	ds_read_b128 v[184:187], v147 offset:18432
	ds_read_b128 v[188:191], v147 offset:19456
	ds_read_b128 v[192:195], v147 offset:20480
	ds_read_b128 v[196:199], v147 offset:21504
	ds_read_b128 v[200:203], v147 offset:22528
	ds_read_b128 v[210:213], v147 offset:23552
	global_load_lds_dwordx4 v178, s[46:47]
	s_add_i32 m0, s76, 0x2000
	s_add_i32 s76, s79, s88
	s_add_u32 s58, s46, 0x40000
	s_addc_u32 s59, s47, 0
	global_load_lds_dwordx4 v178, s[58:59]
	s_mov_b32 m0, s76
	s_nop 0
	s_add_u32 s60, s46, 0x80000
	s_addc_u32 s61, s47, 0
	global_load_lds_dwordx4 v178, s[60:61]
	s_add_i32 m0, s76, 0x2000
	s_nop 0
	s_add_u32 s36, s46, 0xc0000
	s_addc_u32 s37, s47, 0
	global_load_lds_dwordx4 v178, s[36:37]
	s_mov_b32 m0, s45
	s_nop 0
	global_load_lds_dwordx4 v134, s[80:81]
	s_mov_b32 m0, s83
	s_nop 0
	s_add_u32 s58, s80, 0x40000
	s_addc_u32 s59, s81, 0
	global_load_lds_dwordx4 v134, s[58:59]
	s_cmp_eq_u32 s69, s101
	s_cbranch_scc1 .Lgup_skipw1
	s_waitcnt vmcnt(8)
.Lgup_skipw1:
	s_waitcnt lgkmcnt(0)
	s_setprio 1
	s_barrier
	v_mfma_f32_16x16x32_bf16 v[62:65], v[130:133], v[172:175], v[62:65]
	v_mfma_f32_16x16x32_bf16 v[62:65], v[138:141], v[180:183], v[62:65]
	v_mfma_f32_16x16x32_bf16 v[54:57], v[152:155], v[180:183], v[54:57]
	v_mfma_f32_16x16x32_bf16 v[54:57], v[148:151], v[172:175], v[54:57]
	v_mfma_f32_16x16x32_bf16 v[38:41], v[148:151], v[184:187], v[38:41]
	v_mfma_f32_16x16x32_bf16 v[38:41], v[152:155], v[188:191], v[38:41]
	v_mfma_f32_16x16x32_bf16 v[46:49], v[138:141], v[188:191], v[46:49]
	v_mfma_f32_16x16x32_bf16 v[46:49], v[130:133], v[184:187], v[46:49]
	s_setprio 0
	s_setprio 1
	v_mfma_f32_16x16x32_bf16 v[30:33], v[130:133], v[192:195], v[30:33]
	v_mfma_f32_16x16x32_bf16 v[30:33], v[138:141], v[196:199], v[30:33]
	v_mfma_f32_16x16x32_bf16 v[22:25], v[152:155], v[196:199], v[22:25]
	v_mfma_f32_16x16x32_bf16 v[22:25], v[148:151], v[192:195], v[22:25]
	v_mfma_f32_16x16x32_bf16 v[6:9], v[148:151], v[200:203], v[6:9]
	v_mfma_f32_16x16x32_bf16 v[6:9], v[152:155], v[210:213], v[6:9]
	v_mfma_f32_16x16x32_bf16 v[14:17], v[138:141], v[210:213], v[14:17]
	v_mfma_f32_16x16x32_bf16 v[14:17], v[130:133], v[200:203], v[14:17]
	s_setprio 0
	s_setprio 1
	v_mfma_f32_16x16x32_bf16 v[2:5], v[164:167], v[200:203], v[2:5]
	v_mfma_f32_16x16x32_bf16 v[2:5], v[168:171], v[210:213], v[2:5]
	v_mfma_f32_16x16x32_bf16 v[50:53], v[168:171], v[180:183], v[50:53]
	v_mfma_f32_16x16x32_bf16 v[50:53], v[164:167], v[172:175], v[50:53]
	v_mfma_f32_16x16x32_bf16 v[58:61], v[156:159], v[172:175], v[58:61]
	v_mfma_f32_16x16x32_bf16 v[58:61], v[160:163], v[180:183], v[58:61]
	v_mfma_f32_16x16x32_bf16 v[42:45], v[160:163], v[188:191], v[42:45]
	v_mfma_f32_16x16x32_bf16 v[42:45], v[156:159], v[184:187], v[42:45]
	s_setprio 0
	s_setprio 1
	v_mfma_f32_16x16x32_bf16 v[34:37], v[164:167], v[184:187], v[34:37]
	v_mfma_f32_16x16x32_bf16 v[34:37], v[168:171], v[188:191], v[34:37]
	v_mfma_f32_16x16x32_bf16 v[18:21], v[168:171], v[196:199], v[18:21]
	v_mfma_f32_16x16x32_bf16 v[18:21], v[164:167], v[192:195], v[18:21]
	v_mfma_f32_16x16x32_bf16 v[26:29], v[156:159], v[192:195], v[26:29]
	v_mfma_f32_16x16x32_bf16 v[26:29], v[160:163], v[196:199], v[26:29]
	v_mfma_f32_16x16x32_bf16 v[10:13], v[160:163], v[210:213], v[10:13]
	v_mfma_f32_16x16x32_bf16 v[10:13], v[156:159], v[200:203], v[10:13]
	s_barrier
; #define PG8_STAGE(bufoff, gbase, voff) do { _Pragma("unroll") for (int _i = 0; _i < 2; ++_i) \
;         __builtin_amdgcn_global_load_lds((const unsigned*)((const char*)(gbase) + (size_t)_i * qstep + (voff)[0]), (PG8_LAS unsigned*)(lds + (bufoff) + ldsw + _i * 8192), 16, 0, 0); } while (0)
; #define PG8_LDA(dst, b, h) do { _Pragma("unroll") for (int m = 0; m < 4; ++m) _Pragma("unroll") for (int k = 0; k < 2; ++k) dst[m][k] = *(const PG8_LAS bf16x8*)(lds + PG8_SA(b, h) + aoff + m * 2048 + k * 1024); } while (0)
; #define PG8_LDB(dst, b, h) do { _Pragma("unroll") for (int n = 0; n < 2; ++n) _Pragma("unroll") for (int k = 0; k < 2; ++k) dst[n][k] = *(const PG8_LAS bf16x8*)(lds + PG8_SB(b, h) + boff + n * 2048 + k * 1024); } while (0)
; #define PG8_MMA(ai, bj, At, Bt) do { __builtin_amdgcn_s_setprio(1); _Pragma("unroll") for (int m = 0; m < 4; ++m) _Pragma("unroll") for (int n = 0; n < 2; ++n) _Pragma("unroll") for (int k = 0; k < 2; ++k) \
;         acc[ai][bj][m][n] = __builtin_amdgcn_mfma_f32_16x16x32_bf16(Bt[n][k], At[m][k], acc[ai][bj][m][n], 0, 0, 0); __builtin_amdgcn_s_setprio(0); } while (0)
; #define PG8_WAIT_V89() do { if constexpr (SLIVER) PG8_WAIT_V(9); else PG8_WAIT_V(8); } while (0)
; #define PG8_STAGE_S(b, gbase) do { if constexpr (SLIVER) __builtin_amdgcn_global_load_lds((const unsigned*)((const char*)(gbase) + voffS), (PG8_LAS unsigned*)(lds + STAGE_BYTES + (b) * 2048 + wid * 256), 4, 0, 0); } while (0)
; #define PG8_WAIT_L(n) asm volatile("s_waitcnt lgkmcnt(" #n ")" ::: "memory")
; #define PG8_BAR __builtin_amdgcn_s_barrier()
; #define PG8_SCHED __builtin_amdgcn_sched_barrier(0)
; template <class Epi, class Sched, bool ALIGN_EPI = false, bool SP2 = false, bool SLIVER = false>
; __device__ __forceinline__ void gemm_phase(PG8_LAS unsigned char* lds, const Gemm g, const Sched& S, const Epi& E) {
;     ...
;             PG8_LDB(B0, 1, 0); PG8_LDB(B1, 1, 1); PG8_SCHED; PG8_LDA(At, 1, 0); PG8_STAGE(PG8_SA(0, 1), a2 + hstep, voffA); PG8_STAGE_S(0, s2);
;             PG8_WAIT_V89(); PG8_WAIT_L(0); PG8_BAR; PG8_MMA(0, 0, At, B0); PG8_MMA(0, 1, At, B1); PG8_BAR; PG8_SCHED;
	s_setprio 0
	s_add_i32 s76, 0, 0x18000
	v_add_u32_e32 v142, s76, v143
	s_add_i32 s77, 0, 0x1c000
	ds_read_b128 v[130:133], v142
	ds_read_b128 v[138:141], v142 offset:1024
	ds_read_b128 v[148:151], v142 offset:2048
	ds_read_b128 v[152:155], v142 offset:3072
	v_add_u32_e32 v142, s77, v143
	ds_read_b128 v[156:159], v142
	ds_read_b128 v[160:163], v142 offset:1024
	ds_read_b128 v[164:167], v142 offset:2048
	ds_read_b128 v[168:171], v142 offset:3072
	s_mov_b32 m0, s90
	ds_read_b128 v[172:175], v147 offset:32768
	ds_read_b128 v[180:183], v147 offset:33792
	ds_read_b128 v[184:187], v147 offset:34816
	ds_read_b128 v[188:191], v147 offset:35840
	ds_read_b128 v[192:195], v147 offset:36864
	ds_read_b128 v[196:199], v147 offset:37888
	ds_read_b128 v[200:203], v147 offset:38912
	ds_read_b128 v[210:213], v147 offset:39936
	s_add_u32 s60, s80, 0x80000
	s_addc_u32 s61, s81, 0
	global_load_lds_dwordx4 v134, s[60:61]
	s_mov_b32 m0, s91
	s_nop 0
	s_add_u32 s36, s80, 0xc0000
	s_addc_u32 s37, s81, 0
	global_load_lds_dwordx4 v134, s[36:37]
	s_waitcnt vmcnt(8)
	s_waitcnt lgkmcnt(0)
	s_setprio 1
	s_barrier
	v_mfma_f32_16x16x32_bf16 v[126:129], v[130:133], v[172:175], v[126:129]
	v_mfma_f32_16x16x32_bf16 v[126:129], v[138:141], v[180:183], v[126:129]
	v_mfma_f32_16x16x32_bf16 v[118:121], v[152:155], v[180:183], v[118:121]
	v_mfma_f32_16x16x32_bf16 v[118:121], v[148:151], v[172:175], v[118:121]
	v_mfma_f32_16x16x32_bf16 v[102:105], v[148:151], v[184:187], v[102:105]
	v_mfma_f32_16x16x32_bf16 v[102:105], v[152:155], v[188:191], v[102:105]
	v_mfma_f32_16x16x32_bf16 v[110:113], v[138:141], v[188:191], v[110:113]
	v_mfma_f32_16x16x32_bf16 v[110:113], v[130:133], v[184:187], v[110:113]
	s_setprio 0
	s_setprio 1
	v_mfma_f32_16x16x32_bf16 v[94:97], v[130:133], v[192:195], v[94:97]
	v_mfma_f32_16x16x32_bf16 v[94:97], v[138:141], v[196:199], v[94:97]
	v_mfma_f32_16x16x32_bf16 v[86:89], v[152:155], v[196:199], v[86:89]
	v_mfma_f32_16x16x32_bf16 v[86:89], v[148:151], v[192:195], v[86:89]
	v_mfma_f32_16x16x32_bf16 v[70:73], v[148:151], v[200:203], v[70:73]
	v_mfma_f32_16x16x32_bf16 v[70:73], v[152:155], v[210:213], v[70:73]
	v_mfma_f32_16x16x32_bf16 v[78:81], v[138:141], v[210:213], v[78:81]
	v_mfma_f32_16x16x32_bf16 v[78:81], v[130:133], v[200:203], v[78:81]
	s_setprio 0
	s_setprio 1
	v_mfma_f32_16x16x32_bf16 v[66:69], v[164:167], v[200:203], v[66:69]
	v_mfma_f32_16x16x32_bf16 v[66:69], v[168:171], v[210:213], v[66:69]
	v_mfma_f32_16x16x32_bf16 v[114:117], v[168:171], v[180:183], v[114:117]
	v_mfma_f32_16x16x32_bf16 v[114:117], v[164:167], v[172:175], v[114:117]
	v_mfma_f32_16x16x32_bf16 v[122:125], v[156:159], v[172:175], v[122:125]
	v_mfma_f32_16x16x32_bf16 v[122:125], v[160:163], v[180:183], v[122:125]
	v_mfma_f32_16x16x32_bf16 v[106:109], v[160:163], v[188:191], v[106:109]
	v_mfma_f32_16x16x32_bf16 v[106:109], v[156:159], v[184:187], v[106:109]
	s_setprio 0
	s_setprio 1
	v_mfma_f32_16x16x32_bf16 v[98:101], v[164:167], v[184:187], v[98:101]
	v_mfma_f32_16x16x32_bf16 v[98:101], v[168:171], v[188:191], v[98:101]
	v_mfma_f32_16x16x32_bf16 v[82:85], v[168:171], v[196:199], v[82:85]
	v_mfma_f32_16x16x32_bf16 v[82:85], v[164:167], v[192:195], v[82:85]
	v_mfma_f32_16x16x32_bf16 v[90:93], v[156:159], v[192:195], v[90:93]
	v_mfma_f32_16x16x32_bf16 v[90:93], v[160:163], v[196:199], v[90:93]
	v_mfma_f32_16x16x32_bf16 v[74:77], v[160:163], v[210:213], v[74:77]
	v_mfma_f32_16x16x32_bf16 v[74:77], v[156:159], v[200:203], v[74:77]
	s_barrier
; #define PG8_SB(B) __builtin_amdgcn_rcpf(1.f + expneg(B))
; #define PG8_SB(B) __builtin_amdgcn_rcpf(1.f + expneg(B))
; #define PG8_STAGE(bufoff, gbase, voff) do { _Pragma("unroll") for (int _i = 0; _i < 2; ++_i) \
;         __builtin_amdgcn_global_load_lds((const unsigned*)((const char*)(gbase) + (size_t)_i * qstep + (voff)[0]), (PG8_LAS unsigned*)(lds + (bufoff) + ldsw + _i * 8192), 16, 0, 0); } while (0)
; #define PG8_LDA(dst, b, h) do { _Pragma("unroll") for (int m = 0; m < 4; ++m) _Pragma("unroll") for (int k = 0; k < 2; ++k) dst[m][k] = *(const PG8_LAS bf16x8*)(lds + PG8_SA(b, h) + aoff + m * 2048 + k * 1024); } while (0)
; #define PG8_MMA(ai, bj, At, Bt) do { __builtin_amdgcn_s_setprio(1); _Pragma("unroll") for (int m = 0; m < 4; ++m) _Pragma("unroll") for (int n = 0; n < 2; ++n) _Pragma("unroll") for (int k = 0; k < 2; ++k) \
;         acc[ai][bj][m][n] = __builtin_amdgcn_mfma_f32_16x16x32_bf16(Bt[n][k], At[m][k], acc[ai][bj][m][n], 0, 0, 0); __builtin_amdgcn_s_setprio(0); } while (0)
; #define PG8_WAIT_V89() do { if constexpr (SLIVER) PG8_WAIT_V(9); else PG8_WAIT_V(8); } while (0)
; #define PG8_LDS_S(b) do { if constexpr (SLIVER) { Sf[0] = *(const PG8_LAS bf16x8*)(lds + STAGE_BYTES + (b) * 2048 + soff0); Sf[1] = *(const PG8_LAS bf16x8*)(lds + STAGE_BYTES + (b) * 2048 + (soff0 ^ 64)); } } while (0)
; #define PG8_WAIT_L(n) asm volatile("s_waitcnt lgkmcnt(" #n ")" ::: "memory")
; #define PG8_BAR __builtin_amdgcn_s_barrier()
; #define PG8_SCHED __builtin_amdgcn_sched_barrier(0)
; template <class Epi, class Sched, bool ALIGN_EPI = false, bool SP2 = false, bool SLIVER = false>
; __device__ __forceinline__ void gemm_phase(PG8_LAS unsigned char* lds, const Gemm g, const Sched& S, const Epi& E) {
;     ...
;             PG8_LDA(At, 1, 1); PG8_LDS_S(1); PG8_STAGE(PG8_SB(1, 0), b3, voffB); PG8_STAGE(PG8_SB(1, 1), b3 + hstep, voffB); PG8_STAGE(PG8_SA(1, 0), a3, voffA);
;             PG8_WAIT_V89(); PG8_WAIT_L(0); PG8_BAR; PG8_MMA(1, 0, At, B0); PG8_MMA(1, 1, At, B1); PG8_MMA_S(); PG8_BAR; PG8_SCHED;
	s_setprio 0
	s_add_i32 s76, s76, s88
	s_mov_b32 m0, s76
	ds_read_b128 v[172:175], v147 offset:49152
	ds_read_b128 v[180:183], v147 offset:50176
	ds_read_b128 v[184:187], v147 offset:51200
	ds_read_b128 v[188:191], v147 offset:52224
	ds_read_b128 v[192:195], v147 offset:53248
	ds_read_b128 v[196:199], v147 offset:54272
	ds_read_b128 v[200:203], v147 offset:55296
	ds_read_b128 v[210:213], v147 offset:56320
	s_add_u32 s58, s46, 0x80
	s_addc_u32 s59, s47, 0
	global_load_lds_dwordx4 v178, s[58:59]
	s_add_i32 m0, s76, 0x2000
	s_add_i32 s76, s77, s88
	s_add_u32 s60, s46, 0x40080
	s_addc_u32 s61, s47, 0
	global_load_lds_dwordx4 v178, s[60:61]
	s_mov_b32 m0, s76
	s_add_u32 s36, s46, 0x80080
	s_addc_u32 s37, s47, 0
	global_load_lds_dwordx4 v178, s[36:37]
	s_add_i32 m0, s76, 0x2000
	s_nop 0
	s_add_u32 s58, s46, 0xc0080
	s_addc_u32 s59, s47, 0
	global_load_lds_dwordx4 v178, s[58:59]
	s_mov_b32 m0, s93
	s_nop 0
	s_add_u32 s60, s80, 0x80
	s_addc_u32 s61, s81, 0
	global_load_lds_dwordx4 v134, s[60:61]
	s_mov_b32 m0, s94
	s_nop 0
	s_add_u32 s36, s80, 0x40080
	s_addc_u32 s37, s81, 0
	global_load_lds_dwordx4 v134, s[36:37]
	s_waitcnt vmcnt(8)
	s_waitcnt lgkmcnt(0)
	s_setprio 1
	s_barrier
	v_mfma_f32_16x16x32_bf16 v[62:65], v[130:133], v[172:175], v[62:65]
	v_mfma_f32_16x16x32_bf16 v[62:65], v[138:141], v[180:183], v[62:65]
	v_mfma_f32_16x16x32_bf16 v[54:57], v[152:155], v[180:183], v[54:57]
	v_mfma_f32_16x16x32_bf16 v[54:57], v[148:151], v[172:175], v[54:57]
	v_mfma_f32_16x16x32_bf16 v[38:41], v[148:151], v[184:187], v[38:41]
	v_mfma_f32_16x16x32_bf16 v[38:41], v[152:155], v[188:191], v[38:41]
	v_mfma_f32_16x16x32_bf16 v[46:49], v[138:141], v[188:191], v[46:49]
	v_mfma_f32_16x16x32_bf16 v[46:49], v[130:133], v[184:187], v[46:49]
	s_setprio 0
	s_setprio 1
	v_mfma_f32_16x16x32_bf16 v[30:33], v[130:133], v[192:195], v[30:33]
	v_mfma_f32_16x16x32_bf16 v[30:33], v[138:141], v[196:199], v[30:33]
	v_mfma_f32_16x16x32_bf16 v[22:25], v[152:155], v[196:199], v[22:25]
	v_mfma_f32_16x16x32_bf16 v[22:25], v[148:151], v[192:195], v[22:25]
	v_mfma_f32_16x16x32_bf16 v[6:9], v[148:151], v[200:203], v[6:9]
	v_mfma_f32_16x16x32_bf16 v[6:9], v[152:155], v[210:213], v[6:9]
	v_mfma_f32_16x16x32_bf16 v[14:17], v[138:141], v[210:213], v[14:17]
	v_mfma_f32_16x16x32_bf16 v[14:17], v[130:133], v[200:203], v[14:17]
	s_setprio 0
	s_setprio 1
	v_mfma_f32_16x16x32_bf16 v[2:5], v[164:167], v[200:203], v[2:5]
	v_mfma_f32_16x16x32_bf16 v[2:5], v[168:171], v[210:213], v[2:5]
	v_mfma_f32_16x16x32_bf16 v[50:53], v[168:171], v[180:183], v[50:53]
	v_mfma_f32_16x16x32_bf16 v[50:53], v[164:167], v[172:175], v[50:53]
	v_mfma_f32_16x16x32_bf16 v[58:61], v[156:159], v[172:175], v[58:61]
	v_mfma_f32_16x16x32_bf16 v[58:61], v[160:163], v[180:183], v[58:61]
	v_mfma_f32_16x16x32_bf16 v[42:45], v[160:163], v[188:191], v[42:45]
	v_mfma_f32_16x16x32_bf16 v[42:45], v[156:159], v[184:187], v[42:45]
	s_setprio 0
	s_setprio 1
	v_mfma_f32_16x16x32_bf16 v[34:37], v[164:167], v[184:187], v[34:37]
	v_mfma_f32_16x16x32_bf16 v[34:37], v[168:171], v[188:191], v[34:37]
	v_mfma_f32_16x16x32_bf16 v[18:21], v[168:171], v[196:199], v[18:21]
	v_mfma_f32_16x16x32_bf16 v[18:21], v[164:167], v[192:195], v[18:21]
	v_mfma_f32_16x16x32_bf16 v[26:29], v[156:159], v[192:195], v[26:29]
	v_mfma_f32_16x16x32_bf16 v[26:29], v[160:163], v[196:199], v[26:29]
	v_mfma_f32_16x16x32_bf16 v[10:13], v[160:163], v[210:213], v[10:13]
	v_mfma_f32_16x16x32_bf16 v[10:13], v[156:159], v[200:203], v[10:13]
	s_barrier
	s_setprio 0
	s_add_i32 s69, s69, 2
	s_add_u32 s62, s62, 0x100
	s_addc_u32 s63, s63, 0
	s_add_u32 s67, s67, 0x100
	s_addc_u32 s68, s68, 0
	s_cmp_gt_u32 s69, 29
	s_cbranch_scc0 .LBB0_705
	s_and_b64 vcc, exec, s[42:43]
	s_cbranch_vccz .LBB0_708
	s_barrier

; #define PG8_STAGE(bufoff, gbase, voff) do { _Pragma("unroll") for (int _i = 0; _i < 2; ++_i) \
;         __builtin_amdgcn_global_load_lds((const unsigned*)((const char*)(gbase) + (size_t)_i * qstep + (voff)[0]), (PG8_LAS unsigned*)(lds + (bufoff) + ldsw + _i * 8192), 16, 0, 0); } while (0)
; #define PG8_LDA(dst, b, h) do { _Pragma("unroll") for (int m = 0; m < 4; ++m) _Pragma("unroll") for (int k = 0; k < 2; ++k) dst[m][k] = *(const PG8_LAS bf16x8*)(lds + PG8_SA(b, h) + aoff + m * 2048 + k * 1024); } while (0)
; #define PG8_LDB(dst, b, h) do { _Pragma("unroll") for (int n = 0; n < 2; ++n) _Pragma("unroll") for (int k = 0; k < 2; ++k) dst[n][k] = *(const PG8_LAS bf16x8*)(lds + PG8_SB(b, h) + boff + n * 2048 + k * 1024); } while (0)
; #define PG8_MMA(ai, bj, At, Bt) do { __builtin_amdgcn_s_setprio(1); _Pragma("unroll") for (int m = 0; m < 4; ++m) _Pragma("unroll") for (int n = 0; n < 2; ++n) _Pragma("unroll") for (int k = 0; k < 2; ++k) \
;         acc[ai][bj][m][n] = __builtin_amdgcn_mfma_f32_16x16x32_bf16(Bt[n][k], At[m][k], acc[ai][bj][m][n], 0, 0, 0); __builtin_amdgcn_s_setprio(0); } while (0)
; #define PG8_WAIT_V89() do { if constexpr (SLIVER) PG8_WAIT_V(9); else PG8_WAIT_V(8); } while (0)
; #define PG8_WAIT_L(n) asm volatile("s_waitcnt lgkmcnt(" #n ")" ::: "memory")
; #define PG8_BAR __builtin_amdgcn_s_barrier()
; #define PG8_SCHED __builtin_amdgcn_sched_barrier(0)
; template <class Epi, class Sched, bool ALIGN_EPI = false, bool SP2 = false, bool SLIVER = false>
; __device__ __forceinline__ void gemm_phase(PG8_LAS unsigned char* lds, const Gemm g, const Sched& S, const Epi& E) {
;     ...
;             const bool last = (t == nt - 2);
;             const char* a1 = cA + (size_t)(t + 1) * kstep;
;             const char* a2 = last ? nA : cA + (size_t)(t + 2) * kstep; const char* b2 = last ? nB : cB + (size_t)(t + 2) * kstep;
;             const char* a3 = a2 + kstep; const char* b3 = b2 + kstep;
;             const char* s1 = cS + (size_t)(t + 1) * kstep; const char* s2 = last ? nS : cS + (size_t)(t + 2) * kstep;
;             if (last && has_next) S.a_ready(nxt);
;             if constexpr (SP2) {
;             PG8_LDB(B0, 0, 0); PG8_LDB(B1, 0, 1); PG8_SCHED; PG8_LDA(At, 0, 0); PG8_STAGE(PG8_SA(1, 1), a1 + hstep, voffA); PG8_STAGE_S(1, s1);
;             PG8_WAIT_V89(); PG8_WAIT_L(0); PG8_BAR; PG8_MMA(0, 0, At, B0); PG8_MMA(0, 1, At, B1); PG8_BAR; PG8_SCHED;
.LBB0_811:
	s_add_u32 s13, s90, s62
	s_addc_u32 s40, s91, s63
	s_add_u32 s13, s13, 0x100
	s_addc_u32 s66, s40, 0
	s_add_u32 s68, s2, s62
	s_addc_u32 s67, s3, s63
	s_add_i32 s69, 0, 0x10000
	s_cmpk_eq_i32 s62, 0x2b00
	s_cselect_b64 s[80:81], -1, 0
	s_and_b64 s[40:41], s[80:81], exec
	s_cselect_b32 s41, s85, s66
	s_cselect_b32 s40, s84, s13
	v_add_u32_e32 v66, s69, v220
	s_cselect_b32 s67, s87, s67
	s_cselect_b32 s66, s86, s68
	s_add_i32 s13, 0, 0x14000
	ds_read_b128 v[154:157], v66
	ds_read_b128 v[158:161], v66 offset:1024
	ds_read_b128 v[162:165], v66 offset:2048
	ds_read_b128 v[174:177], v66 offset:3072
	v_add_u32_e32 v66, s13, v220
	ds_read_b128 v[184:187], v66
	ds_read_b128 v[188:191], v66 offset:1024
	ds_read_b128 v[192:195], v66 offset:2048
	ds_read_b128 v[180:183], v66 offset:3072
	v_lshl_add_u64 v[146:147], v[214:215], 0, s[62:63]
	v_lshl_add_u64 v[148:149], v[146:147], 0, s[8:9]
	s_add_i32 m0, s19, 0xc000
	s_mov_b64 s[94:95], 0x210080
	ds_read_b128 v[66:69], v223
	ds_read_b128 v[70:73], v223 offset:1024
	ds_read_b128 v[74:77], v223 offset:2048
	ds_read_b128 v[78:81], v223 offset:3072
	ds_read_b128 v[216:219], v223 offset:4096
	ds_read_b128 v[224:227], v223 offset:5120
	ds_read_b128 v[228:231], v223 offset:6144
	ds_read_b128 v[232:235], v223 offset:7168
	global_load_lds_dwordx4 v[148:149], off
	v_lshl_add_u64 v[146:147], v[146:147], 0, s[94:95]
	s_add_i32 m0, s19, 0xe000
	s_nop 0
	global_load_lds_dwordx4 v[146:147], off
	v_lshl_add_u64 v[146:147], v[212:213], 0, s[62:63]
	s_add_i32 m0, s96, 0x20800
	s_nop 0
	global_load_lds_dword v[146:147], off
	s_waitcnt vmcnt(9)
	s_waitcnt lgkmcnt(0)
	s_setprio 1
	s_barrier
	v_mfma_f32_16x16x32_bf16 v[146:149], v[154:157], v[66:69], v[170:173]
	v_mfma_f32_16x16x32_bf16 v[146:149], v[158:161], v[70:73], v[146:149]
	v_mfma_f32_16x16x32_bf16 v[150:153], v[162:165], v[66:69], v[166:169]
	v_mfma_f32_16x16x32_bf16 v[150:153], v[174:177], v[70:73], v[150:153]
	v_mfma_f32_16x16x32_bf16 v[134:137], v[154:157], v[74:77], v[134:137]
	v_mfma_f32_16x16x32_bf16 v[134:137], v[158:161], v[78:81], v[134:137]
	v_mfma_f32_16x16x32_bf16 v[130:133], v[162:165], v[74:77], v[130:133]
	v_mfma_f32_16x16x32_bf16 v[130:133], v[174:177], v[78:81], v[130:133]
	s_setprio 0
	s_setprio 1
	v_mfma_f32_16x16x32_bf16 v[118:121], v[154:157], v[216:219], v[118:121]
	v_mfma_f32_16x16x32_bf16 v[118:121], v[158:161], v[224:227], v[118:121]
	v_mfma_f32_16x16x32_bf16 v[114:117], v[162:165], v[216:219], v[114:117]
	v_mfma_f32_16x16x32_bf16 v[114:117], v[174:177], v[224:227], v[114:117]
	v_mfma_f32_16x16x32_bf16 v[102:105], v[154:157], v[228:231], v[102:105]
	v_mfma_f32_16x16x32_bf16 v[102:105], v[158:161], v[232:235], v[102:105]
	v_mfma_f32_16x16x32_bf16 v[98:101], v[162:165], v[228:231], v[98:101]
	v_mfma_f32_16x16x32_bf16 v[98:101], v[174:177], v[232:235], v[98:101]
	s_setprio 0
	s_setprio 1
	v_mfma_f32_16x16x32_bf16 v[142:145], v[184:187], v[66:69], v[142:145]
	v_mfma_f32_16x16x32_bf16 v[142:145], v[188:191], v[70:73], v[142:145]
	v_mfma_f32_16x16x32_bf16 v[66:69], v[192:195], v[66:69], v[138:141]
	v_mfma_f32_16x16x32_bf16 v[138:141], v[180:183], v[70:73], v[66:69]
	v_mfma_f32_16x16x32_bf16 v[66:69], v[184:187], v[74:77], v[126:129]
	v_mfma_f32_16x16x32_bf16 v[126:129], v[188:191], v[78:81], v[66:69]
	v_mfma_f32_16x16x32_bf16 v[66:69], v[192:195], v[74:77], v[122:125]
	v_mfma_f32_16x16x32_bf16 v[122:125], v[180:183], v[78:81], v[66:69]
	s_setprio 0
	s_setprio 1
	v_mfma_f32_16x16x32_bf16 v[66:69], v[184:187], v[216:219], v[110:113]
	v_mfma_f32_16x16x32_bf16 v[110:113], v[188:191], v[224:227], v[66:69]
	v_mfma_f32_16x16x32_bf16 v[66:69], v[192:195], v[216:219], v[106:109]
	v_mfma_f32_16x16x32_bf16 v[106:109], v[180:183], v[224:227], v[66:69]
	v_mfma_f32_16x16x32_bf16 v[66:69], v[184:187], v[228:231], v[94:97]
	v_mfma_f32_16x16x32_bf16 v[94:97], v[188:191], v[232:235], v[66:69]
	v_mfma_f32_16x16x32_bf16 v[66:69], v[192:195], v[228:231], v[90:93]
	v_mfma_f32_16x16x32_bf16 v[90:93], v[180:183], v[232:235], v[66:69]
	s_barrier
; #define PG8_SB(B) __builtin_amdgcn_rcpf(1.f + expneg(B))
; #define PG8_SB(B) __builtin_amdgcn_rcpf(1.f + expneg(B))
; #define PG8_STAGE(bufoff, gbase, voff) do { _Pragma("unroll") for (int _i = 0; _i < 2; ++_i) \
;         __builtin_amdgcn_global_load_lds((const unsigned*)((const char*)(gbase) + (size_t)_i * qstep + (voff)[0]), (PG8_LAS unsigned*)(lds + (bufoff) + ldsw + _i * 8192), 16, 0, 0); } while (0)
; #define PG8_LDA(dst, b, h) do { _Pragma("unroll") for (int m = 0; m < 4; ++m) _Pragma("unroll") for (int k = 0; k < 2; ++k) dst[m][k] = *(const PG8_LAS bf16x8*)(lds + PG8_SA(b, h) + aoff + m * 2048 + k * 1024); } while (0)
; #define PG8_MMA(ai, bj, At, Bt) do { __builtin_amdgcn_s_setprio(1); _Pragma("unroll") for (int m = 0; m < 4; ++m) _Pragma("unroll") for (int n = 0; n < 2; ++n) _Pragma("unroll") for (int k = 0; k < 2; ++k) \
;         acc[ai][bj][m][n] = __builtin_amdgcn_mfma_f32_16x16x32_bf16(Bt[n][k], At[m][k], acc[ai][bj][m][n], 0, 0, 0); __builtin_amdgcn_s_setprio(0); } while (0)
; #define PG8_WAIT_V89() do { if constexpr (SLIVER) PG8_WAIT_V(9); else PG8_WAIT_V(8); } while (0)
; #define PG8_LDS_S(b) do { if constexpr (SLIVER) { Sf[0] = *(const PG8_LAS bf16x8*)(lds + STAGE_BYTES + (b) * 2048 + soff0); Sf[1] = *(const PG8_LAS bf16x8*)(lds + STAGE_BYTES + (b) * 2048 + (soff0 ^ 64)); } } while (0)
; #define PG8_WAIT_L(n) asm volatile("s_waitcnt lgkmcnt(" #n ")" ::: "memory")
; #define PG8_BAR __builtin_amdgcn_s_barrier()
; #define PG8_SCHED __builtin_amdgcn_sched_barrier(0)
; template <class Epi, class Sched, bool ALIGN_EPI = false, bool SP2 = false, bool SLIVER = false>
; __device__ __forceinline__ void gemm_phase(PG8_LAS unsigned char* lds, const Gemm g, const Sched& S, const Epi& E) {
;     ...
;             PG8_LDA(At, 0, 1); PG8_LDS_S(0); PG8_STAGE(PG8_SB(0, 0), b2, voffB); PG8_STAGE(PG8_SB(0, 1), b2 + hstep, voffB); PG8_STAGE(PG8_SA(0, 0), a2, voffA);
;             PG8_WAIT_V89(); PG8_WAIT_L(0); PG8_BAR; PG8_MMA(1, 0, At, B0); PG8_MMA(1, 1, At, B1); PG8_MMA_S(); PG8_BAR; PG8_SCHED;
	s_setprio 0
	s_add_i32 s68, 0, 0x20000
	v_lshl_add_u64 v[216:217], s[66:67], 0, v[198:199]
	s_add_i32 s66, s69, s18
	v_add_u32_e32 v74, s68, v221
	v_add_u32_e32 v75, s68, v222
	s_mov_b32 m0, s66
	ds_read_b128 v[66:69], v223 offset:16384
	ds_read_b128 v[70:73], v223 offset:17408
	ds_read_b128 v[224:227], v223 offset:18432
	ds_read_b128 v[228:231], v223 offset:19456
	ds_read_b128 v[232:235], v223 offset:20480
	ds_read_b128 v[240:243], v223 offset:21504
	ds_read_b128 v[244:247], v223 offset:22528
	ds_read_b128 v[248:251], v223 offset:23552
	ds_read_b128 v[166:169], v74
	ds_read_b128 v[170:173], v75
	global_load_lds_dwordx4 v[216:217], off
	v_lshl_add_u64 v[74:75], v[216:217], 0, s[64:65]
	s_add_i32 m0, s66, 0x2000
	s_add_i32 s13, s13, s18
	global_load_lds_dwordx4 v[74:75], off
	v_lshl_add_u64 v[74:75], v[216:217], 0, s[0:1]
	s_mov_b32 m0, s13
	v_lshl_add_u64 v[218:219], s[40:41], 0, v[196:197]
	global_load_lds_dwordx4 v[74:75], off
	v_lshl_add_u64 v[74:75], v[216:217], 0, s[74:75]
	s_add_i32 m0, s13, 0x2000
	s_nop 0
	global_load_lds_dwordx4 v[74:75], off
	s_mov_b32 m0, s19
	v_lshl_add_u64 v[74:75], v[218:219], 0, s[64:65]
	global_load_lds_dwordx4 v[218:219], off
	s_mov_b32 m0, s52
	s_nop 0
	global_load_lds_dwordx4 v[74:75], off
	s_waitcnt vmcnt(9)
	s_waitcnt lgkmcnt(0)
	s_setprio 1
	s_barrier
	v_mfma_f32_16x16x32_bf16 v[74:77], v[154:157], v[66:69], v[86:89]
	v_mfma_f32_16x16x32_bf16 v[74:77], v[158:161], v[70:73], v[74:77]
	v_mfma_f32_16x16x32_bf16 v[78:81], v[162:165], v[66:69], v[82:85]
	v_mfma_f32_16x16x32_bf16 v[78:81], v[174:177], v[70:73], v[78:81]
	v_mfma_f32_16x16x32_bf16 v[54:57], v[154:157], v[224:227], v[54:57]
	v_mfma_f32_16x16x32_bf16 v[54:57], v[158:161], v[228:231], v[54:57]
	v_mfma_f32_16x16x32_bf16 v[50:53], v[162:165], v[224:227], v[50:53]
	v_mfma_f32_16x16x32_bf16 v[50:53], v[174:177], v[228:231], v[50:53]
	s_setprio 0
	s_setprio 1
	v_mfma_f32_16x16x32_bf16 v[38:41], v[154:157], v[232:235], v[38:41]
	v_mfma_f32_16x16x32_bf16 v[38:41], v[158:161], v[240:243], v[38:41]
	v_mfma_f32_16x16x32_bf16 v[34:37], v[162:165], v[232:235], v[34:37]
	v_mfma_f32_16x16x32_bf16 v[34:37], v[174:177], v[240:243], v[34:37]
	v_mfma_f32_16x16x32_bf16 v[22:25], v[154:157], v[244:247], v[22:25]
	v_mfma_f32_16x16x32_bf16 v[22:25], v[158:161], v[248:251], v[22:25]
	v_mfma_f32_16x16x32_bf16 v[18:21], v[162:165], v[244:247], v[18:21]
	v_mfma_f32_16x16x32_bf16 v[18:21], v[174:177], v[248:251], v[18:21]
	s_setprio 0
	s_setprio 1
	v_mfma_f32_16x16x32_bf16 v[10:13], v[180:183], v[248:251], v[10:13]
	v_mfma_f32_16x16x32_bf16 v[10:13], v[192:195], v[244:247], v[10:13]
	v_mfma_f32_16x16x32_bf16 v[58:61], v[192:195], v[66:69], v[58:61]
	v_mfma_f32_16x16x32_bf16 v[58:61], v[180:183], v[70:73], v[58:61]
	v_mfma_f32_16x16x32_bf16 v[62:65], v[188:191], v[70:73], v[62:65]
	v_mfma_f32_16x16x32_bf16 v[62:65], v[184:187], v[66:69], v[62:65]
	v_mfma_f32_16x16x32_bf16 v[46:49], v[184:187], v[224:227], v[46:49]
	v_mfma_f32_16x16x32_bf16 v[46:49], v[188:191], v[228:231], v[46:49]
	s_setprio 0
	s_setprio 1
	v_mfma_f32_16x16x32_bf16 v[42:45], v[180:183], v[228:231], v[42:45]
	v_mfma_f32_16x16x32_bf16 v[42:45], v[192:195], v[224:227], v[42:45]
	v_mfma_f32_16x16x32_bf16 v[26:29], v[192:195], v[232:235], v[26:29]
	v_mfma_f32_16x16x32_bf16 v[26:29], v[180:183], v[240:243], v[26:29]
	v_mfma_f32_16x16x32_bf16 v[30:33], v[188:191], v[240:243], v[30:33]
	v_mfma_f32_16x16x32_bf16 v[30:33], v[184:187], v[232:235], v[30:33]
	v_mfma_f32_16x16x32_bf16 v[14:17], v[184:187], v[244:247], v[14:17]
	v_mfma_f32_16x16x32_bf16 v[14:17], v[188:191], v[248:251], v[14:17]
	s_setprio 0
	s_setprio 1
	s_and_b64 vcc, exec, s[82:83]
	s_cbranch_vccz .Lslv_b2
	v_mfma_f32_16x16x32_bf16 v[66:69], v[184:187], v[166:169], v[6:9]
	v_mfma_f32_16x16x32_bf16 v[70:73], v[192:195], v[166:169], v[2:5]
	v_mfma_f32_16x16x32_bf16 v[66:69], v[188:191], v[170:173], v[66:69]
	v_mfma_f32_16x16x32_bf16 v[70:73], v[180:183], v[170:173], v[70:73]
	s_branch .LBB0_815

; #define PG8_STAGE(bufoff, gbase, voff) do { _Pragma("unroll") for (int _i = 0; _i < 2; ++_i) \
;         __builtin_amdgcn_global_load_lds((const unsigned*)((const char*)(gbase) + (size_t)_i * qstep + (voff)[0]), (PG8_LAS unsigned*)(lds + (bufoff) + ldsw + _i * 8192), 16, 0, 0); } while (0)
; #define PG8_LDA(dst, b, h) do { _Pragma("unroll") for (int m = 0; m < 4; ++m) _Pragma("unroll") for (int k = 0; k < 2; ++k) dst[m][k] = *(const PG8_LAS bf16x8*)(lds + PG8_SA(b, h) + aoff + m * 2048 + k * 1024); } while (0)
; #define PG8_LDB(dst, b, h) do { _Pragma("unroll") for (int n = 0; n < 2; ++n) _Pragma("unroll") for (int k = 0; k < 2; ++k) dst[n][k] = *(const PG8_LAS bf16x8*)(lds + PG8_SB(b, h) + boff + n * 2048 + k * 1024); } while (0)
; #define PG8_MMA(ai, bj, At, Bt) do { __builtin_amdgcn_s_setprio(1); _Pragma("unroll") for (int m = 0; m < 4; ++m) _Pragma("unroll") for (int n = 0; n < 2; ++n) _Pragma("unroll") for (int k = 0; k < 2; ++k) \
;         acc[ai][bj][m][n] = __builtin_amdgcn_mfma_f32_16x16x32_bf16(Bt[n][k], At[m][k], acc[ai][bj][m][n], 0, 0, 0); __builtin_amdgcn_s_setprio(0); } while (0)
; #define PG8_WAIT_V89() do { if constexpr (SLIVER) PG8_WAIT_V(9); else PG8_WAIT_V(8); } while (0)
; #define PG8_STAGE_S(b, gbase) do { if constexpr (SLIVER) __builtin_amdgcn_global_load_lds((const unsigned*)((const char*)(gbase) + voffS), (PG8_LAS unsigned*)(lds + STAGE_BYTES + (b) * 2048 + wid * 256), 4, 0, 0); } while (0)
; #define PG8_WAIT_L(n) asm volatile("s_waitcnt lgkmcnt(" #n ")" ::: "memory")
; #define PG8_BAR __builtin_amdgcn_s_barrier()
; #define PG8_SCHED __builtin_amdgcn_sched_barrier(0)
; template <class Epi, class Sched, bool ALIGN_EPI = false, bool SP2 = false, bool SLIVER = false>
; __device__ __forceinline__ void gemm_phase(PG8_LAS unsigned char* lds, const Gemm g, const Sched& S, const Epi& E) {
;     ...
;             PG8_WAIT_V89(); PG8_WAIT_L(0); PG8_BAR; PG8_MMA(1, 0, At, B0); PG8_MMA(1, 1, At, B1); PG8_MMA_S(); PG8_BAR; PG8_SCHED;
;             PG8_LDB(B0, 1, 0); PG8_LDB(B1, 1, 1); PG8_SCHED; PG8_LDA(At, 1, 0); PG8_STAGE(PG8_SA(0, 1), a2 + hstep, voffA); PG8_STAGE_S(0, s2);
;             PG8_WAIT_V89(); PG8_WAIT_L(0); PG8_BAR; PG8_MMA(0, 0, At, B0); PG8_MMA(0, 1, At, B1); PG8_BAR; PG8_SCHED;
.LBB0_815:
	s_barrier
	s_setprio 0
	s_add_u32 s13, s92, s62
	s_addc_u32 s66, s93, s63
	s_add_u32 s13, s13, 0x100
	s_addc_u32 s68, s66, 0
	s_and_b64 s[66:67], s[80:81], exec
	s_cselect_b32 s67, s89, s68
	s_cselect_b32 s66, s88, s13
	s_add_i32 s13, 0, 0x18000
	v_add_u32_e32 v2, s13, v220
	s_add_i32 s68, 0, 0x1c000
	ds_read_b128 v[154:157], v2
	ds_read_b128 v[158:161], v2 offset:1024
	ds_read_b128 v[162:165], v2 offset:2048
	ds_read_b128 v[174:177], v2 offset:3072
	v_add_u32_e32 v2, s68, v220
	ds_read_b128 v[184:187], v2
	ds_read_b128 v[188:191], v2 offset:1024
	ds_read_b128 v[192:195], v2 offset:2048
	ds_read_b128 v[180:183], v2 offset:3072
	s_mov_b32 m0, s53
	v_lshl_add_u64 v[166:167], v[218:219], 0, s[0:1]
	ds_read_b128 v[2:5], v223 offset:32768
	ds_read_b128 v[6:9], v223 offset:33792
	ds_read_b128 v[82:85], v223 offset:34816
	ds_read_b128 v[86:89], v223 offset:35840
	ds_read_b128 v[224:227], v223 offset:36864
	ds_read_b128 v[228:231], v223 offset:37888
	ds_read_b128 v[232:235], v223 offset:38912
	ds_read_b128 v[240:243], v223 offset:39936
	global_load_lds_dwordx4 v[166:167], off
	v_lshl_add_u64 v[166:167], v[218:219], 0, s[74:75]
	s_mov_b32 m0, s54
	s_nop 0
	global_load_lds_dwordx4 v[166:167], off
	v_lshl_add_u64 v[166:167], s[66:67], 0, v[200:201]
	s_mov_b32 m0, s55
	s_nop 0
	global_load_lds_dword v[166:167], off
	s_waitcnt vmcnt(9)
	s_waitcnt lgkmcnt(0)
	s_setprio 1
	s_barrier
	v_mfma_f32_16x16x32_bf16 v[146:149], v[154:157], v[2:5], v[146:149]
	v_mfma_f32_16x16x32_bf16 v[170:173], v[158:161], v[6:9], v[146:149]
	v_mfma_f32_16x16x32_bf16 v[146:149], v[162:165], v[2:5], v[150:153]
	v_mfma_f32_16x16x32_bf16 v[166:169], v[174:177], v[6:9], v[146:149]
	v_mfma_f32_16x16x32_bf16 v[134:137], v[154:157], v[82:85], v[134:137]
	v_mfma_f32_16x16x32_bf16 v[134:137], v[158:161], v[86:89], v[134:137]
	v_mfma_f32_16x16x32_bf16 v[130:133], v[162:165], v[82:85], v[130:133]
	v_mfma_f32_16x16x32_bf16 v[130:133], v[174:177], v[86:89], v[130:133]
	s_setprio 0
	s_setprio 1
	v_mfma_f32_16x16x32_bf16 v[118:121], v[154:157], v[224:227], v[118:121]
	v_mfma_f32_16x16x32_bf16 v[118:121], v[158:161], v[228:231], v[118:121]
	v_mfma_f32_16x16x32_bf16 v[114:117], v[162:165], v[224:227], v[114:117]
	v_mfma_f32_16x16x32_bf16 v[114:117], v[174:177], v[228:231], v[114:117]
	v_mfma_f32_16x16x32_bf16 v[102:105], v[154:157], v[232:235], v[102:105]
	v_mfma_f32_16x16x32_bf16 v[102:105], v[158:161], v[240:243], v[102:105]
	v_mfma_f32_16x16x32_bf16 v[98:101], v[162:165], v[232:235], v[98:101]
	v_mfma_f32_16x16x32_bf16 v[98:101], v[174:177], v[240:243], v[98:101]
	s_setprio 0
	s_setprio 1
	v_mfma_f32_16x16x32_bf16 v[142:145], v[184:187], v[2:5], v[142:145]
	v_mfma_f32_16x16x32_bf16 v[142:145], v[188:191], v[6:9], v[142:145]
	v_mfma_f32_16x16x32_bf16 v[2:5], v[192:195], v[2:5], v[138:141]
	v_mfma_f32_16x16x32_bf16 v[138:141], v[180:183], v[6:9], v[2:5]
	v_mfma_f32_16x16x32_bf16 v[2:5], v[184:187], v[82:85], v[126:129]
	v_mfma_f32_16x16x32_bf16 v[126:129], v[188:191], v[86:89], v[2:5]
	v_mfma_f32_16x16x32_bf16 v[2:5], v[192:195], v[82:85], v[122:125]
	v_mfma_f32_16x16x32_bf16 v[122:125], v[180:183], v[86:89], v[2:5]
	s_setprio 0
	s_setprio 1
	v_mfma_f32_16x16x32_bf16 v[2:5], v[184:187], v[224:227], v[110:113]
	v_mfma_f32_16x16x32_bf16 v[110:113], v[188:191], v[228:231], v[2:5]
	v_mfma_f32_16x16x32_bf16 v[2:5], v[192:195], v[224:227], v[106:109]
	v_mfma_f32_16x16x32_bf16 v[106:109], v[180:183], v[228:231], v[2:5]
	v_mfma_f32_16x16x32_bf16 v[2:5], v[184:187], v[232:235], v[94:97]
	v_mfma_f32_16x16x32_bf16 v[94:97], v[188:191], v[240:243], v[2:5]
	v_mfma_f32_16x16x32_bf16 v[2:5], v[192:195], v[232:235], v[90:93]
	v_mfma_f32_16x16x32_bf16 v[90:93], v[180:183], v[240:243], v[2:5]
	s_barrier
; #define PG8_SB(B) __builtin_amdgcn_rcpf(1.f + expneg(B))
; #define PG8_SB(B) __builtin_amdgcn_rcpf(1.f + expneg(B))
; #define PG8_STAGE(bufoff, gbase, voff) do { _Pragma("unroll") for (int _i = 0; _i < 2; ++_i) \
;         __builtin_amdgcn_global_load_lds((const unsigned*)((const char*)(gbase) + (size_t)_i * qstep + (voff)[0]), (PG8_LAS unsigned*)(lds + (bufoff) + ldsw + _i * 8192), 16, 0, 0); } while (0)
; #define PG8_LDA(dst, b, h) do { _Pragma("unroll") for (int m = 0; m < 4; ++m) _Pragma("unroll") for (int k = 0; k < 2; ++k) dst[m][k] = *(const PG8_LAS bf16x8*)(lds + PG8_SA(b, h) + aoff + m * 2048 + k * 1024); } while (0)
; #define PG8_MMA(ai, bj, At, Bt) do { __builtin_amdgcn_s_setprio(1); _Pragma("unroll") for (int m = 0; m < 4; ++m) _Pragma("unroll") for (int n = 0; n < 2; ++n) _Pragma("unroll") for (int k = 0; k < 2; ++k) \
;         acc[ai][bj][m][n] = __builtin_amdgcn_mfma_f32_16x16x32_bf16(Bt[n][k], At[m][k], acc[ai][bj][m][n], 0, 0, 0); __builtin_amdgcn_s_setprio(0); } while (0)
; #define PG8_WAIT_V89() do { if constexpr (SLIVER) PG8_WAIT_V(9); else PG8_WAIT_V(8); } while (0)
; #define PG8_LDS_S(b) do { if constexpr (SLIVER) { Sf[0] = *(const PG8_LAS bf16x8*)(lds + STAGE_BYTES + (b) * 2048 + soff0); Sf[1] = *(const PG8_LAS bf16x8*)(lds + STAGE_BYTES + (b) * 2048 + (soff0 ^ 64)); } } while (0)
; #define PG8_WAIT_L(n) asm volatile("s_waitcnt lgkmcnt(" #n ")" ::: "memory")
; #define PG8_BAR __builtin_amdgcn_s_barrier()
; #define PG8_SCHED __builtin_amdgcn_sched_barrier(0)
; template <class Epi, class Sched, bool ALIGN_EPI = false, bool SP2 = false, bool SLIVER = false>
; __device__ __forceinline__ void gemm_phase(PG8_LAS unsigned char* lds, const Gemm g, const Sched& S, const Epi& E) {
;     ...
;             PG8_LDA(At, 1, 1); PG8_LDS_S(1); PG8_STAGE(PG8_SB(1, 0), b3, voffB); PG8_STAGE(PG8_SB(1, 1), b3 + hstep, voffB); PG8_STAGE(PG8_SA(1, 0), a3, voffA);
;             PG8_WAIT_V89(); PG8_WAIT_L(0); PG8_BAR; PG8_MMA(1, 0, At, B0); PG8_MMA(1, 1, At, B1); PG8_MMA_S(); PG8_BAR; PG8_SCHED;
	s_setprio 0
	s_add_i32 s66, 0, 0x20800
	v_add_u32_e32 v82, s66, v221
	v_add_u32_e32 v83, s66, v222
	s_add_i32 s13, s13, s18
	ds_read_b128 v[2:5], v223 offset:49152
	ds_read_b128 v[6:9], v223 offset:50176
	ds_read_b128 v[224:227], v223 offset:51200
	ds_read_b128 v[228:231], v223 offset:52224
	ds_read_b128 v[232:235], v223 offset:53248
	ds_read_b128 v[240:243], v223 offset:54272
	ds_read_b128 v[244:247], v223 offset:55296
	ds_read_b128 v[248:251], v223 offset:56320
	ds_read_b128 v[146:149], v82
	ds_read_b128 v[150:153], v83
	v_lshl_add_u64 v[82:83], v[216:217], 0, s[26:27]
	s_mov_b32 m0, s13
	s_mov_b64 s[66:67], 0x210080
	global_load_lds_dwordx4 v[82:83], off
	v_lshl_add_u64 v[82:83], v[216:217], 0, s[60:61]
	s_add_i32 m0, s13, 0x2000
	s_add_i32 s13, s68, s18
	global_load_lds_dwordx4 v[82:83], off
	v_lshl_add_u64 v[82:83], v[216:217], 0, s[8:9]
	s_mov_b32 m0, s13
	s_nop 0
	global_load_lds_dwordx4 v[82:83], off
	v_lshl_add_u64 v[82:83], v[216:217], 0, s[66:67]
	s_add_i32 m0, s13, 0x2000
	s_nop 0
	global_load_lds_dwordx4 v[82:83], off
	v_lshl_add_u64 v[82:83], v[218:219], 0, s[26:27]
	s_mov_b32 m0, s10
	s_nop 0
	global_load_lds_dwordx4 v[82:83], off
	v_lshl_add_u64 v[82:83], v[218:219], 0, s[60:61]
	s_mov_b32 m0, s48
	s_nop 0
	global_load_lds_dwordx4 v[82:83], off
	s_waitcnt vmcnt(9)
	s_waitcnt lgkmcnt(0)
	s_setprio 1
	s_barrier
	v_mfma_f32_16x16x32_bf16 v[74:77], v[154:157], v[2:5], v[74:77]
	v_mfma_f32_16x16x32_bf16 v[86:89], v[158:161], v[6:9], v[74:77]
	v_mfma_f32_16x16x32_bf16 v[74:77], v[162:165], v[2:5], v[78:81]
	v_mfma_f32_16x16x32_bf16 v[82:85], v[174:177], v[6:9], v[74:77]
	v_mfma_f32_16x16x32_bf16 v[54:57], v[154:157], v[224:227], v[54:57]
	v_mfma_f32_16x16x32_bf16 v[54:57], v[158:161], v[228:231], v[54:57]
	v_mfma_f32_16x16x32_bf16 v[50:53], v[162:165], v[224:227], v[50:53]
	v_mfma_f32_16x16x32_bf16 v[50:53], v[174:177], v[228:231], v[50:53]
	s_setprio 0
	s_setprio 1
	v_mfma_f32_16x16x32_bf16 v[38:41], v[154:157], v[232:235], v[38:41]
	v_mfma_f32_16x16x32_bf16 v[38:41], v[158:161], v[240:243], v[38:41]
	v_mfma_f32_16x16x32_bf16 v[34:37], v[162:165], v[232:235], v[34:37]
	v_mfma_f32_16x16x32_bf16 v[34:37], v[174:177], v[240:243], v[34:37]
	v_mfma_f32_16x16x32_bf16 v[22:25], v[154:157], v[244:247], v[22:25]
	v_mfma_f32_16x16x32_bf16 v[22:25], v[158:161], v[248:251], v[22:25]
	v_mfma_f32_16x16x32_bf16 v[18:21], v[162:165], v[244:247], v[18:21]
	v_mfma_f32_16x16x32_bf16 v[18:21], v[174:177], v[248:251], v[18:21]
	s_setprio 0
	s_setprio 1
	v_mfma_f32_16x16x32_bf16 v[62:65], v[184:187], v[2:5], v[62:65]
	v_mfma_f32_16x16x32_bf16 v[62:65], v[188:191], v[6:9], v[62:65]
	v_mfma_f32_16x16x32_bf16 v[2:5], v[192:195], v[2:5], v[58:61]
	v_mfma_f32_16x16x32_bf16 v[58:61], v[180:183], v[6:9], v[2:5]
	v_mfma_f32_16x16x32_bf16 v[2:5], v[184:187], v[224:227], v[46:49]
	v_mfma_f32_16x16x32_bf16 v[46:49], v[188:191], v[228:231], v[2:5]
	v_mfma_f32_16x16x32_bf16 v[2:5], v[192:195], v[224:227], v[42:45]
	v_mfma_f32_16x16x32_bf16 v[42:45], v[180:183], v[228:231], v[2:5]
	s_setprio 0
	s_setprio 1
	v_mfma_f32_16x16x32_bf16 v[2:5], v[184:187], v[232:235], v[30:33]
	v_mfma_f32_16x16x32_bf16 v[30:33], v[188:191], v[240:243], v[2:5]
	v_mfma_f32_16x16x32_bf16 v[2:5], v[192:195], v[232:235], v[26:29]
	v_mfma_f32_16x16x32_bf16 v[26:29], v[180:183], v[240:243], v[2:5]
	v_mfma_f32_16x16x32_bf16 v[2:5], v[184:187], v[244:247], v[14:17]
	v_mfma_f32_16x16x32_bf16 v[14:17], v[188:191], v[248:251], v[2:5]
	v_mfma_f32_16x16x32_bf16 v[2:5], v[192:195], v[244:247], v[10:13]
	v_mfma_f32_16x16x32_bf16 v[10:13], v[180:183], v[248:251], v[2:5]
	s_setprio 0
	s_setprio 1
	s_and_b64 vcc, exec, s[82:83]
	s_cbranch_vccz .Lslv_c2
	v_mfma_f32_16x16x32_bf16 v[2:5], v[184:187], v[146:149], v[66:69]
	v_mfma_f32_16x16x32_bf16 v[6:9], v[188:191], v[150:153], v[2:5]
	v_mfma_f32_16x16x32_bf16 v[2:5], v[192:195], v[146:149], v[70:73]
	v_mfma_f32_16x16x32_bf16 v[2:5], v[180:183], v[150:153], v[2:5]
	s_branch .LBB0_810

; #define PG8_STAGE(bufoff, gbase, voff) do { _Pragma("unroll") for (int _i = 0; _i < 2; ++_i) \
;         __builtin_amdgcn_global_load_lds((const unsigned*)((const char*)(gbase) + (size_t)_i * qstep + (voff)[0]), (PG8_LAS unsigned*)(lds + (bufoff) + ldsw + _i * 8192), 16, 0, 0); } while (0)
; #define PG8_LDA(dst, b, h) do { _Pragma("unroll") for (int m = 0; m < 4; ++m) _Pragma("unroll") for (int k = 0; k < 2; ++k) dst[m][k] = *(const PG8_LAS bf16x8*)(lds + PG8_SA(b, h) + aoff + m * 2048 + k * 1024); } while (0)
; #define PG8_LDB(dst, b, h) do { _Pragma("unroll") for (int n = 0; n < 2; ++n) _Pragma("unroll") for (int k = 0; k < 2; ++k) dst[n][k] = *(const PG8_LAS bf16x8*)(lds + PG8_SB(b, h) + boff + n * 2048 + k * 1024); } while (0)
; #define PG8_MMA(ai, bj, At, Bt) do { __builtin_amdgcn_s_setprio(1); _Pragma("unroll") for (int m = 0; m < 4; ++m) _Pragma("unroll") for (int n = 0; n < 2; ++n) _Pragma("unroll") for (int k = 0; k < 2; ++k) \
;         acc[ai][bj][m][n] = __builtin_amdgcn_mfma_f32_16x16x32_bf16(Bt[n][k], At[m][k], acc[ai][bj][m][n], 0, 0, 0); __builtin_amdgcn_s_setprio(0); } while (0)
; #define PG8_WAIT_V89() do { if constexpr (SLIVER) PG8_WAIT_V(9); else PG8_WAIT_V(8); } while (0)
; #define PG8_WAIT_L(n) asm volatile("s_waitcnt lgkmcnt(" #n ")" ::: "memory")
; #define PG8_BAR __builtin_amdgcn_s_barrier()
; #define PG8_SCHED __builtin_amdgcn_sched_barrier(0)
; template <class Epi, class Sched, bool ALIGN_EPI = false, bool SP2 = false, bool SLIVER = false>
; __device__ __forceinline__ void gemm_phase(PG8_LAS unsigned char* lds, const Gemm g, const Sched& S, const Epi& E) {
;     ...
;             const bool last = (t == nt - 2);
;             const char* a1 = cA + (size_t)(t + 1) * kstep;
;             const char* a2 = last ? nA : cA + (size_t)(t + 2) * kstep; const char* b2 = last ? nB : cB + (size_t)(t + 2) * kstep;
;             const char* a3 = a2 + kstep; const char* b3 = b2 + kstep;
;             const char* s1 = cS + (size_t)(t + 1) * kstep; const char* s2 = last ? nS : cS + (size_t)(t + 2) * kstep;
;             if (last && has_next) S.a_ready(nxt);
;             if constexpr (SP2) {
;             PG8_LDB(B0, 0, 0); PG8_LDB(B1, 0, 1); PG8_SCHED; PG8_LDA(At, 0, 0); PG8_STAGE(PG8_SA(1, 1), a1 + hstep, voffA); PG8_STAGE_S(1, s1);
;             PG8_WAIT_V89(); PG8_WAIT_L(0); PG8_BAR; PG8_MMA(0, 0, At, B0); PG8_MMA(0, 1, At, B1); PG8_BAR; PG8_SCHED;
.LBB0_934:
	s_cmp_eq_u32 s66, s62
	s_cselect_b64 s[80:81], -1, 0
	s_add_u32 s12, s42, s62
	s_addc_u32 s13, s43, s63
	s_add_u32 s40, s12, 0x100
	s_addc_u32 s41, s13, 0
	s_and_b64 s[12:13], s[80:81], exec
	s_cselect_b32 s41, s95, s41
	s_cselect_b32 s40, s94, s40
	s_add_u32 s68, s17, s62
	s_addc_u32 s69, s45, s63
	s_add_i32 s76, 0, 0x10000
	s_and_b64 s[12:13], s[80:81], exec
	v_add_u32_e32 v138, s76, v212
	s_cselect_b32 s13, s97, s69
	s_cselect_b32 s12, s96, s68
	s_add_i32 s68, 0, 0x14000
	ds_read_b128 v[146:149], v138
	ds_read_b128 v[150:153], v138 offset:1024
	ds_read_b128 v[154:157], v138 offset:2048
	ds_read_b128 v[158:161], v138 offset:3072
	v_add_u32_e32 v138, s68, v212
	ds_read_b128 v[166:169], v138
	ds_read_b128 v[170:173], v138 offset:1024
	ds_read_b128 v[174:177], v138 offset:2048
	ds_read_b128 v[162:165], v138 offset:3072
	v_lshl_add_u64 v[202:203], v[198:199], 0, s[62:63]
	s_mov_b64 vcc, 0x90080
	v_lshl_add_u64 v[208:209], v[202:203], 0, vcc
	s_add_i32 m0, s93, 0xc000
	s_mov_b64 vcc, 0xd8080
	ds_read_b128 v[138:141], v215
	ds_read_b128 v[142:145], v215 offset:1024
	ds_read_b128 v[180:183], v215 offset:2048
	ds_read_b128 v[184:187], v215 offset:3072
	ds_read_b128 v[216:219], v215 offset:4096
	ds_read_b128 v[220:223], v215 offset:5120
	ds_read_b128 v[224:227], v215 offset:6144
	ds_read_b128 v[228:231], v215 offset:7168
	global_load_lds_dwordx4 v[208:209], off
	v_lshl_add_u64 v[202:203], v[202:203], 0, vcc
	s_add_i32 m0, s93, 0xe000
	s_nop 0
	global_load_lds_dwordx4 v[202:203], off
	v_lshl_add_u64 v[202:203], v[200:201], 0, s[62:63]
	s_add_i32 m0, s50, 0x20800
	s_nop 0
	global_load_lds_dword v[202:203], off
	s_waitcnt vmcnt(9)
	s_waitcnt lgkmcnt(0)
	s_setprio 1
	s_barrier
	v_mfma_f32_16x16x32_bf16 v[134:137], v[146:149], v[138:141], v[134:137]
	v_mfma_f32_16x16x32_bf16 v[134:137], v[150:153], v[142:145], v[134:137]
	v_mfma_f32_16x16x32_bf16 v[130:133], v[158:161], v[142:145], v[130:133]
	v_mfma_f32_16x16x32_bf16 v[130:133], v[154:157], v[138:141], v[130:133]
	v_mfma_f32_16x16x32_bf16 v[122:125], v[154:157], v[180:183], v[122:125]
	v_mfma_f32_16x16x32_bf16 v[122:125], v[158:161], v[184:187], v[122:125]
	v_mfma_f32_16x16x32_bf16 v[126:129], v[150:153], v[184:187], v[126:129]
	v_mfma_f32_16x16x32_bf16 v[126:129], v[146:149], v[180:183], v[126:129]
	s_setprio 0
	s_setprio 1
	v_mfma_f32_16x16x32_bf16 v[114:117], v[146:149], v[216:219], v[114:117]
	v_mfma_f32_16x16x32_bf16 v[114:117], v[150:153], v[220:223], v[114:117]
	v_mfma_f32_16x16x32_bf16 v[106:109], v[158:161], v[220:223], v[106:109]
	v_mfma_f32_16x16x32_bf16 v[106:109], v[154:157], v[216:219], v[106:109]
	v_mfma_f32_16x16x32_bf16 v[90:93], v[154:157], v[224:227], v[90:93]
	v_mfma_f32_16x16x32_bf16 v[90:93], v[158:161], v[228:231], v[90:93]
	v_mfma_f32_16x16x32_bf16 v[98:101], v[150:153], v[228:231], v[98:101]
	v_mfma_f32_16x16x32_bf16 v[98:101], v[146:149], v[224:227], v[98:101]
	s_setprio 0
	s_setprio 1
	v_mfma_f32_16x16x32_bf16 v[74:77], v[174:177], v[224:227], v[74:77]
	v_mfma_f32_16x16x32_bf16 v[74:77], v[162:165], v[228:231], v[74:77]
	v_mfma_f32_16x16x32_bf16 v[110:113], v[162:165], v[142:145], v[110:113]
	v_mfma_f32_16x16x32_bf16 v[110:113], v[174:177], v[138:141], v[110:113]
	v_mfma_f32_16x16x32_bf16 v[118:121], v[166:169], v[138:141], v[118:121]
	v_mfma_f32_16x16x32_bf16 v[118:121], v[170:173], v[142:145], v[118:121]
	v_mfma_f32_16x16x32_bf16 v[102:105], v[170:173], v[184:187], v[102:105]
	v_mfma_f32_16x16x32_bf16 v[102:105], v[166:169], v[180:183], v[102:105]
	s_setprio 0
	s_setprio 1
	v_mfma_f32_16x16x32_bf16 v[94:97], v[174:177], v[180:183], v[94:97]
	v_mfma_f32_16x16x32_bf16 v[94:97], v[162:165], v[184:187], v[94:97]
	v_mfma_f32_16x16x32_bf16 v[82:85], v[162:165], v[220:223], v[82:85]
	v_mfma_f32_16x16x32_bf16 v[82:85], v[174:177], v[216:219], v[82:85]
	v_mfma_f32_16x16x32_bf16 v[86:89], v[166:169], v[216:219], v[86:89]
	v_mfma_f32_16x16x32_bf16 v[86:89], v[170:173], v[220:223], v[86:89]
	v_mfma_f32_16x16x32_bf16 v[78:81], v[170:173], v[228:231], v[78:81]
	v_mfma_f32_16x16x32_bf16 v[78:81], v[166:169], v[224:227], v[78:81]
	s_barrier
; #define PG8_SB(B) __builtin_amdgcn_rcpf(1.f + expneg(B))
; #define PG8_SB(B) __builtin_amdgcn_rcpf(1.f + expneg(B))
; #define PG8_STAGE(bufoff, gbase, voff) do { _Pragma("unroll") for (int _i = 0; _i < 2; ++_i) \
;         __builtin_amdgcn_global_load_lds((const unsigned*)((const char*)(gbase) + (size_t)_i * qstep + (voff)[0]), (PG8_LAS unsigned*)(lds + (bufoff) + ldsw + _i * 8192), 16, 0, 0); } while (0)
; #define PG8_LDA(dst, b, h) do { _Pragma("unroll") for (int m = 0; m < 4; ++m) _Pragma("unroll") for (int k = 0; k < 2; ++k) dst[m][k] = *(const PG8_LAS bf16x8*)(lds + PG8_SA(b, h) + aoff + m * 2048 + k * 1024); } while (0)
; #define PG8_MMA(ai, bj, At, Bt) do { __builtin_amdgcn_s_setprio(1); _Pragma("unroll") for (int m = 0; m < 4; ++m) _Pragma("unroll") for (int n = 0; n < 2; ++n) _Pragma("unroll") for (int k = 0; k < 2; ++k) \
;         acc[ai][bj][m][n] = __builtin_amdgcn_mfma_f32_16x16x32_bf16(Bt[n][k], At[m][k], acc[ai][bj][m][n], 0, 0, 0); __builtin_amdgcn_s_setprio(0); } while (0)
; #define PG8_WAIT_V89() do { if constexpr (SLIVER) PG8_WAIT_V(9); else PG8_WAIT_V(8); } while (0)
; #define PG8_LDS_S(b) do { if constexpr (SLIVER) { Sf[0] = *(const PG8_LAS bf16x8*)(lds + STAGE_BYTES + (b) * 2048 + soff0); Sf[1] = *(const PG8_LAS bf16x8*)(lds + STAGE_BYTES + (b) * 2048 + (soff0 ^ 64)); } } while (0)
; #define PG8_WAIT_L(n) asm volatile("s_waitcnt lgkmcnt(" #n ")" ::: "memory")
; #define PG8_BAR __builtin_amdgcn_s_barrier()
; #define PG8_SCHED __builtin_amdgcn_sched_barrier(0)
; template <class Epi, class Sched, bool ALIGN_EPI = false, bool SP2 = false, bool SLIVER = false>
; __device__ __forceinline__ void gemm_phase(PG8_LAS unsigned char* lds, const Gemm g, const Sched& S, const Epi& E) {
;     ...
;             PG8_LDA(At, 0, 1); PG8_LDS_S(0); PG8_STAGE(PG8_SB(0, 0), b2, voffB); PG8_STAGE(PG8_SB(0, 1), b2 + hstep, voffB); PG8_STAGE(PG8_SA(0, 0), a2, voffA);
;             PG8_WAIT_V89(); PG8_WAIT_L(0); PG8_BAR; PG8_MMA(1, 0, At, B0); PG8_MMA(1, 1, At, B1); PG8_MMA_S(); PG8_BAR; PG8_SCHED;
	s_setprio 0
	s_add_i32 s69, 0, 0x20000
	v_lshl_add_u64 v[202:203], s[12:13], 0, v[190:191]
	s_add_i32 s12, s76, s92
	v_add_u32_e32 v178, s69, v213
	v_add_u32_e32 v184, s69, v214
	s_mov_b32 m0, s12
	ds_read_b128 v[138:141], v215 offset:16384
	ds_read_b128 v[142:145], v215 offset:17408
	ds_read_b128 v[216:219], v215 offset:18432
	ds_read_b128 v[220:223], v215 offset:19456
	ds_read_b128 v[224:227], v215 offset:20480
	ds_read_b128 v[228:231], v215 offset:21504
	ds_read_b128 v[232:235], v215 offset:22528
	ds_read_b128 v[240:243], v215 offset:23552
	ds_read_b128 v[180:183], v178
	ds_read_b128 v[184:187], v184
	global_load_lds_dwordx4 v[202:203], off
	v_lshl_add_u64 v[208:209], v[202:203], 0, s[70:71]
	s_add_i32 m0, s12, 0x2000
	s_add_i32 s12, s68, s92
	global_load_lds_dwordx4 v[208:209], off
	v_lshl_add_u64 v[208:209], v[202:203], 0, s[46:47]
	s_mov_b32 m0, s12
	v_lshl_add_u64 v[210:211], s[40:41], 0, v[188:189]
	global_load_lds_dwordx4 v[208:209], off
	v_lshl_add_u64 v[208:209], v[202:203], 0, s[6:7]
	s_add_i32 m0, s12, 0x2000
	s_nop 0
	global_load_lds_dwordx4 v[208:209], off
	s_mov_b32 m0, s93
	v_lshl_add_u64 v[208:209], v[210:211], 0, s[70:71]
	global_load_lds_dwordx4 v[210:211], off
	s_mov_b32 m0, s48
	s_nop 0
	global_load_lds_dwordx4 v[208:209], off
	s_waitcnt vmcnt(9)
	s_waitcnt lgkmcnt(0)
	s_setprio 1
	s_barrier
	v_mfma_f32_16x16x32_bf16 v[70:73], v[146:149], v[138:141], v[70:73]
	v_mfma_f32_16x16x32_bf16 v[70:73], v[150:153], v[142:145], v[70:73]
	v_mfma_f32_16x16x32_bf16 v[66:69], v[158:161], v[142:145], v[66:69]
	v_mfma_f32_16x16x32_bf16 v[66:69], v[154:157], v[138:141], v[66:69]
	v_mfma_f32_16x16x32_bf16 v[58:61], v[154:157], v[216:219], v[58:61]
	v_mfma_f32_16x16x32_bf16 v[58:61], v[158:161], v[220:223], v[58:61]
	v_mfma_f32_16x16x32_bf16 v[62:65], v[150:153], v[220:223], v[62:65]
	v_mfma_f32_16x16x32_bf16 v[62:65], v[146:149], v[216:219], v[62:65]
	s_setprio 0
	s_setprio 1
	v_mfma_f32_16x16x32_bf16 v[50:53], v[146:149], v[224:227], v[50:53]
	v_mfma_f32_16x16x32_bf16 v[50:53], v[150:153], v[228:231], v[50:53]
	v_mfma_f32_16x16x32_bf16 v[42:45], v[158:161], v[228:231], v[42:45]
	v_mfma_f32_16x16x32_bf16 v[42:45], v[154:157], v[224:227], v[42:45]
	v_mfma_f32_16x16x32_bf16 v[26:29], v[154:157], v[232:235], v[26:29]
	v_mfma_f32_16x16x32_bf16 v[26:29], v[158:161], v[240:243], v[26:29]
	v_mfma_f32_16x16x32_bf16 v[34:37], v[150:153], v[240:243], v[34:37]
	v_mfma_f32_16x16x32_bf16 v[34:37], v[146:149], v[232:235], v[34:37]
	s_setprio 0
	s_setprio 1
	v_mfma_f32_16x16x32_bf16 v[10:13], v[174:177], v[232:235], v[10:13]
	v_mfma_f32_16x16x32_bf16 v[10:13], v[162:165], v[240:243], v[10:13]
	v_mfma_f32_16x16x32_bf16 v[46:49], v[162:165], v[142:145], v[46:49]
	v_mfma_f32_16x16x32_bf16 v[46:49], v[174:177], v[138:141], v[46:49]
	v_mfma_f32_16x16x32_bf16 v[54:57], v[166:169], v[138:141], v[54:57]
	v_mfma_f32_16x16x32_bf16 v[54:57], v[170:173], v[142:145], v[54:57]
	v_mfma_f32_16x16x32_bf16 v[38:41], v[170:173], v[220:223], v[38:41]
	v_mfma_f32_16x16x32_bf16 v[38:41], v[166:169], v[216:219], v[38:41]
	s_setprio 0
	s_setprio 1
	v_mfma_f32_16x16x32_bf16 v[30:33], v[174:177], v[216:219], v[30:33]
	v_mfma_f32_16x16x32_bf16 v[30:33], v[162:165], v[220:223], v[30:33]
	v_mfma_f32_16x16x32_bf16 v[18:21], v[162:165], v[228:231], v[18:21]
	v_mfma_f32_16x16x32_bf16 v[18:21], v[174:177], v[224:227], v[18:21]
	v_mfma_f32_16x16x32_bf16 v[22:25], v[166:169], v[224:227], v[22:25]
	v_mfma_f32_16x16x32_bf16 v[22:25], v[170:173], v[228:231], v[22:25]
	v_mfma_f32_16x16x32_bf16 v[14:17], v[170:173], v[240:243], v[14:17]
	v_mfma_f32_16x16x32_bf16 v[14:17], v[166:169], v[232:235], v[14:17]
	s_setprio 0
	s_setprio 1
	s_and_b64 vcc, exec, s[90:91]
	s_cbranch_vccz .Lslv_b3
	v_mfma_f32_16x16x32_bf16 v[138:141], v[166:169], v[180:183], v[6:9]
	v_mfma_f32_16x16x32_bf16 v[142:145], v[174:177], v[180:183], v[2:5]
	v_mfma_f32_16x16x32_bf16 v[138:141], v[170:173], v[184:187], v[138:141]
	v_mfma_f32_16x16x32_bf16 v[142:145], v[162:165], v[184:187], v[142:145]
	s_branch .LBB0_938

; #define PG8_STAGE(bufoff, gbase, voff) do { _Pragma("unroll") for (int _i = 0; _i < 2; ++_i) \
;         __builtin_amdgcn_global_load_lds((const unsigned*)((const char*)(gbase) + (size_t)_i * qstep + (voff)[0]), (PG8_LAS unsigned*)(lds + (bufoff) + ldsw + _i * 8192), 16, 0, 0); } while (0)
; #define PG8_LDA(dst, b, h) do { _Pragma("unroll") for (int m = 0; m < 4; ++m) _Pragma("unroll") for (int k = 0; k < 2; ++k) dst[m][k] = *(const PG8_LAS bf16x8*)(lds + PG8_SA(b, h) + aoff + m * 2048 + k * 1024); } while (0)
; #define PG8_LDB(dst, b, h) do { _Pragma("unroll") for (int n = 0; n < 2; ++n) _Pragma("unroll") for (int k = 0; k < 2; ++k) dst[n][k] = *(const PG8_LAS bf16x8*)(lds + PG8_SB(b, h) + boff + n * 2048 + k * 1024); } while (0)
; #define PG8_MMA(ai, bj, At, Bt) do { __builtin_amdgcn_s_setprio(1); _Pragma("unroll") for (int m = 0; m < 4; ++m) _Pragma("unroll") for (int n = 0; n < 2; ++n) _Pragma("unroll") for (int k = 0; k < 2; ++k) \
;         acc[ai][bj][m][n] = __builtin_amdgcn_mfma_f32_16x16x32_bf16(Bt[n][k], At[m][k], acc[ai][bj][m][n], 0, 0, 0); __builtin_amdgcn_s_setprio(0); } while (0)
; #define PG8_WAIT_V89() do { if constexpr (SLIVER) PG8_WAIT_V(9); else PG8_WAIT_V(8); } while (0)
; #define PG8_STAGE_S(b, gbase) do { if constexpr (SLIVER) __builtin_amdgcn_global_load_lds((const unsigned*)((const char*)(gbase) + voffS), (PG8_LAS unsigned*)(lds + STAGE_BYTES + (b) * 2048 + wid * 256), 4, 0, 0); } while (0)
; #define PG8_WAIT_L(n) asm volatile("s_waitcnt lgkmcnt(" #n ")" ::: "memory")
; #define PG8_BAR __builtin_amdgcn_s_barrier()
; #define PG8_SCHED __builtin_amdgcn_sched_barrier(0)
; template <class Epi, class Sched, bool ALIGN_EPI = false, bool SP2 = false, bool SLIVER = false>
; __device__ __forceinline__ void gemm_phase(PG8_LAS unsigned char* lds, const Gemm g, const Sched& S, const Epi& E) {
;     ...
;             PG8_WAIT_V89(); PG8_WAIT_L(0); PG8_BAR; PG8_MMA(1, 0, At, B0); PG8_MMA(1, 1, At, B1); PG8_MMA_S(); PG8_BAR; PG8_SCHED;
;             PG8_LDB(B0, 1, 0); PG8_LDB(B1, 1, 1); PG8_SCHED; PG8_LDA(At, 1, 0); PG8_STAGE(PG8_SA(0, 1), a2 + hstep, voffA); PG8_STAGE_S(0, s2);
;             PG8_WAIT_V89(); PG8_WAIT_L(0); PG8_BAR; PG8_MMA(0, 0, At, B0); PG8_MMA(0, 1, At, B1); PG8_BAR; PG8_SCHED;
.LBB0_938:
	s_barrier
	s_setprio 0
	s_add_u32 s12, s54, s62
	s_addc_u32 s13, s55, s63
	s_add_u32 s68, s12, 0x100
	s_addc_u32 s69, s13, 0
	s_and_b64 s[12:13], s[80:81], exec
	s_cselect_b32 s13, s19, s69
	s_cselect_b32 s12, s18, s68
	s_add_i32 s68, 0, 0x18000
	v_add_u32_e32 v2, s68, v212
	s_add_i32 s69, 0, 0x1c000
	ds_read_b128 v[146:149], v2
	ds_read_b128 v[150:153], v2 offset:1024
	ds_read_b128 v[154:157], v2 offset:2048
	ds_read_b128 v[158:161], v2 offset:3072
	v_add_u32_e32 v2, s69, v212
	ds_read_b128 v[166:169], v2
	ds_read_b128 v[170:173], v2 offset:1024
	ds_read_b128 v[174:177], v2 offset:2048
	ds_read_b128 v[162:165], v2 offset:3072
	s_mov_b32 m0, s49
	v_lshl_add_u64 v[208:209], v[210:211], 0, s[46:47]
	ds_read_b128 v[2:5], v215 offset:32768
	ds_read_b128 v[6:9], v215 offset:33792
	ds_read_b128 v[180:183], v215 offset:34816
	ds_read_b128 v[184:187], v215 offset:35840
	ds_read_b128 v[216:219], v215 offset:36864
	ds_read_b128 v[220:223], v215 offset:37888
	ds_read_b128 v[224:227], v215 offset:38912
	ds_read_b128 v[228:231], v215 offset:39936
	global_load_lds_dwordx4 v[208:209], off
	v_lshl_add_u64 v[208:209], v[210:211], 0, s[6:7]
	s_mov_b32 m0, s88
	s_nop 0
	global_load_lds_dwordx4 v[208:209], off
	v_lshl_add_u64 v[208:209], s[12:13], 0, v[192:193]
	s_mov_b32 m0, s89
	s_nop 0
	global_load_lds_dword v[208:209], off
	s_waitcnt vmcnt(9)
	s_waitcnt lgkmcnt(0)
	s_setprio 1
	s_barrier
	v_mfma_f32_16x16x32_bf16 v[134:137], v[146:149], v[2:5], v[134:137]
	v_mfma_f32_16x16x32_bf16 v[134:137], v[150:153], v[6:9], v[134:137]
	v_mfma_f32_16x16x32_bf16 v[130:133], v[158:161], v[6:9], v[130:133]
	v_mfma_f32_16x16x32_bf16 v[130:133], v[154:157], v[2:5], v[130:133]
	v_mfma_f32_16x16x32_bf16 v[122:125], v[154:157], v[180:183], v[122:125]
	v_mfma_f32_16x16x32_bf16 v[122:125], v[158:161], v[184:187], v[122:125]
	v_mfma_f32_16x16x32_bf16 v[126:129], v[150:153], v[184:187], v[126:129]
	v_mfma_f32_16x16x32_bf16 v[126:129], v[146:149], v[180:183], v[126:129]
	s_setprio 0
	s_setprio 1
	v_mfma_f32_16x16x32_bf16 v[114:117], v[146:149], v[216:219], v[114:117]
	v_mfma_f32_16x16x32_bf16 v[114:117], v[150:153], v[220:223], v[114:117]
	v_mfma_f32_16x16x32_bf16 v[106:109], v[158:161], v[220:223], v[106:109]
	v_mfma_f32_16x16x32_bf16 v[106:109], v[154:157], v[216:219], v[106:109]
	v_mfma_f32_16x16x32_bf16 v[90:93], v[154:157], v[224:227], v[90:93]
	v_mfma_f32_16x16x32_bf16 v[90:93], v[158:161], v[228:231], v[90:93]
	v_mfma_f32_16x16x32_bf16 v[98:101], v[150:153], v[228:231], v[98:101]
	v_mfma_f32_16x16x32_bf16 v[98:101], v[146:149], v[224:227], v[98:101]
	s_setprio 0
	s_setprio 1
	v_mfma_f32_16x16x32_bf16 v[118:121], v[166:169], v[2:5], v[118:121]
	v_mfma_f32_16x16x32_bf16 v[118:121], v[170:173], v[6:9], v[118:121]
	v_mfma_f32_16x16x32_bf16 v[2:5], v[174:177], v[2:5], v[110:113]
	v_mfma_f32_16x16x32_bf16 v[110:113], v[162:165], v[6:9], v[2:5]
	v_mfma_f32_16x16x32_bf16 v[2:5], v[166:169], v[180:183], v[102:105]
	v_mfma_f32_16x16x32_bf16 v[102:105], v[170:173], v[184:187], v[2:5]
	v_mfma_f32_16x16x32_bf16 v[2:5], v[174:177], v[180:183], v[94:97]
	v_mfma_f32_16x16x32_bf16 v[94:97], v[162:165], v[184:187], v[2:5]
	s_setprio 0
	s_setprio 1
	v_mfma_f32_16x16x32_bf16 v[2:5], v[166:169], v[216:219], v[86:89]
	v_mfma_f32_16x16x32_bf16 v[86:89], v[170:173], v[220:223], v[2:5]
	v_mfma_f32_16x16x32_bf16 v[2:5], v[174:177], v[216:219], v[82:85]
	v_mfma_f32_16x16x32_bf16 v[82:85], v[162:165], v[220:223], v[2:5]
	v_mfma_f32_16x16x32_bf16 v[2:5], v[166:169], v[224:227], v[78:81]
	v_mfma_f32_16x16x32_bf16 v[78:81], v[170:173], v[228:231], v[2:5]
	v_mfma_f32_16x16x32_bf16 v[2:5], v[174:177], v[224:227], v[74:77]
	v_mfma_f32_16x16x32_bf16 v[74:77], v[162:165], v[228:231], v[2:5]
	s_barrier
; #define PG8_SB(B) __builtin_amdgcn_rcpf(1.f + expneg(B))
; #define PG8_SB(B) __builtin_amdgcn_rcpf(1.f + expneg(B))
; #define PG8_STAGE(bufoff, gbase, voff) do { _Pragma("unroll") for (int _i = 0; _i < 2; ++_i) \
;         __builtin_amdgcn_global_load_lds((const unsigned*)((const char*)(gbase) + (size_t)_i * qstep + (voff)[0]), (PG8_LAS unsigned*)(lds + (bufoff) + ldsw + _i * 8192), 16, 0, 0); } while (0)
; #define PG8_LDA(dst, b, h) do { _Pragma("unroll") for (int m = 0; m < 4; ++m) _Pragma("unroll") for (int k = 0; k < 2; ++k) dst[m][k] = *(const PG8_LAS bf16x8*)(lds + PG8_SA(b, h) + aoff + m * 2048 + k * 1024); } while (0)
; #define PG8_MMA(ai, bj, At, Bt) do { __builtin_amdgcn_s_setprio(1); _Pragma("unroll") for (int m = 0; m < 4; ++m) _Pragma("unroll") for (int n = 0; n < 2; ++n) _Pragma("unroll") for (int k = 0; k < 2; ++k) \
;         acc[ai][bj][m][n] = __builtin_amdgcn_mfma_f32_16x16x32_bf16(Bt[n][k], At[m][k], acc[ai][bj][m][n], 0, 0, 0); __builtin_amdgcn_s_setprio(0); } while (0)
; #define PG8_WAIT_V89() do { if constexpr (SLIVER) PG8_WAIT_V(9); else PG8_WAIT_V(8); } while (0)
; #define PG8_LDS_S(b) do { if constexpr (SLIVER) { Sf[0] = *(const PG8_LAS bf16x8*)(lds + STAGE_BYTES + (b) * 2048 + soff0); Sf[1] = *(const PG8_LAS bf16x8*)(lds + STAGE_BYTES + (b) * 2048 + (soff0 ^ 64)); } } while (0)
; #define PG8_WAIT_L(n) asm volatile("s_waitcnt lgkmcnt(" #n ")" ::: "memory")
; #define PG8_BAR __builtin_amdgcn_s_barrier()
; #define PG8_SCHED __builtin_amdgcn_sched_barrier(0)
; template <class Epi, class Sched, bool ALIGN_EPI = false, bool SP2 = false, bool SLIVER = false>
; __device__ __forceinline__ void gemm_phase(PG8_LAS unsigned char* lds, const Gemm g, const Sched& S, const Epi& E) {
;     ...
;             PG8_LDA(At, 1, 1); PG8_LDS_S(1); PG8_STAGE(PG8_SB(1, 0), b3, voffB); PG8_STAGE(PG8_SB(1, 1), b3 + hstep, voffB); PG8_STAGE(PG8_SA(1, 0), a3, voffA);
;             PG8_WAIT_V89(); PG8_WAIT_L(0); PG8_BAR; PG8_MMA(1, 0, At, B0); PG8_MMA(1, 1, At, B1); PG8_MMA_S(); PG8_BAR; PG8_SCHED;
	s_setprio 0
	s_add_i32 s12, 0, 0x20800
	v_add_u32_e32 v178, s12, v213
	v_add_u32_e32 v184, s12, v214
	s_add_i32 s12, s68, s92
	v_lshl_add_u64 v[208:209], v[202:203], 0, s[26:27]
	s_mov_b32 m0, s12
	ds_read_b128 v[2:5], v215 offset:49152
	ds_read_b128 v[6:9], v215 offset:50176
	ds_read_b128 v[216:219], v215 offset:51200
	ds_read_b128 v[220:223], v215 offset:52224
	ds_read_b128 v[224:227], v215 offset:53248
	ds_read_b128 v[228:231], v215 offset:54272
	ds_read_b128 v[232:235], v215 offset:55296
	ds_read_b128 v[240:243], v215 offset:56320
	ds_read_b128 v[180:183], v178
	ds_read_b128 v[184:187], v184
	global_load_lds_dwordx4 v[208:209], off
	v_lshl_add_u64 v[208:209], v[202:203], 0, s[58:59]
	s_add_i32 m0, s12, 0x2000
	s_mov_b64 s[12:13], 0x90080
	global_load_lds_dwordx4 v[208:209], off
	v_lshl_add_u64 v[208:209], v[202:203], 0, s[12:13]
	s_add_i32 s12, s69, s92
	s_mov_b32 m0, s12
	s_mov_b64 s[68:69], 0xd8080
	global_load_lds_dwordx4 v[208:209], off
	v_lshl_add_u64 v[202:203], v[202:203], 0, s[68:69]
	s_add_i32 m0, s12, 0x2000
	s_nop 0
	global_load_lds_dwordx4 v[202:203], off
	v_lshl_add_u64 v[202:203], v[210:211], 0, s[26:27]
	s_mov_b32 m0, s51
	s_nop 0
	global_load_lds_dwordx4 v[202:203], off
	v_lshl_add_u64 v[202:203], v[210:211], 0, s[58:59]
	s_mov_b32 m0, s53
	s_nop 0
	global_load_lds_dwordx4 v[202:203], off
	s_waitcnt vmcnt(9)
	s_waitcnt lgkmcnt(0)
	s_setprio 1
	s_barrier
	v_mfma_f32_16x16x32_bf16 v[70:73], v[146:149], v[2:5], v[70:73]
	v_mfma_f32_16x16x32_bf16 v[70:73], v[150:153], v[6:9], v[70:73]
	v_mfma_f32_16x16x32_bf16 v[66:69], v[158:161], v[6:9], v[66:69]
	v_mfma_f32_16x16x32_bf16 v[66:69], v[154:157], v[2:5], v[66:69]
	v_mfma_f32_16x16x32_bf16 v[58:61], v[154:157], v[216:219], v[58:61]
	v_mfma_f32_16x16x32_bf16 v[58:61], v[158:161], v[220:223], v[58:61]
	v_mfma_f32_16x16x32_bf16 v[62:65], v[150:153], v[220:223], v[62:65]
	v_mfma_f32_16x16x32_bf16 v[62:65], v[146:149], v[216:219], v[62:65]
	s_setprio 0
	s_setprio 1
	v_mfma_f32_16x16x32_bf16 v[50:53], v[146:149], v[224:227], v[50:53]
	v_mfma_f32_16x16x32_bf16 v[50:53], v[150:153], v[228:231], v[50:53]
	v_mfma_f32_16x16x32_bf16 v[42:45], v[158:161], v[228:231], v[42:45]
	v_mfma_f32_16x16x32_bf16 v[42:45], v[154:157], v[224:227], v[42:45]
	v_mfma_f32_16x16x32_bf16 v[26:29], v[154:157], v[232:235], v[26:29]
	v_mfma_f32_16x16x32_bf16 v[26:29], v[158:161], v[240:243], v[26:29]
	v_mfma_f32_16x16x32_bf16 v[34:37], v[150:153], v[240:243], v[34:37]
	v_mfma_f32_16x16x32_bf16 v[34:37], v[146:149], v[232:235], v[34:37]
	s_setprio 0
	s_setprio 1
	v_mfma_f32_16x16x32_bf16 v[54:57], v[166:169], v[2:5], v[54:57]
	v_mfma_f32_16x16x32_bf16 v[54:57], v[170:173], v[6:9], v[54:57]
	v_mfma_f32_16x16x32_bf16 v[2:5], v[174:177], v[2:5], v[46:49]
	v_mfma_f32_16x16x32_bf16 v[46:49], v[162:165], v[6:9], v[2:5]
	v_mfma_f32_16x16x32_bf16 v[2:5], v[166:169], v[216:219], v[38:41]
	v_mfma_f32_16x16x32_bf16 v[38:41], v[170:173], v[220:223], v[2:5]
	v_mfma_f32_16x16x32_bf16 v[2:5], v[174:177], v[216:219], v[30:33]
	v_mfma_f32_16x16x32_bf16 v[30:33], v[162:165], v[220:223], v[2:5]
	s_setprio 0
	s_setprio 1
	v_mfma_f32_16x16x32_bf16 v[2:5], v[166:169], v[224:227], v[22:25]
	v_mfma_f32_16x16x32_bf16 v[22:25], v[170:173], v[228:231], v[2:5]
	v_mfma_f32_16x16x32_bf16 v[2:5], v[174:177], v[224:227], v[18:21]
	v_mfma_f32_16x16x32_bf16 v[18:21], v[162:165], v[228:231], v[2:5]
	v_mfma_f32_16x16x32_bf16 v[2:5], v[166:169], v[232:235], v[14:17]
	v_mfma_f32_16x16x32_bf16 v[14:17], v[170:173], v[240:243], v[2:5]
	v_mfma_f32_16x16x32_bf16 v[2:5], v[174:177], v[232:235], v[10:13]
	v_mfma_f32_16x16x32_bf16 v[10:13], v[162:165], v[240:243], v[2:5]
	s_setprio 0
	s_setprio 1
	s_and_b64 vcc, exec, s[90:91]
	s_cbranch_vccz .Lslv_c3
	v_mfma_f32_16x16x32_bf16 v[2:5], v[166:169], v[180:183], v[138:141]
	v_mfma_f32_16x16x32_bf16 v[6:9], v[170:173], v[184:187], v[2:5]
	v_mfma_f32_16x16x32_bf16 v[2:5], v[174:177], v[180:183], v[142:145]
	v_mfma_f32_16x16x32_bf16 v[2:5], v[162:165], v[184:187], v[2:5]
	s_branch .LBB0_933
